# all 7 GEMM K-loops: first iteration peeled with SrcC=0 on the first MFMA of each accumulator, the 128 accumulator-zeroing v_mov per tile removed
# speedup vs baseline: 1.0026x; 1.0026x over previous
; #define PG8_STAGE(bufoff, gbase, voff) do { _Pragma("unroll") for (int _i = 0; _i < 2; ++_i) \
;         __builtin_amdgcn_global_load_lds((const unsigned*)((const char*)(gbase) + (voff)[_i]), (PG8_LAS unsigned*)(lds + (bufoff) + ldsw + _i * 8192), 16, 0, 0); } while (0)
; #define PG8_LDA(dst, b, h) do { _Pragma("unroll") for (int m = 0; m < 4; ++m) _Pragma("unroll") for (int k = 0; k < 2; ++k) dst[m][k] = *(const PG8_LAS bf16x8*)(lds + PG8_SA(b, h) + aoff + m * 2048 + k * 1024); } while (0)
; #define PG8_LDB(dst, b, h) do { _Pragma("unroll") for (int n = 0; n < 2; ++n) _Pragma("unroll") for (int k = 0; k < 2; ++k) dst[n][k] = *(const PG8_LAS bf16x8*)(lds + PG8_SB(b, h) + boff + n * 2048 + k * 1024); } while (0)
; #define PG8_WAIT_V(n) asm volatile("s_waitcnt vmcnt(" #n ")" ::: "memory")
; #define PG8_WAIT_L(n) asm volatile("s_waitcnt lgkmcnt(" #n ")" ::: "memory")
; #define PG8_BAR __builtin_amdgcn_s_barrier()
; #define PG8_SCHED __builtin_amdgcn_sched_barrier(0)
; template <class Epi, class Sched, bool ALIGN_EPI = false, bool SP2 = false>
; __device__ __forceinline__ void gemm_phase(PG8_LAS unsigned char* lds, const Gemm g, const Sched& S, const Epi& E) {
;     ...
;         const bool has_next = S.next(ui + 1, nxt);
;         const char* nA = has_next ? (const char*)g.A + (size_t)nxt.pm * tstep : cA; const char* nB = has_next ? (const char*)g.Bt + (size_t)nxt.pn * tstep : cB;
;         for (int t = 0; t < nt; t += 2) {
;             const bool last = (t == nt - 2);
;             const char* a1 = cA + (size_t)(t + 1) * kstep;
;             const char* a2 = last ? nA : cA + (size_t)(t + 2) * kstep; const char* b2 = last ? nB : cB + (size_t)(t + 2) * kstep;
;             const char* a3 = a2 + kstep; const char* b3 = b2 + kstep;
;             if (last && has_next) S.a_ready(nxt);
;             if constexpr (SP2) {
;             PG8_LDB(B0, 0, 0); PG8_LDB(B1, 0, 1); PG8_SCHED; PG8_LDA(At, 0, 0); PG8_STAGE(PG8_SA(1, 1), a1 + hstep, voffA);
;             PG8_WAIT_V(8); PG8_WAIT_L(0); PG8_BAR; PG8_MMA(0, 0, At, B0); PG8_MMA(0, 1, At, B1); PG8_BAR; PG8_SCHED;
;             PG8_LDA(At, 0, 1); PG8_STAGE(PG8_SB(0, 0), b2, voffB); PG8_STAGE(PG8_SB(0, 1), b2 + hstep, voffB); PG8_STAGE(PG8_SA(0, 0), a2, voffA);
;             PG8_WAIT_V(8); PG8_WAIT_L(0); PG8_BAR; PG8_MMA(1, 0, At, B0); PG8_MMA(1, 1, At, B1); PG8_BAR; PG8_SCHED;
.LBB0_300:
	s_ashr_i32 s13, s12, 31
	s_lshl_b64 s[16:17], s[12:13], 19
	s_add_u32 s16, s0, s16
	s_addc_u32 s17, s1, s17
	s_and_b64 s[18:19], s[4:5], exec
	s_cselect_b32 s13, s17, s25
	s_cselect_b32 s21, s16, s24
	s_ashr_i32 s11, s10, 31
	s_lshl_b64 s[18:19], s[10:11], 19
	s_add_u32 s18, s33, s18
	s_addc_u32 s19, s34, s19
	s_and_b64 s[28:29], s[4:5], exec
	s_cselect_b32 s11, s19, s27
	s_cselect_b32 s44, s18, s26
	s_add_u32 s24, s24, 0x40080
	s_addc_u32 s25, s25, 0
	s_add_u32 s45, s26, 0x100
	s_addc_u32 s46, s27, 0
	s_mov_b32 s47, -2
	s_add_u32 s26, s24, 0xfffc0080
	s_addc_u32 s27, s25, -1
	s_add_i32 s48, 0, 0x10000
	s_cmp_eq_u32 s47, 12
	s_cselect_b32 s29, s13, s27
	s_cselect_b32 s28, s21, s26
	v_add_u32_e32 v154, s48, v156
	s_cselect_b32 s27, s11, s46
	s_cselect_b32 s26, s44, s45
	s_add_i32 s50, 0, 0x14000
	ds_read_b128 v[94:97], v154
	ds_read_b128 v[134:137], v154 offset:1024
	ds_read_b128 v[158:161], v154 offset:2048
	ds_read_b128 v[162:165], v154 offset:3072
	v_add_u32_e32 v154, s50, v156
	ds_read_b128 v[166:169], v154
	ds_read_b128 v[170:173], v154 offset:1024
	ds_read_b128 v[174:177], v154 offset:2048
	ds_read_b128 v[186:189], v154 offset:3072
	v_lshl_add_u64 v[154:155], s[24:25], 0, v[150:151]
	s_add_i32 m0, s23, 0xc000
	ds_read_b128 v[190:193], v157
	ds_read_b128 v[194:197], v157 offset:1024
	ds_read_b128 v[198:201], v157 offset:2048
	ds_read_b128 v[202:205], v157 offset:3072
	ds_read_b128 v[206:209], v157 offset:4096
	ds_read_b128 v[210:213], v157 offset:5120
	ds_read_b128 v[214:217], v157 offset:6144
	ds_read_b128 v[218:221], v157 offset:7168
	global_load_lds_dwordx4 v[154:155], off
	v_lshl_add_u64 v[154:155], s[24:25], 0, v[152:153]
	s_add_i32 m0, s23, 0xe000
	s_nop 0
	global_load_lds_dwordx4 v[154:155], off
	s_waitcnt vmcnt(8)
	s_waitcnt lgkmcnt(0)
	s_barrier
	s_setprio 1
	v_mfma_f32_16x16x32_bf16 v[130:133], v[94:97], v[190:193], 0
	v_mfma_f32_16x16x32_bf16 v[126:129], v[158:161], v[190:193], 0
	v_mfma_f32_16x16x32_bf16 v[114:117], v[94:97], v[198:201], 0
	v_mfma_f32_16x16x32_bf16 v[110:113], v[158:161], v[198:201], 0
	v_mfma_f32_16x16x32_bf16 v[98:101], v[94:97], v[206:209], 0
	v_mfma_f32_16x16x32_bf16 v[90:93], v[158:161], v[206:209], 0
	v_mfma_f32_16x16x32_bf16 v[78:81], v[94:97], v[214:217], 0
	v_mfma_f32_16x16x32_bf16 v[74:77], v[158:161], v[214:217], 0
	v_mfma_f32_16x16x32_bf16 v[130:133], v[134:137], v[194:197], v[130:133]
	v_mfma_f32_16x16x32_bf16 v[126:129], v[162:165], v[194:197], v[126:129]
	v_mfma_f32_16x16x32_bf16 v[114:117], v[134:137], v[202:205], v[114:117]
	v_mfma_f32_16x16x32_bf16 v[110:113], v[162:165], v[202:205], v[110:113]
	v_mfma_f32_16x16x32_bf16 v[98:101], v[134:137], v[210:213], v[98:101]
	v_mfma_f32_16x16x32_bf16 v[90:93], v[162:165], v[210:213], v[90:93]
	v_mfma_f32_16x16x32_bf16 v[78:81], v[134:137], v[218:221], v[78:81]
	v_mfma_f32_16x16x32_bf16 v[74:77], v[162:165], v[218:221], v[74:77]
	s_setprio 0
	s_setprio 1
	v_mfma_f32_16x16x32_bf16 v[122:125], v[166:169], v[190:193], 0
	v_mfma_f32_16x16x32_bf16 v[118:121], v[174:177], v[190:193], 0
	v_mfma_f32_16x16x32_bf16 v[106:109], v[166:169], v[198:201], 0
	v_mfma_f32_16x16x32_bf16 v[102:105], v[174:177], v[198:201], 0
	v_mfma_f32_16x16x32_bf16 v[86:89], v[166:169], v[206:209], 0
	v_mfma_f32_16x16x32_bf16 v[82:85], v[174:177], v[206:209], 0
	v_mfma_f32_16x16x32_bf16 v[70:73], v[166:169], v[214:217], 0
	v_mfma_f32_16x16x32_bf16 v[66:69], v[174:177], v[214:217], 0
	v_mfma_f32_16x16x32_bf16 v[122:125], v[170:173], v[194:197], v[122:125]
	v_mfma_f32_16x16x32_bf16 v[118:121], v[186:189], v[194:197], v[118:121]
	v_mfma_f32_16x16x32_bf16 v[106:109], v[170:173], v[202:205], v[106:109]
	v_mfma_f32_16x16x32_bf16 v[102:105], v[186:189], v[202:205], v[102:105]
	v_mfma_f32_16x16x32_bf16 v[86:89], v[170:173], v[210:213], v[86:89]
	v_mfma_f32_16x16x32_bf16 v[82:85], v[186:189], v[210:213], v[82:85]
	v_mfma_f32_16x16x32_bf16 v[70:73], v[170:173], v[218:221], v[70:73]
	v_mfma_f32_16x16x32_bf16 v[66:69], v[186:189], v[218:221], v[66:69]
	s_setprio 0
	s_barrier
	s_add_i32 s48, s48, s35
	v_lshl_add_u64 v[154:155], s[26:27], 0, v[142:143]
	s_mov_b32 m0, s48
	ds_read_b128 v[190:193], v157 offset:16384
	ds_read_b128 v[194:197], v157 offset:17408
	ds_read_b128 v[198:201], v157 offset:18432
	ds_read_b128 v[202:205], v157 offset:19456
	ds_read_b128 v[206:209], v157 offset:20480
	ds_read_b128 v[210:213], v157 offset:21504
	ds_read_b128 v[214:217], v157 offset:22528
	ds_read_b128 v[218:221], v157 offset:23552
	global_load_lds_dwordx4 v[154:155], off
	s_add_i32 m0, s48, 0x2000
	s_add_u32 s48, s26, 0x40000
	v_lshl_add_u64 v[180:181], s[26:27], 0, v[138:139]
	s_addc_u32 s49, s27, 0
	s_add_i32 s50, s50, s35
	global_load_lds_dwordx4 v[180:181], off
	v_lshl_add_u64 v[182:183], s[48:49], 0, v[142:143]
	s_mov_b32 m0, s50
	v_lshl_add_u64 v[222:223], s[28:29], 0, v[140:141]
	global_load_lds_dwordx4 v[182:183], off
	v_lshl_add_u64 v[182:183], s[48:49], 0, v[138:139]
	s_add_i32 m0, s50, 0x2000
	s_nop 0
	global_load_lds_dwordx4 v[182:183], off
	v_lshl_add_u64 v[182:183], s[28:29], 0, v[144:145]
	s_mov_b32 m0, s23
	s_nop 0
	global_load_lds_dwordx4 v[182:183], off
	s_mov_b32 m0, s37
	s_nop 0
	global_load_lds_dwordx4 v[222:223], off
	s_waitcnt vmcnt(8)
	s_waitcnt lgkmcnt(0)
	s_barrier
; #define PG8_STAGE(bufoff, gbase, voff) do { _Pragma("unroll") for (int _i = 0; _i < 2; ++_i) \
;         __builtin_amdgcn_global_load_lds((const unsigned*)((const char*)(gbase) + (voff)[_i]), (PG8_LAS unsigned*)(lds + (bufoff) + ldsw + _i * 8192), 16, 0, 0); } while (0)
; #define PG8_LDA(dst, b, h) do { _Pragma("unroll") for (int m = 0; m < 4; ++m) _Pragma("unroll") for (int k = 0; k < 2; ++k) dst[m][k] = *(const PG8_LAS bf16x8*)(lds + PG8_SA(b, h) + aoff + m * 2048 + k * 1024); } while (0)
; #define PG8_LDB(dst, b, h) do { _Pragma("unroll") for (int n = 0; n < 2; ++n) _Pragma("unroll") for (int k = 0; k < 2; ++k) dst[n][k] = *(const PG8_LAS bf16x8*)(lds + PG8_SB(b, h) + boff + n * 2048 + k * 1024); } while (0)
; #define PG8_MMA(ai, bj, At, Bt) do { __builtin_amdgcn_s_setprio(1); _Pragma("unroll") for (int m = 0; m < 4; ++m) _Pragma("unroll") for (int n = 0; n < 2; ++n) _Pragma("unroll") for (int k = 0; k < 2; ++k) \
;         acc[ai][bj][m][n] = __builtin_amdgcn_mfma_f32_16x16x32_bf16(Bt[n][k], At[m][k], acc[ai][bj][m][n], 0, 0, 0); __builtin_amdgcn_s_setprio(0); } while (0)
; #define PG8_WAIT_V(n) asm volatile("s_waitcnt vmcnt(" #n ")" ::: "memory")
; #define PG8_WAIT_L(n) asm volatile("s_waitcnt lgkmcnt(" #n ")" ::: "memory")
; #define PG8_BAR __builtin_amdgcn_s_barrier()
; #define PG8_SCHED __builtin_amdgcn_sched_barrier(0)
; template <class Epi, class Sched, bool ALIGN_EPI = false, bool SP2 = false>
; __device__ __forceinline__ void gemm_phase(PG8_LAS unsigned char* lds, const Gemm g, const Sched& S, const Epi& E) {
;     ...
;             PG8_WAIT_V(8); PG8_WAIT_L(0); PG8_BAR; PG8_MMA(1, 0, At, B0); PG8_MMA(1, 1, At, B1); PG8_BAR; PG8_SCHED;
;             PG8_LDB(B0, 1, 0); PG8_LDB(B1, 1, 1); PG8_SCHED; PG8_LDA(At, 1, 0); PG8_STAGE(PG8_SA(0, 1), a2 + hstep, voffA);
;             PG8_WAIT_V(8); PG8_WAIT_L(0); PG8_BAR; PG8_MMA(0, 0, At, B0); PG8_MMA(0, 1, At, B1); PG8_BAR; PG8_SCHED;
;             PG8_LDA(At, 1, 1); PG8_STAGE(PG8_SB(1, 0), b3, voffB); PG8_STAGE(PG8_SB(1, 1), b3 + hstep, voffB); PG8_STAGE(PG8_SA(1, 0), a3, voffA);
;             PG8_WAIT_V(8); PG8_WAIT_L(0); PG8_BAR; PG8_MMA(1, 0, At, B0); PG8_MMA(1, 1, At, B1); PG8_BAR; PG8_SCHED;
	s_setprio 1
	v_mfma_f32_16x16x32_bf16 v[62:65], v[94:97], v[190:193], 0
	v_mfma_f32_16x16x32_bf16 v[58:61], v[158:161], v[190:193], 0
	v_mfma_f32_16x16x32_bf16 v[50:53], v[94:97], v[198:201], 0
	v_mfma_f32_16x16x32_bf16 v[42:45], v[158:161], v[198:201], 0
	v_mfma_f32_16x16x32_bf16 v[34:37], v[94:97], v[206:209], 0
	v_mfma_f32_16x16x32_bf16 v[26:29], v[158:161], v[206:209], 0
	v_mfma_f32_16x16x32_bf16 v[18:21], v[94:97], v[214:217], 0
	v_mfma_f32_16x16x32_bf16 v[10:13], v[158:161], v[214:217], 0
	v_mfma_f32_16x16x32_bf16 v[62:65], v[134:137], v[194:197], v[62:65]
	v_mfma_f32_16x16x32_bf16 v[58:61], v[162:165], v[194:197], v[58:61]
	v_mfma_f32_16x16x32_bf16 v[50:53], v[134:137], v[202:205], v[50:53]
	v_mfma_f32_16x16x32_bf16 v[42:45], v[162:165], v[202:205], v[42:45]
	v_mfma_f32_16x16x32_bf16 v[34:37], v[134:137], v[210:213], v[34:37]
	v_mfma_f32_16x16x32_bf16 v[26:29], v[162:165], v[210:213], v[26:29]
	v_mfma_f32_16x16x32_bf16 v[18:21], v[134:137], v[218:221], v[18:21]
	v_mfma_f32_16x16x32_bf16 v[10:13], v[162:165], v[218:221], v[10:13]
	s_setprio 0
	s_setprio 1
	v_mfma_f32_16x16x32_bf16 v[54:57], v[166:169], v[190:193], 0
	v_mfma_f32_16x16x32_bf16 v[46:49], v[174:177], v[190:193], 0
	v_mfma_f32_16x16x32_bf16 v[38:41], v[166:169], v[198:201], 0
	v_mfma_f32_16x16x32_bf16 v[30:33], v[174:177], v[198:201], 0
	v_mfma_f32_16x16x32_bf16 v[22:25], v[166:169], v[206:209], 0
	v_mfma_f32_16x16x32_bf16 v[14:17], v[174:177], v[206:209], 0
	v_mfma_f32_16x16x32_bf16 v[6:9], v[166:169], v[214:217], 0
	v_mfma_f32_16x16x32_bf16 v[2:5], v[174:177], v[214:217], 0
	v_mfma_f32_16x16x32_bf16 v[54:57], v[170:173], v[194:197], v[54:57]
	v_mfma_f32_16x16x32_bf16 v[46:49], v[186:189], v[194:197], v[46:49]
	v_mfma_f32_16x16x32_bf16 v[38:41], v[170:173], v[202:205], v[38:41]
	v_mfma_f32_16x16x32_bf16 v[30:33], v[186:189], v[202:205], v[30:33]
	v_mfma_f32_16x16x32_bf16 v[22:25], v[170:173], v[210:213], v[22:25]
	v_mfma_f32_16x16x32_bf16 v[14:17], v[186:189], v[210:213], v[14:17]
	v_mfma_f32_16x16x32_bf16 v[6:9], v[170:173], v[218:221], v[6:9]
	v_mfma_f32_16x16x32_bf16 v[2:5], v[186:189], v[218:221], v[2:5]
	s_setprio 0
	s_barrier
	s_add_i32 s48, 0, 0x18000
	s_add_i32 s49, 0, 0x1c000
	v_add_u32_e32 v162, s48, v156
	v_add_u32_e32 v179, s49, v156
	ds_read_b128 v[94:97], v162
	ds_read_b128 v[134:137], v162 offset:1024
	ds_read_b128 v[158:161], v162 offset:2048
	ds_read_b128 v[162:165], v162 offset:3072
	ds_read_b128 v[166:169], v179
	ds_read_b128 v[170:173], v179 offset:1024
	ds_read_b128 v[174:177], v179 offset:2048
	ds_read_b128 v[186:189], v179 offset:3072
	s_add_u32 s28, s28, 0x40000
	s_addc_u32 s29, s29, 0
	s_mov_b32 m0, s38
	v_lshl_add_u64 v[240:241], s[28:29], 0, v[144:145]
	ds_read_b128 v[190:193], v157 offset:32768
	ds_read_b128 v[194:197], v157 offset:33792
	ds_read_b128 v[198:201], v157 offset:34816
	ds_read_b128 v[202:205], v157 offset:35840
	ds_read_b128 v[206:209], v157 offset:36864
	ds_read_b128 v[210:213], v157 offset:37888
	ds_read_b128 v[214:217], v157 offset:38912
	ds_read_b128 v[218:221], v157 offset:39936
	global_load_lds_dwordx4 v[240:241], off
	v_lshl_add_u64 v[240:241], s[28:29], 0, v[140:141]
	s_mov_b32 m0, s39
	s_nop 0
	global_load_lds_dwordx4 v[240:241], off
	s_waitcnt vmcnt(8)
	s_waitcnt lgkmcnt(0)
	s_barrier
	s_setprio 1
	v_mfma_f32_16x16x32_bf16 v[130:133], v[94:97], v[190:193], v[130:133]
	v_mfma_f32_16x16x32_bf16 v[126:129], v[158:161], v[190:193], v[126:129]
	v_mfma_f32_16x16x32_bf16 v[114:117], v[94:97], v[198:201], v[114:117]
	v_mfma_f32_16x16x32_bf16 v[110:113], v[158:161], v[198:201], v[110:113]
	v_mfma_f32_16x16x32_bf16 v[98:101], v[94:97], v[206:209], v[98:101]
	v_mfma_f32_16x16x32_bf16 v[90:93], v[158:161], v[206:209], v[90:93]
	v_mfma_f32_16x16x32_bf16 v[78:81], v[94:97], v[214:217], v[78:81]
	v_mfma_f32_16x16x32_bf16 v[74:77], v[158:161], v[214:217], v[74:77]
	v_mfma_f32_16x16x32_bf16 v[130:133], v[134:137], v[194:197], v[130:133]
	v_mfma_f32_16x16x32_bf16 v[126:129], v[162:165], v[194:197], v[126:129]
	v_mfma_f32_16x16x32_bf16 v[114:117], v[134:137], v[202:205], v[114:117]
	v_mfma_f32_16x16x32_bf16 v[110:113], v[162:165], v[202:205], v[110:113]
	v_mfma_f32_16x16x32_bf16 v[98:101], v[134:137], v[210:213], v[98:101]
	v_mfma_f32_16x16x32_bf16 v[90:93], v[162:165], v[210:213], v[90:93]
	v_mfma_f32_16x16x32_bf16 v[78:81], v[134:137], v[218:221], v[78:81]
	v_mfma_f32_16x16x32_bf16 v[74:77], v[162:165], v[218:221], v[74:77]
	s_setprio 0
	s_setprio 1
	v_mfma_f32_16x16x32_bf16 v[122:125], v[166:169], v[190:193], v[122:125]
	v_mfma_f32_16x16x32_bf16 v[118:121], v[174:177], v[190:193], v[118:121]
	v_mfma_f32_16x16x32_bf16 v[106:109], v[166:169], v[198:201], v[106:109]
	v_mfma_f32_16x16x32_bf16 v[102:105], v[174:177], v[198:201], v[102:105]
	v_mfma_f32_16x16x32_bf16 v[86:89], v[166:169], v[206:209], v[86:89]
	v_mfma_f32_16x16x32_bf16 v[82:85], v[174:177], v[206:209], v[82:85]
	v_mfma_f32_16x16x32_bf16 v[70:73], v[166:169], v[214:217], v[70:73]
	v_mfma_f32_16x16x32_bf16 v[66:69], v[174:177], v[214:217], v[66:69]
	v_mfma_f32_16x16x32_bf16 v[122:125], v[170:173], v[194:197], v[122:125]
	v_mfma_f32_16x16x32_bf16 v[118:121], v[186:189], v[194:197], v[118:121]
	v_mfma_f32_16x16x32_bf16 v[106:109], v[170:173], v[202:205], v[106:109]
	v_mfma_f32_16x16x32_bf16 v[102:105], v[186:189], v[202:205], v[102:105]
	v_mfma_f32_16x16x32_bf16 v[86:89], v[170:173], v[210:213], v[86:89]
	v_mfma_f32_16x16x32_bf16 v[82:85], v[186:189], v[210:213], v[82:85]
	v_mfma_f32_16x16x32_bf16 v[70:73], v[170:173], v[218:221], v[70:73]
	v_mfma_f32_16x16x32_bf16 v[66:69], v[186:189], v[218:221], v[66:69]
	s_setprio 0
	s_barrier
; #define PG8_STAGE(bufoff, gbase, voff) do { _Pragma("unroll") for (int _i = 0; _i < 2; ++_i) \
;         __builtin_amdgcn_global_load_lds((const unsigned*)((const char*)(gbase) + (voff)[_i]), (PG8_LAS unsigned*)(lds + (bufoff) + ldsw + _i * 8192), 16, 0, 0); } while (0)
; #define PG8_LDA(dst, b, h) do { _Pragma("unroll") for (int m = 0; m < 4; ++m) _Pragma("unroll") for (int k = 0; k < 2; ++k) dst[m][k] = *(const PG8_LAS bf16x8*)(lds + PG8_SA(b, h) + aoff + m * 2048 + k * 1024); } while (0)
; #define PG8_MMA(ai, bj, At, Bt) do { __builtin_amdgcn_s_setprio(1); _Pragma("unroll") for (int m = 0; m < 4; ++m) _Pragma("unroll") for (int n = 0; n < 2; ++n) _Pragma("unroll") for (int k = 0; k < 2; ++k) \
;         acc[ai][bj][m][n] = __builtin_amdgcn_mfma_f32_16x16x32_bf16(Bt[n][k], At[m][k], acc[ai][bj][m][n], 0, 0, 0); __builtin_amdgcn_s_setprio(0); } while (0)
; #define PG8_WAIT_V(n) asm volatile("s_waitcnt vmcnt(" #n ")" ::: "memory")
; #define PG8_WAIT_L(n) asm volatile("s_waitcnt lgkmcnt(" #n ")" ::: "memory")
; #define PG8_BAR __builtin_amdgcn_s_barrier()
; #define PG8_SCHED __builtin_amdgcn_sched_barrier(0)
; template <class Epi, class Sched, bool ALIGN_EPI = false, bool SP2 = false>
; __device__ __forceinline__ void gemm_phase(PG8_LAS unsigned char* lds, const Gemm g, const Sched& S, const Epi& E) {
;     ...
;             PG8_WAIT_V(8); PG8_WAIT_L(0); PG8_BAR; PG8_MMA(0, 0, At, B0); PG8_MMA(0, 1, At, B1); PG8_BAR; PG8_SCHED;
;             PG8_LDA(At, 1, 1); PG8_STAGE(PG8_SB(1, 0), b3, voffB); PG8_STAGE(PG8_SB(1, 1), b3 + hstep, voffB); PG8_STAGE(PG8_SA(1, 0), a3, voffA);
;             PG8_WAIT_V(8); PG8_WAIT_L(0); PG8_BAR; PG8_MMA(1, 0, At, B0); PG8_MMA(1, 1, At, B1); PG8_BAR; PG8_SCHED;
	s_add_i32 s28, s48, s35
	v_lshl_add_u64 v[154:155], v[154:155], 0, s[80:81]
	s_mov_b32 m0, s28
	ds_read_b128 v[190:193], v157 offset:49152
	ds_read_b128 v[194:197], v157 offset:50176
	ds_read_b128 v[198:201], v157 offset:51200
	ds_read_b128 v[202:205], v157 offset:52224
	ds_read_b128 v[206:209], v157 offset:53248
	ds_read_b128 v[210:213], v157 offset:54272
	ds_read_b128 v[214:217], v157 offset:55296
	ds_read_b128 v[218:221], v157 offset:56320
	global_load_lds_dwordx4 v[154:155], off
	s_add_i32 m0, s28, 0x2000
	s_add_u32 s26, s26, 0x40080
	v_lshl_add_u64 v[154:155], v[180:181], 0, s[80:81]
	s_addc_u32 s27, s27, 0
	s_add_i32 s28, s49, s35
	global_load_lds_dwordx4 v[154:155], off
	v_lshl_add_u64 v[154:155], s[26:27], 0, v[142:143]
	s_mov_b32 m0, s28
	s_nop 0
	global_load_lds_dwordx4 v[154:155], off
	v_lshl_add_u64 v[154:155], s[26:27], 0, v[138:139]
	s_add_i32 m0, s28, 0x2000
	s_nop 0
	global_load_lds_dwordx4 v[154:155], off
	v_lshl_add_u64 v[154:155], v[182:183], 0, s[80:81]
	s_mov_b32 m0, s40
	s_nop 0
	global_load_lds_dwordx4 v[154:155], off
	v_lshl_add_u64 v[154:155], v[222:223], 0, s[80:81]
	s_mov_b32 m0, s41
	s_nop 0
	global_load_lds_dwordx4 v[154:155], off
	s_waitcnt vmcnt(8)
	s_waitcnt lgkmcnt(0)
	s_barrier
	s_setprio 1
	v_mfma_f32_16x16x32_bf16 v[62:65], v[94:97], v[190:193], v[62:65]
	v_mfma_f32_16x16x32_bf16 v[58:61], v[158:161], v[190:193], v[58:61]
	v_mfma_f32_16x16x32_bf16 v[50:53], v[94:97], v[198:201], v[50:53]
	v_mfma_f32_16x16x32_bf16 v[42:45], v[158:161], v[198:201], v[42:45]
	v_mfma_f32_16x16x32_bf16 v[34:37], v[94:97], v[206:209], v[34:37]
	v_mfma_f32_16x16x32_bf16 v[26:29], v[158:161], v[206:209], v[26:29]
	v_mfma_f32_16x16x32_bf16 v[18:21], v[94:97], v[214:217], v[18:21]
	v_mfma_f32_16x16x32_bf16 v[10:13], v[158:161], v[214:217], v[10:13]
	v_mfma_f32_16x16x32_bf16 v[62:65], v[134:137], v[194:197], v[62:65]
	v_mfma_f32_16x16x32_bf16 v[58:61], v[162:165], v[194:197], v[58:61]
	v_mfma_f32_16x16x32_bf16 v[50:53], v[134:137], v[202:205], v[50:53]
	v_mfma_f32_16x16x32_bf16 v[42:45], v[162:165], v[202:205], v[42:45]
	v_mfma_f32_16x16x32_bf16 v[34:37], v[134:137], v[210:213], v[34:37]
	v_mfma_f32_16x16x32_bf16 v[26:29], v[162:165], v[210:213], v[26:29]
	v_mfma_f32_16x16x32_bf16 v[18:21], v[134:137], v[218:221], v[18:21]
	v_mfma_f32_16x16x32_bf16 v[10:13], v[162:165], v[218:221], v[10:13]
	s_setprio 0
	s_setprio 1
	v_mfma_f32_16x16x32_bf16 v[54:57], v[166:169], v[190:193], v[54:57]
	v_mfma_f32_16x16x32_bf16 v[46:49], v[174:177], v[190:193], v[46:49]
	v_mfma_f32_16x16x32_bf16 v[38:41], v[166:169], v[198:201], v[38:41]
	v_mfma_f32_16x16x32_bf16 v[30:33], v[174:177], v[198:201], v[30:33]
	v_mfma_f32_16x16x32_bf16 v[22:25], v[166:169], v[206:209], v[22:25]
	v_mfma_f32_16x16x32_bf16 v[14:17], v[174:177], v[206:209], v[14:17]
	v_mfma_f32_16x16x32_bf16 v[6:9], v[166:169], v[214:217], v[6:9]
	v_mfma_f32_16x16x32_bf16 v[2:5], v[174:177], v[214:217], v[2:5]
	v_mfma_f32_16x16x32_bf16 v[54:57], v[170:173], v[194:197], v[54:57]
	v_mfma_f32_16x16x32_bf16 v[46:49], v[186:189], v[194:197], v[46:49]
	v_mfma_f32_16x16x32_bf16 v[38:41], v[170:173], v[202:205], v[38:41]
	v_mfma_f32_16x16x32_bf16 v[30:33], v[186:189], v[202:205], v[30:33]
	v_mfma_f32_16x16x32_bf16 v[22:25], v[170:173], v[210:213], v[22:25]
	v_mfma_f32_16x16x32_bf16 v[14:17], v[186:189], v[210:213], v[14:17]
	v_mfma_f32_16x16x32_bf16 v[6:9], v[170:173], v[218:221], v[6:9]
	v_mfma_f32_16x16x32_bf16 v[2:5], v[186:189], v[218:221], v[2:5]
	s_setprio 0
	s_barrier
	s_add_i32 s47, s47, 2
	s_add_u32 s24, s24, 0x100
	s_addc_u32 s25, s25, 0
	s_add_u32 s45, s45, 0x100
	s_addc_u32 s46, s46, 0
	s_cmp_gt_u32 s47, 13
	s_branch .LBB0_301

; #define PG8_STAGE(bufoff, gbase, voff) do { _Pragma("unroll") for (int _i = 0; _i < 2; ++_i) \
;         __builtin_amdgcn_global_load_lds((const unsigned*)((const char*)(gbase) + (voff)[_i]), (PG8_LAS unsigned*)(lds + (bufoff) + ldsw + _i * 8192), 16, 0, 0); } while (0)
; #define PG8_LDA(dst, b, h) do { _Pragma("unroll") for (int m = 0; m < 4; ++m) _Pragma("unroll") for (int k = 0; k < 2; ++k) dst[m][k] = *(const PG8_LAS bf16x8*)(lds + PG8_SA(b, h) + aoff + m * 2048 + k * 1024); } while (0)
; #define PG8_LDB(dst, b, h) do { _Pragma("unroll") for (int n = 0; n < 2; ++n) _Pragma("unroll") for (int k = 0; k < 2; ++k) dst[n][k] = *(const PG8_LAS bf16x8*)(lds + PG8_SB(b, h) + boff + n * 2048 + k * 1024); } while (0)
; #define PG8_WAIT_V(n) asm volatile("s_waitcnt vmcnt(" #n ")" ::: "memory")
; #define PG8_WAIT_L(n) asm volatile("s_waitcnt lgkmcnt(" #n ")" ::: "memory")
; #define PG8_BAR __builtin_amdgcn_s_barrier()
; #define PG8_SCHED __builtin_amdgcn_sched_barrier(0)
; template <class Epi, class Sched, bool ALIGN_EPI = false, bool SP2 = false>
; __device__ __forceinline__ void gemm_phase(PG8_LAS unsigned char* lds, const Gemm g, const Sched& S, const Epi& E) {
;     ...
;         const bool has_next = S.next(ui + 1, nxt);
;         const char* nA = has_next ? (const char*)g.A + (size_t)nxt.pm * tstep : cA; const char* nB = has_next ? (const char*)g.Bt + (size_t)nxt.pn * tstep : cB;
;         for (int t = 0; t < nt; t += 2) {
;             const bool last = (t == nt - 2);
;             const char* a1 = cA + (size_t)(t + 1) * kstep;
;             const char* a2 = last ? nA : cA + (size_t)(t + 2) * kstep; const char* b2 = last ? nB : cB + (size_t)(t + 2) * kstep;
;             const char* a3 = a2 + kstep; const char* b3 = b2 + kstep;
;             if (last && has_next) S.a_ready(nxt);
;             if constexpr (SP2) {
;             PG8_LDB(B0, 0, 0); PG8_LDB(B1, 0, 1); PG8_SCHED; PG8_LDA(At, 0, 0); PG8_STAGE(PG8_SA(1, 1), a1 + hstep, voffA);
;             PG8_WAIT_V(8); PG8_WAIT_L(0); PG8_BAR; PG8_MMA(0, 0, At, B0); PG8_MMA(0, 1, At, B1); PG8_BAR; PG8_SCHED;
;             PG8_LDA(At, 0, 1); PG8_STAGE(PG8_SB(0, 0), b2, voffB); PG8_STAGE(PG8_SB(0, 1), b2 + hstep, voffB); PG8_STAGE(PG8_SA(0, 0), a2, voffA);
;             PG8_WAIT_V(8); PG8_WAIT_L(0); PG8_BAR; PG8_MMA(1, 0, At, B0); PG8_MMA(1, 1, At, B1); PG8_BAR; PG8_SCHED;
.LBB0_317:
	s_ashr_i32 s13, s12, 31
	s_lshl_b64 s[16:17], s[12:13], 19
	s_add_u32 s16, s8, s16
	s_addc_u32 s17, s9, s17
	s_and_b64 s[18:19], s[4:5], exec
	s_cselect_b32 s13, s17, s25
	s_cselect_b32 s21, s16, s24
	s_ashr_i32 s11, s10, 31
	s_lshl_b64 s[18:19], s[10:11], 19
	s_add_u32 s18, s33, s18
	s_addc_u32 s19, s34, s19
	s_and_b64 s[28:29], s[4:5], exec
	s_cselect_b32 s11, s19, s27
	s_cselect_b32 s44, s18, s26
	s_add_u32 s24, s24, 0x40080
	s_addc_u32 s25, s25, 0
	s_add_u32 s45, s26, 0x100
	s_addc_u32 s46, s27, 0
	s_mov_b32 s47, -2
	s_add_u32 s26, s24, 0xfffc0080
	s_addc_u32 s27, s25, -1
	s_add_i32 s48, 0, 0x10000
	s_cmp_eq_u32 s47, 12
	s_cselect_b32 s29, s13, s27
	s_cselect_b32 s28, s21, s26
	v_add_u32_e32 v154, s48, v156
	s_cselect_b32 s27, s11, s46
	s_cselect_b32 s26, s44, s45
	s_add_i32 s50, 0, 0x14000
	ds_read_b128 v[94:97], v154
	ds_read_b128 v[134:137], v154 offset:1024
	ds_read_b128 v[158:161], v154 offset:2048
	ds_read_b128 v[162:165], v154 offset:3072
	v_add_u32_e32 v154, s50, v156
	ds_read_b128 v[166:169], v154
	ds_read_b128 v[170:173], v154 offset:1024
	ds_read_b128 v[174:177], v154 offset:2048
	ds_read_b128 v[186:189], v154 offset:3072
	v_lshl_add_u64 v[154:155], s[24:25], 0, v[150:151]
	s_add_i32 m0, s23, 0xc000
	ds_read_b128 v[190:193], v157
	ds_read_b128 v[194:197], v157 offset:1024
	ds_read_b128 v[198:201], v157 offset:2048
	ds_read_b128 v[202:205], v157 offset:3072
	ds_read_b128 v[206:209], v157 offset:4096
	ds_read_b128 v[210:213], v157 offset:5120
	ds_read_b128 v[214:217], v157 offset:6144
	ds_read_b128 v[218:221], v157 offset:7168
	global_load_lds_dwordx4 v[154:155], off
	v_lshl_add_u64 v[154:155], s[24:25], 0, v[152:153]
	s_add_i32 m0, s23, 0xe000
	s_nop 0
	global_load_lds_dwordx4 v[154:155], off
	s_waitcnt vmcnt(8)
	s_waitcnt lgkmcnt(0)
	s_barrier
	s_setprio 1
	v_mfma_f32_16x16x32_bf16 v[130:133], v[94:97], v[190:193], 0
	v_mfma_f32_16x16x32_bf16 v[126:129], v[158:161], v[190:193], 0
	v_mfma_f32_16x16x32_bf16 v[114:117], v[94:97], v[198:201], 0
	v_mfma_f32_16x16x32_bf16 v[110:113], v[158:161], v[198:201], 0
	v_mfma_f32_16x16x32_bf16 v[98:101], v[94:97], v[206:209], 0
	v_mfma_f32_16x16x32_bf16 v[90:93], v[158:161], v[206:209], 0
	v_mfma_f32_16x16x32_bf16 v[78:81], v[94:97], v[214:217], 0
	v_mfma_f32_16x16x32_bf16 v[74:77], v[158:161], v[214:217], 0
	v_mfma_f32_16x16x32_bf16 v[130:133], v[134:137], v[194:197], v[130:133]
	v_mfma_f32_16x16x32_bf16 v[126:129], v[162:165], v[194:197], v[126:129]
	v_mfma_f32_16x16x32_bf16 v[114:117], v[134:137], v[202:205], v[114:117]
	v_mfma_f32_16x16x32_bf16 v[110:113], v[162:165], v[202:205], v[110:113]
	v_mfma_f32_16x16x32_bf16 v[98:101], v[134:137], v[210:213], v[98:101]
	v_mfma_f32_16x16x32_bf16 v[90:93], v[162:165], v[210:213], v[90:93]
	v_mfma_f32_16x16x32_bf16 v[78:81], v[134:137], v[218:221], v[78:81]
	v_mfma_f32_16x16x32_bf16 v[74:77], v[162:165], v[218:221], v[74:77]
	s_setprio 0
	s_setprio 1
	v_mfma_f32_16x16x32_bf16 v[122:125], v[166:169], v[190:193], 0
	v_mfma_f32_16x16x32_bf16 v[118:121], v[174:177], v[190:193], 0
	v_mfma_f32_16x16x32_bf16 v[106:109], v[166:169], v[198:201], 0
	v_mfma_f32_16x16x32_bf16 v[102:105], v[174:177], v[198:201], 0
	v_mfma_f32_16x16x32_bf16 v[86:89], v[166:169], v[206:209], 0
	v_mfma_f32_16x16x32_bf16 v[82:85], v[174:177], v[206:209], 0
	v_mfma_f32_16x16x32_bf16 v[70:73], v[166:169], v[214:217], 0
	v_mfma_f32_16x16x32_bf16 v[66:69], v[174:177], v[214:217], 0
	v_mfma_f32_16x16x32_bf16 v[122:125], v[170:173], v[194:197], v[122:125]
	v_mfma_f32_16x16x32_bf16 v[118:121], v[186:189], v[194:197], v[118:121]
	v_mfma_f32_16x16x32_bf16 v[106:109], v[170:173], v[202:205], v[106:109]
	v_mfma_f32_16x16x32_bf16 v[102:105], v[186:189], v[202:205], v[102:105]
	v_mfma_f32_16x16x32_bf16 v[86:89], v[170:173], v[210:213], v[86:89]
	v_mfma_f32_16x16x32_bf16 v[82:85], v[186:189], v[210:213], v[82:85]
	v_mfma_f32_16x16x32_bf16 v[70:73], v[170:173], v[218:221], v[70:73]
	v_mfma_f32_16x16x32_bf16 v[66:69], v[186:189], v[218:221], v[66:69]
	s_setprio 0
	s_barrier
	s_add_i32 s48, s48, s35
	v_lshl_add_u64 v[154:155], s[26:27], 0, v[142:143]
	s_mov_b32 m0, s48
	ds_read_b128 v[190:193], v157 offset:16384
	ds_read_b128 v[194:197], v157 offset:17408
	ds_read_b128 v[198:201], v157 offset:18432
	ds_read_b128 v[202:205], v157 offset:19456
	ds_read_b128 v[206:209], v157 offset:20480
	ds_read_b128 v[210:213], v157 offset:21504
	ds_read_b128 v[214:217], v157 offset:22528
	ds_read_b128 v[218:221], v157 offset:23552
	global_load_lds_dwordx4 v[154:155], off
	s_add_i32 m0, s48, 0x2000
	s_add_u32 s48, s26, 0x40000
	v_lshl_add_u64 v[180:181], s[26:27], 0, v[138:139]
	s_addc_u32 s49, s27, 0
	s_add_i32 s50, s50, s35
	global_load_lds_dwordx4 v[180:181], off
	v_lshl_add_u64 v[182:183], s[48:49], 0, v[142:143]
	s_mov_b32 m0, s50
	v_lshl_add_u64 v[222:223], s[28:29], 0, v[140:141]
	global_load_lds_dwordx4 v[182:183], off
	v_lshl_add_u64 v[182:183], s[48:49], 0, v[138:139]
	s_add_i32 m0, s50, 0x2000
	s_nop 0
	global_load_lds_dwordx4 v[182:183], off
	v_lshl_add_u64 v[182:183], s[28:29], 0, v[144:145]
	s_mov_b32 m0, s23
	s_nop 0
	global_load_lds_dwordx4 v[182:183], off
	s_mov_b32 m0, s37
	s_nop 0
	global_load_lds_dwordx4 v[222:223], off
	s_waitcnt vmcnt(8)
	s_waitcnt lgkmcnt(0)
	s_barrier
; #define PG8_STAGE(bufoff, gbase, voff) do { _Pragma("unroll") for (int _i = 0; _i < 2; ++_i) \
;         __builtin_amdgcn_global_load_lds((const unsigned*)((const char*)(gbase) + (voff)[_i]), (PG8_LAS unsigned*)(lds + (bufoff) + ldsw + _i * 8192), 16, 0, 0); } while (0)
; #define PG8_LDA(dst, b, h) do { _Pragma("unroll") for (int m = 0; m < 4; ++m) _Pragma("unroll") for (int k = 0; k < 2; ++k) dst[m][k] = *(const PG8_LAS bf16x8*)(lds + PG8_SA(b, h) + aoff + m * 2048 + k * 1024); } while (0)
; #define PG8_LDB(dst, b, h) do { _Pragma("unroll") for (int n = 0; n < 2; ++n) _Pragma("unroll") for (int k = 0; k < 2; ++k) dst[n][k] = *(const PG8_LAS bf16x8*)(lds + PG8_SB(b, h) + boff + n * 2048 + k * 1024); } while (0)
; #define PG8_MMA(ai, bj, At, Bt) do { __builtin_amdgcn_s_setprio(1); _Pragma("unroll") for (int m = 0; m < 4; ++m) _Pragma("unroll") for (int n = 0; n < 2; ++n) _Pragma("unroll") for (int k = 0; k < 2; ++k) \
;         acc[ai][bj][m][n] = __builtin_amdgcn_mfma_f32_16x16x32_bf16(Bt[n][k], At[m][k], acc[ai][bj][m][n], 0, 0, 0); __builtin_amdgcn_s_setprio(0); } while (0)
; #define PG8_WAIT_V(n) asm volatile("s_waitcnt vmcnt(" #n ")" ::: "memory")
; #define PG8_WAIT_L(n) asm volatile("s_waitcnt lgkmcnt(" #n ")" ::: "memory")
; #define PG8_BAR __builtin_amdgcn_s_barrier()
; #define PG8_SCHED __builtin_amdgcn_sched_barrier(0)
; template <class Epi, class Sched, bool ALIGN_EPI = false, bool SP2 = false>
; __device__ __forceinline__ void gemm_phase(PG8_LAS unsigned char* lds, const Gemm g, const Sched& S, const Epi& E) {
;     ...
;             PG8_WAIT_V(8); PG8_WAIT_L(0); PG8_BAR; PG8_MMA(1, 0, At, B0); PG8_MMA(1, 1, At, B1); PG8_BAR; PG8_SCHED;
;             PG8_LDB(B0, 1, 0); PG8_LDB(B1, 1, 1); PG8_SCHED; PG8_LDA(At, 1, 0); PG8_STAGE(PG8_SA(0, 1), a2 + hstep, voffA);
;             PG8_WAIT_V(8); PG8_WAIT_L(0); PG8_BAR; PG8_MMA(0, 0, At, B0); PG8_MMA(0, 1, At, B1); PG8_BAR; PG8_SCHED;
	s_setprio 1
	v_mfma_f32_16x16x32_bf16 v[62:65], v[94:97], v[190:193], 0
	v_mfma_f32_16x16x32_bf16 v[58:61], v[158:161], v[190:193], 0
	v_mfma_f32_16x16x32_bf16 v[50:53], v[94:97], v[198:201], 0
	v_mfma_f32_16x16x32_bf16 v[42:45], v[158:161], v[198:201], 0
	v_mfma_f32_16x16x32_bf16 v[34:37], v[94:97], v[206:209], 0
	v_mfma_f32_16x16x32_bf16 v[26:29], v[158:161], v[206:209], 0
	v_mfma_f32_16x16x32_bf16 v[18:21], v[94:97], v[214:217], 0
	v_mfma_f32_16x16x32_bf16 v[10:13], v[158:161], v[214:217], 0
	v_mfma_f32_16x16x32_bf16 v[62:65], v[134:137], v[194:197], v[62:65]
	v_mfma_f32_16x16x32_bf16 v[58:61], v[162:165], v[194:197], v[58:61]
	v_mfma_f32_16x16x32_bf16 v[50:53], v[134:137], v[202:205], v[50:53]
	v_mfma_f32_16x16x32_bf16 v[42:45], v[162:165], v[202:205], v[42:45]
	v_mfma_f32_16x16x32_bf16 v[34:37], v[134:137], v[210:213], v[34:37]
	v_mfma_f32_16x16x32_bf16 v[26:29], v[162:165], v[210:213], v[26:29]
	v_mfma_f32_16x16x32_bf16 v[18:21], v[134:137], v[218:221], v[18:21]
	v_mfma_f32_16x16x32_bf16 v[10:13], v[162:165], v[218:221], v[10:13]
	s_setprio 0
	s_setprio 1
	v_mfma_f32_16x16x32_bf16 v[54:57], v[166:169], v[190:193], 0
	v_mfma_f32_16x16x32_bf16 v[46:49], v[174:177], v[190:193], 0
	v_mfma_f32_16x16x32_bf16 v[38:41], v[166:169], v[198:201], 0
	v_mfma_f32_16x16x32_bf16 v[30:33], v[174:177], v[198:201], 0
	v_mfma_f32_16x16x32_bf16 v[22:25], v[166:169], v[206:209], 0
	v_mfma_f32_16x16x32_bf16 v[14:17], v[174:177], v[206:209], 0
	v_mfma_f32_16x16x32_bf16 v[6:9], v[166:169], v[214:217], 0
	v_mfma_f32_16x16x32_bf16 v[2:5], v[174:177], v[214:217], 0
	v_mfma_f32_16x16x32_bf16 v[54:57], v[170:173], v[194:197], v[54:57]
	v_mfma_f32_16x16x32_bf16 v[46:49], v[186:189], v[194:197], v[46:49]
	v_mfma_f32_16x16x32_bf16 v[38:41], v[170:173], v[202:205], v[38:41]
	v_mfma_f32_16x16x32_bf16 v[30:33], v[186:189], v[202:205], v[30:33]
	v_mfma_f32_16x16x32_bf16 v[22:25], v[170:173], v[210:213], v[22:25]
	v_mfma_f32_16x16x32_bf16 v[14:17], v[186:189], v[210:213], v[14:17]
	v_mfma_f32_16x16x32_bf16 v[6:9], v[170:173], v[218:221], v[6:9]
	v_mfma_f32_16x16x32_bf16 v[2:5], v[186:189], v[218:221], v[2:5]
	s_setprio 0
	s_barrier
	s_add_i32 s48, 0, 0x18000
	s_add_i32 s49, 0, 0x1c000
	v_add_u32_e32 v162, s48, v156
	v_add_u32_e32 v179, s49, v156
	ds_read_b128 v[94:97], v162
	ds_read_b128 v[134:137], v162 offset:1024
	ds_read_b128 v[158:161], v162 offset:2048
	ds_read_b128 v[162:165], v162 offset:3072
	ds_read_b128 v[166:169], v179
	ds_read_b128 v[170:173], v179 offset:1024
	ds_read_b128 v[174:177], v179 offset:2048
	ds_read_b128 v[186:189], v179 offset:3072
	s_add_u32 s28, s28, 0x40000
	s_addc_u32 s29, s29, 0
	s_mov_b32 m0, s38
	v_lshl_add_u64 v[240:241], s[28:29], 0, v[144:145]
	ds_read_b128 v[190:193], v157 offset:32768
	ds_read_b128 v[194:197], v157 offset:33792
	ds_read_b128 v[198:201], v157 offset:34816
	ds_read_b128 v[202:205], v157 offset:35840
	ds_read_b128 v[206:209], v157 offset:36864
	ds_read_b128 v[210:213], v157 offset:37888
	ds_read_b128 v[214:217], v157 offset:38912
	ds_read_b128 v[218:221], v157 offset:39936
	global_load_lds_dwordx4 v[240:241], off
	v_lshl_add_u64 v[240:241], s[28:29], 0, v[140:141]
	s_mov_b32 m0, s39
	s_nop 0
	global_load_lds_dwordx4 v[240:241], off
	s_waitcnt vmcnt(8)
	s_waitcnt lgkmcnt(0)
	s_barrier
	s_setprio 1
	v_mfma_f32_16x16x32_bf16 v[130:133], v[94:97], v[190:193], v[130:133]
	v_mfma_f32_16x16x32_bf16 v[126:129], v[158:161], v[190:193], v[126:129]
	v_mfma_f32_16x16x32_bf16 v[114:117], v[94:97], v[198:201], v[114:117]
	v_mfma_f32_16x16x32_bf16 v[110:113], v[158:161], v[198:201], v[110:113]
	v_mfma_f32_16x16x32_bf16 v[98:101], v[94:97], v[206:209], v[98:101]
	v_mfma_f32_16x16x32_bf16 v[90:93], v[158:161], v[206:209], v[90:93]
	v_mfma_f32_16x16x32_bf16 v[78:81], v[94:97], v[214:217], v[78:81]
	v_mfma_f32_16x16x32_bf16 v[74:77], v[158:161], v[214:217], v[74:77]
	v_mfma_f32_16x16x32_bf16 v[130:133], v[134:137], v[194:197], v[130:133]
	v_mfma_f32_16x16x32_bf16 v[126:129], v[162:165], v[194:197], v[126:129]
	v_mfma_f32_16x16x32_bf16 v[114:117], v[134:137], v[202:205], v[114:117]
	v_mfma_f32_16x16x32_bf16 v[110:113], v[162:165], v[202:205], v[110:113]
	v_mfma_f32_16x16x32_bf16 v[98:101], v[134:137], v[210:213], v[98:101]
	v_mfma_f32_16x16x32_bf16 v[90:93], v[162:165], v[210:213], v[90:93]
	v_mfma_f32_16x16x32_bf16 v[78:81], v[134:137], v[218:221], v[78:81]
	v_mfma_f32_16x16x32_bf16 v[74:77], v[162:165], v[218:221], v[74:77]
	s_setprio 0
	s_setprio 1
	v_mfma_f32_16x16x32_bf16 v[122:125], v[166:169], v[190:193], v[122:125]
	v_mfma_f32_16x16x32_bf16 v[118:121], v[174:177], v[190:193], v[118:121]
	v_mfma_f32_16x16x32_bf16 v[106:109], v[166:169], v[198:201], v[106:109]
	v_mfma_f32_16x16x32_bf16 v[102:105], v[174:177], v[198:201], v[102:105]
	v_mfma_f32_16x16x32_bf16 v[86:89], v[166:169], v[206:209], v[86:89]
	v_mfma_f32_16x16x32_bf16 v[82:85], v[174:177], v[206:209], v[82:85]
	v_mfma_f32_16x16x32_bf16 v[70:73], v[166:169], v[214:217], v[70:73]
	v_mfma_f32_16x16x32_bf16 v[66:69], v[174:177], v[214:217], v[66:69]
	v_mfma_f32_16x16x32_bf16 v[122:125], v[170:173], v[194:197], v[122:125]
	v_mfma_f32_16x16x32_bf16 v[118:121], v[186:189], v[194:197], v[118:121]
	v_mfma_f32_16x16x32_bf16 v[106:109], v[170:173], v[202:205], v[106:109]
	v_mfma_f32_16x16x32_bf16 v[102:105], v[186:189], v[202:205], v[102:105]
	v_mfma_f32_16x16x32_bf16 v[86:89], v[170:173], v[210:213], v[86:89]
	v_mfma_f32_16x16x32_bf16 v[82:85], v[186:189], v[210:213], v[82:85]
	v_mfma_f32_16x16x32_bf16 v[70:73], v[170:173], v[218:221], v[70:73]
	v_mfma_f32_16x16x32_bf16 v[66:69], v[186:189], v[218:221], v[66:69]
	s_setprio 0
	s_barrier
; #define PG8_STAGE(bufoff, gbase, voff) do { _Pragma("unroll") for (int _i = 0; _i < 2; ++_i) \
;         __builtin_amdgcn_global_load_lds((const unsigned*)((const char*)(gbase) + (voff)[_i]), (PG8_LAS unsigned*)(lds + (bufoff) + ldsw + _i * 8192), 16, 0, 0); } while (0)
; #define PG8_LDA(dst, b, h) do { _Pragma("unroll") for (int m = 0; m < 4; ++m) _Pragma("unroll") for (int k = 0; k < 2; ++k) dst[m][k] = *(const PG8_LAS bf16x8*)(lds + PG8_SA(b, h) + aoff + m * 2048 + k * 1024); } while (0)
; #define PG8_MMA(ai, bj, At, Bt) do { __builtin_amdgcn_s_setprio(1); _Pragma("unroll") for (int m = 0; m < 4; ++m) _Pragma("unroll") for (int n = 0; n < 2; ++n) _Pragma("unroll") for (int k = 0; k < 2; ++k) \
;         acc[ai][bj][m][n] = __builtin_amdgcn_mfma_f32_16x16x32_bf16(Bt[n][k], At[m][k], acc[ai][bj][m][n], 0, 0, 0); __builtin_amdgcn_s_setprio(0); } while (0)
; #define PG8_WAIT_V(n) asm volatile("s_waitcnt vmcnt(" #n ")" ::: "memory")
; #define PG8_WAIT_L(n) asm volatile("s_waitcnt lgkmcnt(" #n ")" ::: "memory")
; #define PG8_BAR __builtin_amdgcn_s_barrier()
; #define PG8_SCHED __builtin_amdgcn_sched_barrier(0)
; template <class Epi, class Sched, bool ALIGN_EPI = false, bool SP2 = false>
; __device__ __forceinline__ void gemm_phase(PG8_LAS unsigned char* lds, const Gemm g, const Sched& S, const Epi& E) {
;     ...
;             PG8_LDA(At, 1, 1); PG8_STAGE(PG8_SB(1, 0), b3, voffB); PG8_STAGE(PG8_SB(1, 1), b3 + hstep, voffB); PG8_STAGE(PG8_SA(1, 0), a3, voffA);
;             PG8_WAIT_V(8); PG8_WAIT_L(0); PG8_BAR; PG8_MMA(1, 0, At, B0); PG8_MMA(1, 1, At, B1); PG8_BAR; PG8_SCHED;
	s_add_i32 s28, s48, s35
	v_lshl_add_u64 v[154:155], v[154:155], 0, s[80:81]
	s_mov_b32 m0, s28
	ds_read_b128 v[190:193], v157 offset:49152
	ds_read_b128 v[194:197], v157 offset:50176
	ds_read_b128 v[198:201], v157 offset:51200
	ds_read_b128 v[202:205], v157 offset:52224
	ds_read_b128 v[206:209], v157 offset:53248
	ds_read_b128 v[210:213], v157 offset:54272
	ds_read_b128 v[214:217], v157 offset:55296
	ds_read_b128 v[218:221], v157 offset:56320
	global_load_lds_dwordx4 v[154:155], off
	s_add_i32 m0, s28, 0x2000
	s_add_u32 s26, s26, 0x40080
	v_lshl_add_u64 v[154:155], v[180:181], 0, s[80:81]
	s_addc_u32 s27, s27, 0
	s_add_i32 s28, s49, s35
	global_load_lds_dwordx4 v[154:155], off
	v_lshl_add_u64 v[154:155], s[26:27], 0, v[142:143]
	s_mov_b32 m0, s28
	s_nop 0
	global_load_lds_dwordx4 v[154:155], off
	v_lshl_add_u64 v[154:155], s[26:27], 0, v[138:139]
	s_add_i32 m0, s28, 0x2000
	s_nop 0
	global_load_lds_dwordx4 v[154:155], off
	v_lshl_add_u64 v[154:155], v[182:183], 0, s[80:81]
	s_mov_b32 m0, s40
	s_nop 0
	global_load_lds_dwordx4 v[154:155], off
	v_lshl_add_u64 v[154:155], v[222:223], 0, s[80:81]
	s_mov_b32 m0, s41
	s_nop 0
	global_load_lds_dwordx4 v[154:155], off
	s_waitcnt vmcnt(8)
	s_waitcnt lgkmcnt(0)
	s_barrier
	s_setprio 1
	v_mfma_f32_16x16x32_bf16 v[62:65], v[94:97], v[190:193], v[62:65]
	v_mfma_f32_16x16x32_bf16 v[58:61], v[158:161], v[190:193], v[58:61]
	v_mfma_f32_16x16x32_bf16 v[50:53], v[94:97], v[198:201], v[50:53]
	v_mfma_f32_16x16x32_bf16 v[42:45], v[158:161], v[198:201], v[42:45]
	v_mfma_f32_16x16x32_bf16 v[34:37], v[94:97], v[206:209], v[34:37]
	v_mfma_f32_16x16x32_bf16 v[26:29], v[158:161], v[206:209], v[26:29]
	v_mfma_f32_16x16x32_bf16 v[18:21], v[94:97], v[214:217], v[18:21]
	v_mfma_f32_16x16x32_bf16 v[10:13], v[158:161], v[214:217], v[10:13]
	v_mfma_f32_16x16x32_bf16 v[62:65], v[134:137], v[194:197], v[62:65]
	v_mfma_f32_16x16x32_bf16 v[58:61], v[162:165], v[194:197], v[58:61]
	v_mfma_f32_16x16x32_bf16 v[50:53], v[134:137], v[202:205], v[50:53]
	v_mfma_f32_16x16x32_bf16 v[42:45], v[162:165], v[202:205], v[42:45]
	v_mfma_f32_16x16x32_bf16 v[34:37], v[134:137], v[210:213], v[34:37]
	v_mfma_f32_16x16x32_bf16 v[26:29], v[162:165], v[210:213], v[26:29]
	v_mfma_f32_16x16x32_bf16 v[18:21], v[134:137], v[218:221], v[18:21]
	v_mfma_f32_16x16x32_bf16 v[10:13], v[162:165], v[218:221], v[10:13]
	s_setprio 0
	s_setprio 1
	v_mfma_f32_16x16x32_bf16 v[54:57], v[166:169], v[190:193], v[54:57]
	v_mfma_f32_16x16x32_bf16 v[46:49], v[174:177], v[190:193], v[46:49]
	v_mfma_f32_16x16x32_bf16 v[38:41], v[166:169], v[198:201], v[38:41]
	v_mfma_f32_16x16x32_bf16 v[30:33], v[174:177], v[198:201], v[30:33]
	v_mfma_f32_16x16x32_bf16 v[22:25], v[166:169], v[206:209], v[22:25]
	v_mfma_f32_16x16x32_bf16 v[14:17], v[174:177], v[206:209], v[14:17]
	v_mfma_f32_16x16x32_bf16 v[6:9], v[166:169], v[214:217], v[6:9]
	v_mfma_f32_16x16x32_bf16 v[2:5], v[174:177], v[214:217], v[2:5]
	v_mfma_f32_16x16x32_bf16 v[54:57], v[170:173], v[194:197], v[54:57]
	v_mfma_f32_16x16x32_bf16 v[46:49], v[186:189], v[194:197], v[46:49]
	v_mfma_f32_16x16x32_bf16 v[38:41], v[170:173], v[202:205], v[38:41]
	v_mfma_f32_16x16x32_bf16 v[30:33], v[186:189], v[202:205], v[30:33]
	v_mfma_f32_16x16x32_bf16 v[22:25], v[170:173], v[210:213], v[22:25]
	v_mfma_f32_16x16x32_bf16 v[14:17], v[186:189], v[210:213], v[14:17]
	v_mfma_f32_16x16x32_bf16 v[6:9], v[170:173], v[218:221], v[6:9]
	v_mfma_f32_16x16x32_bf16 v[2:5], v[186:189], v[218:221], v[2:5]
	s_setprio 0
	s_barrier
	s_add_i32 s47, s47, 2
	s_add_u32 s24, s24, 0x100
	s_addc_u32 s25, s25, 0
	s_add_u32 s45, s45, 0x100
	s_addc_u32 s46, s46, 0
	s_cmp_gt_u32 s47, 13
	s_branch .LBB0_318

; #define PG8_STAGE(bufoff, gbase, voff) do { _Pragma("unroll") for (int _i = 0; _i < 2; ++_i) \
;         __builtin_amdgcn_global_load_lds((const unsigned*)((const char*)(gbase) + (voff)[_i]), (PG8_LAS unsigned*)(lds + (bufoff) + ldsw + _i * 8192), 16, 0, 0); } while (0)
; #define PG8_LDA(dst, b, h) do { _Pragma("unroll") for (int m = 0; m < 4; ++m) _Pragma("unroll") for (int k = 0; k < 2; ++k) dst[m][k] = *(const PG8_LAS bf16x8*)(lds + PG8_SA(b, h) + aoff + m * 2048 + k * 1024); } while (0)
; #define PG8_LDB(dst, b, h) do { _Pragma("unroll") for (int n = 0; n < 2; ++n) _Pragma("unroll") for (int k = 0; k < 2; ++k) dst[n][k] = *(const PG8_LAS bf16x8*)(lds + PG8_SB(b, h) + boff + n * 2048 + k * 1024); } while (0)
; #define PG8_MMA(ai, bj, At, Bt) do { __builtin_amdgcn_s_setprio(1); _Pragma("unroll") for (int m = 0; m < 4; ++m) _Pragma("unroll") for (int n = 0; n < 2; ++n) _Pragma("unroll") for (int k = 0; k < 2; ++k) \
;         acc[ai][bj][m][n] = __builtin_amdgcn_mfma_f32_16x16x32_bf16(Bt[n][k], At[m][k], acc[ai][bj][m][n], 0, 0, 0); __builtin_amdgcn_s_setprio(0); } while (0)
; #define PG8_WAIT_V(n) asm volatile("s_waitcnt vmcnt(" #n ")" ::: "memory")
; template <class Epi, class Sched, bool ALIGN_EPI = false, bool SP2 = false>
; __device__ __forceinline__ void gemm_phase(PG8_LAS unsigned char* lds, const Gemm g, const Sched& S, const Epi& E) {
;     ...
;         const char* nA = has_next ? (const char*)g.A + (size_t)nxt.pm * tstep : cA; const char* nB = has_next ? (const char*)g.Bt + (size_t)nxt.pn * tstep : cB;
;         for (int t = 0; t < nt; t += 2) {
;             const bool last = (t == nt - 2);
;             const char* a1 = cA + (size_t)(t + 1) * kstep;
;             const char* a2 = last ? nA : cA + (size_t)(t + 2) * kstep; const char* b2 = last ? nB : cB + (size_t)(t + 2) * kstep;
;             const char* a3 = a2 + kstep; const char* b3 = b2 + kstep;
;             if (last && has_next) S.a_ready(nxt);
;             if constexpr (SP2) {
;             PG8_LDB(B0, 0, 0); PG8_LDB(B1, 0, 1); PG8_SCHED; PG8_LDA(At, 0, 0); PG8_STAGE(PG8_SA(1, 1), a1 + hstep, voffA);
;             PG8_WAIT_V(8); PG8_WAIT_L(0); PG8_BAR; PG8_MMA(0, 0, At, B0); PG8_MMA(0, 1, At, B1); PG8_BAR; PG8_SCHED;
;             PG8_LDA(At, 0, 1); PG8_STAGE(PG8_SB(0, 0), b2, voffB); PG8_STAGE(PG8_SB(0, 1), b2 + hstep, voffB); PG8_STAGE(PG8_SA(0, 0), a2, voffA);
.LBB0_1061:
	s_ashr_i32 s23, s22, 31
	s_lshl_b64 s[24:25], s[22:23], 19
	s_add_u32 s24, s42, s24
	s_addc_u32 s25, s43, s25
	s_and_b64 s[26:27], s[6:7], exec
	s_cselect_b32 s23, s25, s35
	s_cselect_b32 s29, s24, s34
	s_ashr_i32 s21, s20, 31
	s_lshl_b64 s[26:27], s[20:21], 19
	s_add_u32 s26, s40, s26
	s_addc_u32 s27, s41, s27
	s_and_b64 s[38:39], s[6:7], exec
	s_cselect_b32 s21, s27, s37
	s_cselect_b32 s31, s26, s36
	s_add_u32 s34, s34, 0x40080
	s_addc_u32 s35, s35, 0
	s_add_u32 s56, s36, 0x100
	s_addc_u32 s57, s37, 0
	s_mov_b32 s58, -2
	s_waitcnt lgkmcnt(0)
	s_add_u32 s36, s34, 0xfffc0080
	s_addc_u32 s37, s35, -1
	s_add_i32 s59, 0, 0x10000
	s_cmp_eq_u32 s58, 12
	s_cselect_b32 s39, s23, s37
	s_cselect_b32 s38, s29, s36
	s_cselect_b32 s37, s21, s57
	s_cselect_b32 s36, s31, s56
	s_add_i32 s62, 0, 0x14000
	v_add_u32_e32 v142, s59, v179
	v_add_u32_e32 v170, s62, v179
	ds_read_b128 v[130:133], v142
	ds_read_b128 v[134:137], v142 offset:1024
	ds_read_b128 v[138:141], v142 offset:2048
	ds_read_b128 v[142:145], v142 offset:3072
	ds_read_b128 v[146:149], v170
	ds_read_b128 v[150:153], v170 offset:1024
	ds_read_b128 v[166:169], v170 offset:2048
	ds_read_b128 v[170:173], v170 offset:3072
	v_lshl_add_u64 v[212:213], s[34:35], 0, v[162:163]
	s_add_i32 m0, s46, 0xc000
	ds_read_b128 v[174:177], v187
	ds_read_b128 v[180:183], v187 offset:1024
	ds_read_b128 v[188:191], v187 offset:2048
	ds_read_b128 v[192:195], v187 offset:3072
	ds_read_b128 v[196:199], v187 offset:4096
	ds_read_b128 v[200:203], v187 offset:5120
	ds_read_b128 v[204:207], v187 offset:6144
	ds_read_b128 v[208:211], v187 offset:7168
	global_load_lds_dwordx4 v[212:213], off
	v_lshl_add_u64 v[212:213], s[34:35], 0, v[164:165]
	s_add_i32 m0, s46, 0xe000
	s_nop 0
	global_load_lds_dwordx4 v[212:213], off
	s_waitcnt vmcnt(8)
	s_waitcnt lgkmcnt(0)
	s_barrier
	s_setprio 1
	v_mfma_f32_16x16x32_bf16 v[126:129], v[130:133], v[174:177], 0
	v_mfma_f32_16x16x32_bf16 v[122:125], v[138:141], v[174:177], 0
	v_mfma_f32_16x16x32_bf16 v[110:113], v[130:133], v[188:191], 0
	v_mfma_f32_16x16x32_bf16 v[106:109], v[138:141], v[188:191], 0
	v_mfma_f32_16x16x32_bf16 v[94:97], v[130:133], v[196:199], 0
	v_mfma_f32_16x16x32_bf16 v[90:93], v[138:141], v[196:199], 0
	v_mfma_f32_16x16x32_bf16 v[78:81], v[130:133], v[204:207], 0
	v_mfma_f32_16x16x32_bf16 v[74:77], v[138:141], v[204:207], 0
	v_mfma_f32_16x16x32_bf16 v[126:129], v[134:137], v[180:183], v[126:129]
	v_mfma_f32_16x16x32_bf16 v[122:125], v[142:145], v[180:183], v[122:125]
	v_mfma_f32_16x16x32_bf16 v[110:113], v[134:137], v[192:195], v[110:113]
	v_mfma_f32_16x16x32_bf16 v[106:109], v[142:145], v[192:195], v[106:109]
	v_mfma_f32_16x16x32_bf16 v[94:97], v[134:137], v[200:203], v[94:97]
	v_mfma_f32_16x16x32_bf16 v[90:93], v[142:145], v[200:203], v[90:93]
	v_mfma_f32_16x16x32_bf16 v[78:81], v[134:137], v[208:211], v[78:81]
	v_mfma_f32_16x16x32_bf16 v[74:77], v[142:145], v[208:211], v[74:77]
	s_setprio 0
	s_setprio 1
	v_mfma_f32_16x16x32_bf16 v[118:121], v[146:149], v[174:177], 0
	v_mfma_f32_16x16x32_bf16 v[114:117], v[166:169], v[174:177], 0
	v_mfma_f32_16x16x32_bf16 v[102:105], v[146:149], v[188:191], 0
	v_mfma_f32_16x16x32_bf16 v[98:101], v[166:169], v[188:191], 0
	v_mfma_f32_16x16x32_bf16 v[86:89], v[146:149], v[196:199], 0
	v_mfma_f32_16x16x32_bf16 v[82:85], v[166:169], v[196:199], 0
	v_mfma_f32_16x16x32_bf16 v[70:73], v[146:149], v[204:207], 0
	v_mfma_f32_16x16x32_bf16 v[66:69], v[166:169], v[204:207], 0
	v_mfma_f32_16x16x32_bf16 v[118:121], v[150:153], v[180:183], v[118:121]
	v_mfma_f32_16x16x32_bf16 v[114:117], v[170:173], v[180:183], v[114:117]
	v_mfma_f32_16x16x32_bf16 v[102:105], v[150:153], v[192:195], v[102:105]
	v_mfma_f32_16x16x32_bf16 v[98:101], v[170:173], v[192:195], v[98:101]
	v_mfma_f32_16x16x32_bf16 v[86:89], v[150:153], v[200:203], v[86:89]
	v_mfma_f32_16x16x32_bf16 v[82:85], v[170:173], v[200:203], v[82:85]
	v_mfma_f32_16x16x32_bf16 v[70:73], v[150:153], v[208:211], v[70:73]
	v_mfma_f32_16x16x32_bf16 v[66:69], v[170:173], v[208:211], v[66:69]
	s_setprio 0
	s_barrier
	s_add_i32 s59, s59, s33
	v_lshl_add_u64 v[212:213], s[36:37], 0, v[156:157]
	s_mov_b32 m0, s59
	ds_read_b128 v[174:177], v187 offset:16384
	ds_read_b128 v[180:183], v187 offset:17408
	ds_read_b128 v[188:191], v187 offset:18432
	ds_read_b128 v[192:195], v187 offset:19456
	ds_read_b128 v[196:199], v187 offset:20480
	ds_read_b128 v[200:203], v187 offset:21504
	ds_read_b128 v[204:207], v187 offset:22528
	ds_read_b128 v[208:211], v187 offset:23552
	global_load_lds_dwordx4 v[212:213], off
	s_add_i32 m0, s59, 0x2000
	s_add_u32 s60, s36, 0x40000
	v_lshl_add_u64 v[214:215], s[36:37], 0, v[160:161]
	s_addc_u32 s61, s37, 0
	s_add_i32 s59, s62, s33
	global_load_lds_dwordx4 v[214:215], off
	v_lshl_add_u64 v[216:217], s[60:61], 0, v[156:157]
	s_mov_b32 m0, s59
	v_lshl_add_u64 v[218:219], s[38:39], 0, v[158:159]
	global_load_lds_dwordx4 v[216:217], off
	v_lshl_add_u64 v[216:217], s[60:61], 0, v[160:161]
	s_add_i32 m0, s59, 0x2000
	s_nop 0
	global_load_lds_dwordx4 v[216:217], off
	v_lshl_add_u64 v[216:217], s[38:39], 0, v[154:155]
	s_mov_b32 m0, s46
	s_nop 0
	global_load_lds_dwordx4 v[216:217], off
	s_mov_b32 m0, s47
	s_nop 0
	global_load_lds_dwordx4 v[218:219], off
	s_waitcnt vmcnt(8)
	s_waitcnt lgkmcnt(0)
	s_barrier
; #define PG8_STAGE(bufoff, gbase, voff) do { _Pragma("unroll") for (int _i = 0; _i < 2; ++_i) \
;         __builtin_amdgcn_global_load_lds((const unsigned*)((const char*)(gbase) + (voff)[_i]), (PG8_LAS unsigned*)(lds + (bufoff) + ldsw + _i * 8192), 16, 0, 0); } while (0)
; #define PG8_LDA(dst, b, h) do { _Pragma("unroll") for (int m = 0; m < 4; ++m) _Pragma("unroll") for (int k = 0; k < 2; ++k) dst[m][k] = *(const PG8_LAS bf16x8*)(lds + PG8_SA(b, h) + aoff + m * 2048 + k * 1024); } while (0)
; #define PG8_LDB(dst, b, h) do { _Pragma("unroll") for (int n = 0; n < 2; ++n) _Pragma("unroll") for (int k = 0; k < 2; ++k) dst[n][k] = *(const PG8_LAS bf16x8*)(lds + PG8_SB(b, h) + boff + n * 2048 + k * 1024); } while (0)
; #define PG8_MMA(ai, bj, At, Bt) do { __builtin_amdgcn_s_setprio(1); _Pragma("unroll") for (int m = 0; m < 4; ++m) _Pragma("unroll") for (int n = 0; n < 2; ++n) _Pragma("unroll") for (int k = 0; k < 2; ++k) \
;         acc[ai][bj][m][n] = __builtin_amdgcn_mfma_f32_16x16x32_bf16(Bt[n][k], At[m][k], acc[ai][bj][m][n], 0, 0, 0); __builtin_amdgcn_s_setprio(0); } while (0)
; #define PG8_WAIT_V(n) asm volatile("s_waitcnt vmcnt(" #n ")" ::: "memory")
; #define PG8_WAIT_L(n) asm volatile("s_waitcnt lgkmcnt(" #n ")" ::: "memory")
; #define PG8_BAR __builtin_amdgcn_s_barrier()
; #define PG8_SCHED __builtin_amdgcn_sched_barrier(0)
; template <class Epi, class Sched, bool ALIGN_EPI = false, bool SP2 = false>
; __device__ __forceinline__ void gemm_phase(PG8_LAS unsigned char* lds, const Gemm g, const Sched& S, const Epi& E) {
;     ...
;             PG8_WAIT_V(8); PG8_WAIT_L(0); PG8_BAR; PG8_MMA(1, 0, At, B0); PG8_MMA(1, 1, At, B1); PG8_BAR; PG8_SCHED;
;             PG8_LDB(B0, 1, 0); PG8_LDB(B1, 1, 1); PG8_SCHED; PG8_LDA(At, 1, 0); PG8_STAGE(PG8_SA(0, 1), a2 + hstep, voffA);
;             PG8_WAIT_V(8); PG8_WAIT_L(0); PG8_BAR; PG8_MMA(0, 0, At, B0); PG8_MMA(0, 1, At, B1); PG8_BAR; PG8_SCHED;
	s_setprio 1
	v_mfma_f32_16x16x32_bf16 v[62:65], v[130:133], v[174:177], 0
	v_mfma_f32_16x16x32_bf16 v[58:61], v[138:141], v[174:177], 0
	v_mfma_f32_16x16x32_bf16 v[46:49], v[130:133], v[188:191], 0
	v_mfma_f32_16x16x32_bf16 v[42:45], v[138:141], v[188:191], 0
	v_mfma_f32_16x16x32_bf16 v[30:33], v[130:133], v[196:199], 0
	v_mfma_f32_16x16x32_bf16 v[26:29], v[138:141], v[196:199], 0
	v_mfma_f32_16x16x32_bf16 v[14:17], v[130:133], v[204:207], 0
	v_mfma_f32_16x16x32_bf16 v[10:13], v[138:141], v[204:207], 0
	v_mfma_f32_16x16x32_bf16 v[62:65], v[134:137], v[180:183], v[62:65]
	v_mfma_f32_16x16x32_bf16 v[58:61], v[142:145], v[180:183], v[58:61]
	v_mfma_f32_16x16x32_bf16 v[46:49], v[134:137], v[192:195], v[46:49]
	v_mfma_f32_16x16x32_bf16 v[42:45], v[142:145], v[192:195], v[42:45]
	v_mfma_f32_16x16x32_bf16 v[30:33], v[134:137], v[200:203], v[30:33]
	v_mfma_f32_16x16x32_bf16 v[26:29], v[142:145], v[200:203], v[26:29]
	v_mfma_f32_16x16x32_bf16 v[14:17], v[134:137], v[208:211], v[14:17]
	v_mfma_f32_16x16x32_bf16 v[10:13], v[142:145], v[208:211], v[10:13]
	s_setprio 0
	s_setprio 1
	v_mfma_f32_16x16x32_bf16 v[54:57], v[146:149], v[174:177], 0
	v_mfma_f32_16x16x32_bf16 v[50:53], v[166:169], v[174:177], 0
	v_mfma_f32_16x16x32_bf16 v[38:41], v[146:149], v[188:191], 0
	v_mfma_f32_16x16x32_bf16 v[34:37], v[166:169], v[188:191], 0
	v_mfma_f32_16x16x32_bf16 v[22:25], v[146:149], v[196:199], 0
	v_mfma_f32_16x16x32_bf16 v[18:21], v[166:169], v[196:199], 0
	v_mfma_f32_16x16x32_bf16 v[6:9], v[146:149], v[204:207], 0
	v_mfma_f32_16x16x32_bf16 v[2:5], v[166:169], v[204:207], 0
	v_mfma_f32_16x16x32_bf16 v[54:57], v[150:153], v[180:183], v[54:57]
	v_mfma_f32_16x16x32_bf16 v[50:53], v[170:173], v[180:183], v[50:53]
	v_mfma_f32_16x16x32_bf16 v[38:41], v[150:153], v[192:195], v[38:41]
	v_mfma_f32_16x16x32_bf16 v[34:37], v[170:173], v[192:195], v[34:37]
	v_mfma_f32_16x16x32_bf16 v[22:25], v[150:153], v[200:203], v[22:25]
	v_mfma_f32_16x16x32_bf16 v[18:21], v[170:173], v[200:203], v[18:21]
	v_mfma_f32_16x16x32_bf16 v[6:9], v[150:153], v[208:211], v[6:9]
	v_mfma_f32_16x16x32_bf16 v[2:5], v[170:173], v[208:211], v[2:5]
	s_setprio 0
	s_barrier
	s_add_i32 s59, 0, 0x18000
	s_add_i32 s60, 0, 0x1c000
	v_add_u32_e32 v142, s59, v179
	v_add_u32_e32 v170, s60, v179
	ds_read_b128 v[130:133], v142
	ds_read_b128 v[134:137], v142 offset:1024
	ds_read_b128 v[138:141], v142 offset:2048
	ds_read_b128 v[142:145], v142 offset:3072
	ds_read_b128 v[146:149], v170
	ds_read_b128 v[150:153], v170 offset:1024
	ds_read_b128 v[166:169], v170 offset:2048
	ds_read_b128 v[170:173], v170 offset:3072
	s_add_u32 s38, s38, 0x40000
	s_addc_u32 s39, s39, 0
	s_mov_b32 m0, s48
	v_lshl_add_u64 v[220:221], s[38:39], 0, v[154:155]
	ds_read_b128 v[174:177], v187 offset:32768
	ds_read_b128 v[180:183], v187 offset:33792
	ds_read_b128 v[188:191], v187 offset:34816
	ds_read_b128 v[192:195], v187 offset:35840
	ds_read_b128 v[196:199], v187 offset:36864
	ds_read_b128 v[200:203], v187 offset:37888
	ds_read_b128 v[204:207], v187 offset:38912
	ds_read_b128 v[208:211], v187 offset:39936
	global_load_lds_dwordx4 v[220:221], off
	v_lshl_add_u64 v[220:221], s[38:39], 0, v[158:159]
	s_mov_b32 m0, s49
	s_nop 0
	global_load_lds_dwordx4 v[220:221], off
	s_waitcnt vmcnt(8)
	s_waitcnt lgkmcnt(0)
	s_barrier
	s_setprio 1
	v_mfma_f32_16x16x32_bf16 v[126:129], v[130:133], v[174:177], v[126:129]
	v_mfma_f32_16x16x32_bf16 v[122:125], v[138:141], v[174:177], v[122:125]
	v_mfma_f32_16x16x32_bf16 v[110:113], v[130:133], v[188:191], v[110:113]
	v_mfma_f32_16x16x32_bf16 v[106:109], v[138:141], v[188:191], v[106:109]
	v_mfma_f32_16x16x32_bf16 v[94:97], v[130:133], v[196:199], v[94:97]
	v_mfma_f32_16x16x32_bf16 v[90:93], v[138:141], v[196:199], v[90:93]
	v_mfma_f32_16x16x32_bf16 v[78:81], v[130:133], v[204:207], v[78:81]
	v_mfma_f32_16x16x32_bf16 v[74:77], v[138:141], v[204:207], v[74:77]
	v_mfma_f32_16x16x32_bf16 v[126:129], v[134:137], v[180:183], v[126:129]
	v_mfma_f32_16x16x32_bf16 v[122:125], v[142:145], v[180:183], v[122:125]
	v_mfma_f32_16x16x32_bf16 v[110:113], v[134:137], v[192:195], v[110:113]
	v_mfma_f32_16x16x32_bf16 v[106:109], v[142:145], v[192:195], v[106:109]
	v_mfma_f32_16x16x32_bf16 v[94:97], v[134:137], v[200:203], v[94:97]
	v_mfma_f32_16x16x32_bf16 v[90:93], v[142:145], v[200:203], v[90:93]
	v_mfma_f32_16x16x32_bf16 v[78:81], v[134:137], v[208:211], v[78:81]
	v_mfma_f32_16x16x32_bf16 v[74:77], v[142:145], v[208:211], v[74:77]
	s_setprio 0
	s_setprio 1
	v_mfma_f32_16x16x32_bf16 v[118:121], v[146:149], v[174:177], v[118:121]
	v_mfma_f32_16x16x32_bf16 v[114:117], v[166:169], v[174:177], v[114:117]
	v_mfma_f32_16x16x32_bf16 v[102:105], v[146:149], v[188:191], v[102:105]
	v_mfma_f32_16x16x32_bf16 v[98:101], v[166:169], v[188:191], v[98:101]
	v_mfma_f32_16x16x32_bf16 v[86:89], v[146:149], v[196:199], v[86:89]
	v_mfma_f32_16x16x32_bf16 v[82:85], v[166:169], v[196:199], v[82:85]
	v_mfma_f32_16x16x32_bf16 v[70:73], v[146:149], v[204:207], v[70:73]
	v_mfma_f32_16x16x32_bf16 v[66:69], v[166:169], v[204:207], v[66:69]
	v_mfma_f32_16x16x32_bf16 v[118:121], v[150:153], v[180:183], v[118:121]
	v_mfma_f32_16x16x32_bf16 v[114:117], v[170:173], v[180:183], v[114:117]
	v_mfma_f32_16x16x32_bf16 v[102:105], v[150:153], v[192:195], v[102:105]
	v_mfma_f32_16x16x32_bf16 v[98:101], v[170:173], v[192:195], v[98:101]
	v_mfma_f32_16x16x32_bf16 v[86:89], v[150:153], v[200:203], v[86:89]
	v_mfma_f32_16x16x32_bf16 v[82:85], v[170:173], v[200:203], v[82:85]
	v_mfma_f32_16x16x32_bf16 v[70:73], v[150:153], v[208:211], v[70:73]
	v_mfma_f32_16x16x32_bf16 v[66:69], v[170:173], v[208:211], v[66:69]
	s_setprio 0
	s_barrier
; #define PG8_STAGE(bufoff, gbase, voff) do { _Pragma("unroll") for (int _i = 0; _i < 2; ++_i) \
;         __builtin_amdgcn_global_load_lds((const unsigned*)((const char*)(gbase) + (voff)[_i]), (PG8_LAS unsigned*)(lds + (bufoff) + ldsw + _i * 8192), 16, 0, 0); } while (0)
; #define PG8_LDA(dst, b, h) do { _Pragma("unroll") for (int m = 0; m < 4; ++m) _Pragma("unroll") for (int k = 0; k < 2; ++k) dst[m][k] = *(const PG8_LAS bf16x8*)(lds + PG8_SA(b, h) + aoff + m * 2048 + k * 1024); } while (0)
; #define PG8_MMA(ai, bj, At, Bt) do { __builtin_amdgcn_s_setprio(1); _Pragma("unroll") for (int m = 0; m < 4; ++m) _Pragma("unroll") for (int n = 0; n < 2; ++n) _Pragma("unroll") for (int k = 0; k < 2; ++k) \
;         acc[ai][bj][m][n] = __builtin_amdgcn_mfma_f32_16x16x32_bf16(Bt[n][k], At[m][k], acc[ai][bj][m][n], 0, 0, 0); __builtin_amdgcn_s_setprio(0); } while (0)
; #define PG8_WAIT_V(n) asm volatile("s_waitcnt vmcnt(" #n ")" ::: "memory")
; #define PG8_WAIT_L(n) asm volatile("s_waitcnt lgkmcnt(" #n ")" ::: "memory")
; #define PG8_BAR __builtin_amdgcn_s_barrier()
; #define PG8_SCHED __builtin_amdgcn_sched_barrier(0)
; template <class Epi, class Sched, bool ALIGN_EPI = false, bool SP2 = false>
; __device__ __forceinline__ void gemm_phase(PG8_LAS unsigned char* lds, const Gemm g, const Sched& S, const Epi& E) {
;     ...
;             PG8_LDA(At, 1, 1); PG8_STAGE(PG8_SB(1, 0), b3, voffB); PG8_STAGE(PG8_SB(1, 1), b3 + hstep, voffB); PG8_STAGE(PG8_SA(1, 0), a3, voffA);
;             PG8_WAIT_V(8); PG8_WAIT_L(0); PG8_BAR; PG8_MMA(1, 0, At, B0); PG8_MMA(1, 1, At, B1); PG8_BAR; PG8_SCHED;
	s_add_i32 s38, s59, s33
	v_lshl_add_u64 v[212:213], v[212:213], 0, s[80:81]
	s_mov_b32 m0, s38
	ds_read_b128 v[174:177], v187 offset:49152
	ds_read_b128 v[180:183], v187 offset:50176
	ds_read_b128 v[188:191], v187 offset:51200
	ds_read_b128 v[192:195], v187 offset:52224
	ds_read_b128 v[196:199], v187 offset:53248
	ds_read_b128 v[200:203], v187 offset:54272
	ds_read_b128 v[204:207], v187 offset:55296
	ds_read_b128 v[208:211], v187 offset:56320
	global_load_lds_dwordx4 v[212:213], off
	s_add_i32 m0, s38, 0x2000
	s_add_u32 s36, s36, 0x40080
	v_lshl_add_u64 v[212:213], v[214:215], 0, s[80:81]
	s_addc_u32 s37, s37, 0
	s_add_i32 s38, s60, s33
	global_load_lds_dwordx4 v[212:213], off
	v_lshl_add_u64 v[212:213], s[36:37], 0, v[156:157]
	s_mov_b32 m0, s38
	s_nop 0
	global_load_lds_dwordx4 v[212:213], off
	v_lshl_add_u64 v[212:213], s[36:37], 0, v[160:161]
	s_add_i32 m0, s38, 0x2000
	s_nop 0
	global_load_lds_dwordx4 v[212:213], off
	v_lshl_add_u64 v[212:213], v[216:217], 0, s[80:81]
	s_mov_b32 m0, s51
	s_nop 0
	global_load_lds_dwordx4 v[212:213], off
	v_lshl_add_u64 v[212:213], v[218:219], 0, s[80:81]
	s_mov_b32 m0, s52
	s_nop 0
	global_load_lds_dwordx4 v[212:213], off
	s_waitcnt vmcnt(8)
	s_waitcnt lgkmcnt(0)
	s_barrier
	s_setprio 1
	v_mfma_f32_16x16x32_bf16 v[62:65], v[130:133], v[174:177], v[62:65]
	v_mfma_f32_16x16x32_bf16 v[58:61], v[138:141], v[174:177], v[58:61]
	v_mfma_f32_16x16x32_bf16 v[46:49], v[130:133], v[188:191], v[46:49]
	v_mfma_f32_16x16x32_bf16 v[42:45], v[138:141], v[188:191], v[42:45]
	v_mfma_f32_16x16x32_bf16 v[30:33], v[130:133], v[196:199], v[30:33]
	v_mfma_f32_16x16x32_bf16 v[26:29], v[138:141], v[196:199], v[26:29]
	v_mfma_f32_16x16x32_bf16 v[14:17], v[130:133], v[204:207], v[14:17]
	v_mfma_f32_16x16x32_bf16 v[10:13], v[138:141], v[204:207], v[10:13]
	v_mfma_f32_16x16x32_bf16 v[62:65], v[134:137], v[180:183], v[62:65]
	v_mfma_f32_16x16x32_bf16 v[58:61], v[142:145], v[180:183], v[58:61]
	v_mfma_f32_16x16x32_bf16 v[46:49], v[134:137], v[192:195], v[46:49]
	v_mfma_f32_16x16x32_bf16 v[42:45], v[142:145], v[192:195], v[42:45]
	v_mfma_f32_16x16x32_bf16 v[30:33], v[134:137], v[200:203], v[30:33]
	v_mfma_f32_16x16x32_bf16 v[26:29], v[142:145], v[200:203], v[26:29]
	v_mfma_f32_16x16x32_bf16 v[14:17], v[134:137], v[208:211], v[14:17]
	v_mfma_f32_16x16x32_bf16 v[10:13], v[142:145], v[208:211], v[10:13]
	s_setprio 0
	s_setprio 1
	v_mfma_f32_16x16x32_bf16 v[54:57], v[146:149], v[174:177], v[54:57]
	v_mfma_f32_16x16x32_bf16 v[50:53], v[166:169], v[174:177], v[50:53]
	v_mfma_f32_16x16x32_bf16 v[38:41], v[146:149], v[188:191], v[38:41]
	v_mfma_f32_16x16x32_bf16 v[34:37], v[166:169], v[188:191], v[34:37]
	v_mfma_f32_16x16x32_bf16 v[22:25], v[146:149], v[196:199], v[22:25]
	v_mfma_f32_16x16x32_bf16 v[18:21], v[166:169], v[196:199], v[18:21]
	v_mfma_f32_16x16x32_bf16 v[6:9], v[146:149], v[204:207], v[6:9]
	v_mfma_f32_16x16x32_bf16 v[2:5], v[166:169], v[204:207], v[2:5]
	v_mfma_f32_16x16x32_bf16 v[54:57], v[150:153], v[180:183], v[54:57]
	v_mfma_f32_16x16x32_bf16 v[50:53], v[170:173], v[180:183], v[50:53]
	v_mfma_f32_16x16x32_bf16 v[38:41], v[150:153], v[192:195], v[38:41]
	v_mfma_f32_16x16x32_bf16 v[34:37], v[170:173], v[192:195], v[34:37]
	v_mfma_f32_16x16x32_bf16 v[22:25], v[150:153], v[200:203], v[22:25]
	v_mfma_f32_16x16x32_bf16 v[18:21], v[170:173], v[200:203], v[18:21]
	v_mfma_f32_16x16x32_bf16 v[6:9], v[150:153], v[208:211], v[6:9]
	v_mfma_f32_16x16x32_bf16 v[2:5], v[170:173], v[208:211], v[2:5]
	s_setprio 0
	s_barrier
	s_add_i32 s58, s58, 2
	s_add_u32 s34, s34, 0x100
	s_addc_u32 s35, s35, 0
	s_add_u32 s56, s56, 0x100
	s_addc_u32 s57, s57, 0
	s_cmp_gt_u32 s58, 13
	s_branch .LBB0_1062

; #define PG8_STAGE(bufoff, gbase, voff) do { _Pragma("unroll") for (int _i = 0; _i < 2; ++_i) \
;         __builtin_amdgcn_global_load_lds((const unsigned*)((const char*)(gbase) + (voff)[_i]), (PG8_LAS unsigned*)(lds + (bufoff) + ldsw + _i * 8192), 16, 0, 0); } while (0)
; #define PG8_LDA(dst, b, h) do { _Pragma("unroll") for (int m = 0; m < 4; ++m) _Pragma("unroll") for (int k = 0; k < 2; ++k) dst[m][k] = *(const PG8_LAS bf16x8*)(lds + PG8_SA(b, h) + aoff + m * 2048 + k * 1024); } while (0)
; #define PG8_LDB(dst, b, h) do { _Pragma("unroll") for (int n = 0; n < 2; ++n) _Pragma("unroll") for (int k = 0; k < 2; ++k) dst[n][k] = *(const PG8_LAS bf16x8*)(lds + PG8_SB(b, h) + boff + n * 2048 + k * 1024); } while (0)
; #define PG8_MMA(ai, bj, At, Bt) do { __builtin_amdgcn_s_setprio(1); _Pragma("unroll") for (int m = 0; m < 4; ++m) _Pragma("unroll") for (int n = 0; n < 2; ++n) _Pragma("unroll") for (int k = 0; k < 2; ++k) \
;         acc[ai][bj][m][n] = __builtin_amdgcn_mfma_f32_16x16x32_bf16(Bt[n][k], At[m][k], acc[ai][bj][m][n], 0, 0, 0); __builtin_amdgcn_s_setprio(0); } while (0)
; #define PG8_WAIT_V(n) asm volatile("s_waitcnt vmcnt(" #n ")" ::: "memory")
; template <class Epi, class Sched, bool ALIGN_EPI = false, bool SP2 = false>
; __device__ __forceinline__ void gemm_phase(PG8_LAS unsigned char* lds, const Gemm g, const Sched& S, const Epi& E) {
;     ...
;         const char* nA = has_next ? (const char*)g.A + (size_t)nxt.pm * tstep : cA; const char* nB = has_next ? (const char*)g.Bt + (size_t)nxt.pn * tstep : cB;
;         for (int t = 0; t < nt; t += 2) {
;             const bool last = (t == nt - 2);
;             const char* a1 = cA + (size_t)(t + 1) * kstep;
;             const char* a2 = last ? nA : cA + (size_t)(t + 2) * kstep; const char* b2 = last ? nB : cB + (size_t)(t + 2) * kstep;
;             const char* a3 = a2 + kstep; const char* b3 = b2 + kstep;
;             if (last && has_next) S.a_ready(nxt);
;             if constexpr (SP2) {
;             PG8_LDB(B0, 0, 0); PG8_LDB(B1, 0, 1); PG8_SCHED; PG8_LDA(At, 0, 0); PG8_STAGE(PG8_SA(1, 1), a1 + hstep, voffA);
;             PG8_WAIT_V(8); PG8_WAIT_L(0); PG8_BAR; PG8_MMA(0, 0, At, B0); PG8_MMA(0, 1, At, B1); PG8_BAR; PG8_SCHED;
;             PG8_LDA(At, 0, 1); PG8_STAGE(PG8_SB(0, 0), b2, voffB); PG8_STAGE(PG8_SB(0, 1), b2 + hstep, voffB); PG8_STAGE(PG8_SA(0, 0), a2, voffA);
.LBB0_1105:
	s_ashr_i32 s19, s18, 31
	s_lshl_b64 s[20:21], s[18:19], 19
	s_add_u32 s20, s42, s20
	s_addc_u32 s21, s43, s21
	s_and_b64 s[22:23], s[6:7], exec
	s_cselect_b32 s19, s21, s29
	s_cselect_b32 s25, s20, s28
	s_ashr_i32 s17, s16, 31
	s_lshl_b64 s[22:23], s[16:17], 19
	s_add_u32 s22, s40, s22
	s_addc_u32 s23, s41, s23
	s_and_b64 s[34:35], s[6:7], exec
	s_cselect_b32 s17, s23, s31
	s_cselect_b32 s27, s22, s30
	s_add_u32 s28, s28, 0x40080
	s_addc_u32 s29, s29, 0
	s_add_u32 s52, s30, 0x100
	s_addc_u32 s53, s31, 0
	s_mov_b32 s54, -2
	s_waitcnt lgkmcnt(0)
	s_add_u32 s30, s28, 0xfffc0080
	s_addc_u32 s31, s29, -1
	s_add_i32 s55, 0, 0x10000
	s_cmp_eq_u32 s54, 12
	s_cselect_b32 s35, s19, s31
	s_cselect_b32 s34, s25, s30
	s_cselect_b32 s31, s17, s53
	s_cselect_b32 s30, s27, s52
	s_add_i32 s58, 0, 0x14000
	v_add_u32_e32 v142, s55, v179
	v_add_u32_e32 v158, s58, v179
	ds_read_b128 v[130:133], v142
	ds_read_b128 v[134:137], v142 offset:1024
	ds_read_b128 v[138:141], v142 offset:2048
	ds_read_b128 v[142:145], v142 offset:3072
	ds_read_b128 v[146:149], v158
	ds_read_b128 v[150:153], v158 offset:1024
	ds_read_b128 v[154:157], v158 offset:2048
	ds_read_b128 v[158:161], v158 offset:3072
	v_lshl_add_u64 v[212:213], s[28:29], 0, v[194:195]
	s_add_i32 m0, s36, 0xc000
	ds_read_b128 v[162:165], v211
	ds_read_b128 v[166:169], v211 offset:1024
	ds_read_b128 v[170:173], v211 offset:2048
	ds_read_b128 v[174:177], v211 offset:3072
	ds_read_b128 v[180:183], v211 offset:4096
	ds_read_b128 v[198:201], v211 offset:5120
	ds_read_b128 v[202:205], v211 offset:6144
	ds_read_b128 v[206:209], v211 offset:7168
	global_load_lds_dwordx4 v[212:213], off
	v_lshl_add_u64 v[212:213], s[28:29], 0, v[196:197]
	s_add_i32 m0, s36, 0xe000
	s_nop 0
	global_load_lds_dwordx4 v[212:213], off
	s_waitcnt vmcnt(8)
	s_waitcnt lgkmcnt(0)
	s_barrier
	s_setprio 1
	v_mfma_f32_16x16x32_bf16 v[126:129], v[130:133], v[162:165], 0
	v_mfma_f32_16x16x32_bf16 v[122:125], v[138:141], v[162:165], 0
	v_mfma_f32_16x16x32_bf16 v[110:113], v[130:133], v[170:173], 0
	v_mfma_f32_16x16x32_bf16 v[106:109], v[138:141], v[170:173], 0
	v_mfma_f32_16x16x32_bf16 v[94:97], v[130:133], v[180:183], 0
	v_mfma_f32_16x16x32_bf16 v[90:93], v[138:141], v[180:183], 0
	v_mfma_f32_16x16x32_bf16 v[78:81], v[130:133], v[202:205], 0
	v_mfma_f32_16x16x32_bf16 v[74:77], v[138:141], v[202:205], 0
	v_mfma_f32_16x16x32_bf16 v[126:129], v[134:137], v[166:169], v[126:129]
	v_mfma_f32_16x16x32_bf16 v[122:125], v[142:145], v[166:169], v[122:125]
	v_mfma_f32_16x16x32_bf16 v[110:113], v[134:137], v[174:177], v[110:113]
	v_mfma_f32_16x16x32_bf16 v[106:109], v[142:145], v[174:177], v[106:109]
	v_mfma_f32_16x16x32_bf16 v[94:97], v[134:137], v[198:201], v[94:97]
	v_mfma_f32_16x16x32_bf16 v[90:93], v[142:145], v[198:201], v[90:93]
	v_mfma_f32_16x16x32_bf16 v[78:81], v[134:137], v[206:209], v[78:81]
	v_mfma_f32_16x16x32_bf16 v[74:77], v[142:145], v[206:209], v[74:77]
	s_setprio 0
	s_setprio 1
	v_mfma_f32_16x16x32_bf16 v[118:121], v[146:149], v[162:165], 0
	v_mfma_f32_16x16x32_bf16 v[114:117], v[154:157], v[162:165], 0
	v_mfma_f32_16x16x32_bf16 v[102:105], v[146:149], v[170:173], 0
	v_mfma_f32_16x16x32_bf16 v[98:101], v[154:157], v[170:173], 0
	v_mfma_f32_16x16x32_bf16 v[86:89], v[146:149], v[180:183], 0
	v_mfma_f32_16x16x32_bf16 v[82:85], v[154:157], v[180:183], 0
	v_mfma_f32_16x16x32_bf16 v[70:73], v[146:149], v[202:205], 0
	v_mfma_f32_16x16x32_bf16 v[66:69], v[154:157], v[202:205], 0
	v_mfma_f32_16x16x32_bf16 v[118:121], v[150:153], v[166:169], v[118:121]
	v_mfma_f32_16x16x32_bf16 v[114:117], v[158:161], v[166:169], v[114:117]
	v_mfma_f32_16x16x32_bf16 v[102:105], v[150:153], v[174:177], v[102:105]
	v_mfma_f32_16x16x32_bf16 v[98:101], v[158:161], v[174:177], v[98:101]
	v_mfma_f32_16x16x32_bf16 v[86:89], v[150:153], v[198:201], v[86:89]
	v_mfma_f32_16x16x32_bf16 v[82:85], v[158:161], v[198:201], v[82:85]
	v_mfma_f32_16x16x32_bf16 v[70:73], v[150:153], v[206:209], v[70:73]
	v_mfma_f32_16x16x32_bf16 v[66:69], v[158:161], v[206:209], v[66:69]
	s_setprio 0
	s_barrier
	s_add_i32 s55, s55, s33
	v_lshl_add_u64 v[212:213], s[30:31], 0, v[188:189]
	s_mov_b32 m0, s55
	ds_read_b128 v[162:165], v211 offset:16384
	ds_read_b128 v[166:169], v211 offset:17408
	ds_read_b128 v[170:173], v211 offset:18432
	ds_read_b128 v[174:177], v211 offset:19456
	ds_read_b128 v[180:183], v211 offset:20480
	ds_read_b128 v[198:201], v211 offset:21504
	ds_read_b128 v[202:205], v211 offset:22528
	ds_read_b128 v[206:209], v211 offset:23552
	global_load_lds_dwordx4 v[212:213], off
	s_add_i32 m0, s55, 0x2000
	s_add_u32 s56, s30, 0x40000
	v_lshl_add_u64 v[214:215], s[30:31], 0, v[192:193]
	s_addc_u32 s57, s31, 0
	s_add_i32 s55, s58, s33
	global_load_lds_dwordx4 v[214:215], off
	v_lshl_add_u64 v[216:217], s[56:57], 0, v[188:189]
	s_mov_b32 m0, s55
	v_lshl_add_u64 v[218:219], s[34:35], 0, v[190:191]
	global_load_lds_dwordx4 v[216:217], off
	v_lshl_add_u64 v[216:217], s[56:57], 0, v[192:193]
	s_add_i32 m0, s55, 0x2000
	s_nop 0
	global_load_lds_dwordx4 v[216:217], off
	v_lshl_add_u64 v[216:217], s[34:35], 0, v[186:187]
	s_mov_b32 m0, s36
	s_nop 0
	global_load_lds_dwordx4 v[216:217], off
	s_mov_b32 m0, s37
	s_nop 0
	global_load_lds_dwordx4 v[218:219], off
	s_waitcnt vmcnt(8)
	s_waitcnt lgkmcnt(0)
	s_barrier
; #define PG8_STAGE(bufoff, gbase, voff) do { _Pragma("unroll") for (int _i = 0; _i < 2; ++_i) \
;         __builtin_amdgcn_global_load_lds((const unsigned*)((const char*)(gbase) + (voff)[_i]), (PG8_LAS unsigned*)(lds + (bufoff) + ldsw + _i * 8192), 16, 0, 0); } while (0)
; #define PG8_LDA(dst, b, h) do { _Pragma("unroll") for (int m = 0; m < 4; ++m) _Pragma("unroll") for (int k = 0; k < 2; ++k) dst[m][k] = *(const PG8_LAS bf16x8*)(lds + PG8_SA(b, h) + aoff + m * 2048 + k * 1024); } while (0)
; #define PG8_LDB(dst, b, h) do { _Pragma("unroll") for (int n = 0; n < 2; ++n) _Pragma("unroll") for (int k = 0; k < 2; ++k) dst[n][k] = *(const PG8_LAS bf16x8*)(lds + PG8_SB(b, h) + boff + n * 2048 + k * 1024); } while (0)
; #define PG8_MMA(ai, bj, At, Bt) do { __builtin_amdgcn_s_setprio(1); _Pragma("unroll") for (int m = 0; m < 4; ++m) _Pragma("unroll") for (int n = 0; n < 2; ++n) _Pragma("unroll") for (int k = 0; k < 2; ++k) \
;         acc[ai][bj][m][n] = __builtin_amdgcn_mfma_f32_16x16x32_bf16(Bt[n][k], At[m][k], acc[ai][bj][m][n], 0, 0, 0); __builtin_amdgcn_s_setprio(0); } while (0)
; #define PG8_WAIT_V(n) asm volatile("s_waitcnt vmcnt(" #n ")" ::: "memory")
; #define PG8_WAIT_L(n) asm volatile("s_waitcnt lgkmcnt(" #n ")" ::: "memory")
; #define PG8_BAR __builtin_amdgcn_s_barrier()
; #define PG8_SCHED __builtin_amdgcn_sched_barrier(0)
; template <class Epi, class Sched, bool ALIGN_EPI = false, bool SP2 = false>
; __device__ __forceinline__ void gemm_phase(PG8_LAS unsigned char* lds, const Gemm g, const Sched& S, const Epi& E) {
;     ...
;             PG8_WAIT_V(8); PG8_WAIT_L(0); PG8_BAR; PG8_MMA(1, 0, At, B0); PG8_MMA(1, 1, At, B1); PG8_BAR; PG8_SCHED;
;             PG8_LDB(B0, 1, 0); PG8_LDB(B1, 1, 1); PG8_SCHED; PG8_LDA(At, 1, 0); PG8_STAGE(PG8_SA(0, 1), a2 + hstep, voffA);
;             PG8_WAIT_V(8); PG8_WAIT_L(0); PG8_BAR; PG8_MMA(0, 0, At, B0); PG8_MMA(0, 1, At, B1); PG8_BAR; PG8_SCHED;
	s_setprio 1
	v_mfma_f32_16x16x32_bf16 v[62:65], v[130:133], v[162:165], 0
	v_mfma_f32_16x16x32_bf16 v[58:61], v[138:141], v[162:165], 0
	v_mfma_f32_16x16x32_bf16 v[46:49], v[130:133], v[170:173], 0
	v_mfma_f32_16x16x32_bf16 v[42:45], v[138:141], v[170:173], 0
	v_mfma_f32_16x16x32_bf16 v[30:33], v[130:133], v[180:183], 0
	v_mfma_f32_16x16x32_bf16 v[26:29], v[138:141], v[180:183], 0
	v_mfma_f32_16x16x32_bf16 v[14:17], v[130:133], v[202:205], 0
	v_mfma_f32_16x16x32_bf16 v[10:13], v[138:141], v[202:205], 0
	v_mfma_f32_16x16x32_bf16 v[62:65], v[134:137], v[166:169], v[62:65]
	v_mfma_f32_16x16x32_bf16 v[58:61], v[142:145], v[166:169], v[58:61]
	v_mfma_f32_16x16x32_bf16 v[46:49], v[134:137], v[174:177], v[46:49]
	v_mfma_f32_16x16x32_bf16 v[42:45], v[142:145], v[174:177], v[42:45]
	v_mfma_f32_16x16x32_bf16 v[30:33], v[134:137], v[198:201], v[30:33]
	v_mfma_f32_16x16x32_bf16 v[26:29], v[142:145], v[198:201], v[26:29]
	v_mfma_f32_16x16x32_bf16 v[14:17], v[134:137], v[206:209], v[14:17]
	v_mfma_f32_16x16x32_bf16 v[10:13], v[142:145], v[206:209], v[10:13]
	s_setprio 0
	s_setprio 1
	v_mfma_f32_16x16x32_bf16 v[54:57], v[146:149], v[162:165], 0
	v_mfma_f32_16x16x32_bf16 v[50:53], v[154:157], v[162:165], 0
	v_mfma_f32_16x16x32_bf16 v[38:41], v[146:149], v[170:173], 0
	v_mfma_f32_16x16x32_bf16 v[34:37], v[154:157], v[170:173], 0
	v_mfma_f32_16x16x32_bf16 v[22:25], v[146:149], v[180:183], 0
	v_mfma_f32_16x16x32_bf16 v[18:21], v[154:157], v[180:183], 0
	v_mfma_f32_16x16x32_bf16 v[6:9], v[146:149], v[202:205], 0
	v_mfma_f32_16x16x32_bf16 v[2:5], v[154:157], v[202:205], 0
	v_mfma_f32_16x16x32_bf16 v[54:57], v[150:153], v[166:169], v[54:57]
	v_mfma_f32_16x16x32_bf16 v[50:53], v[158:161], v[166:169], v[50:53]
	v_mfma_f32_16x16x32_bf16 v[38:41], v[150:153], v[174:177], v[38:41]
	v_mfma_f32_16x16x32_bf16 v[34:37], v[158:161], v[174:177], v[34:37]
	v_mfma_f32_16x16x32_bf16 v[22:25], v[150:153], v[198:201], v[22:25]
	v_mfma_f32_16x16x32_bf16 v[18:21], v[158:161], v[198:201], v[18:21]
	v_mfma_f32_16x16x32_bf16 v[6:9], v[150:153], v[206:209], v[6:9]
	v_mfma_f32_16x16x32_bf16 v[2:5], v[158:161], v[206:209], v[2:5]
	s_setprio 0
	s_barrier
	s_add_i32 s55, 0, 0x18000
	s_add_i32 s56, 0, 0x1c000
	v_add_u32_e32 v142, s55, v179
	v_add_u32_e32 v158, s56, v179
	ds_read_b128 v[130:133], v142
	ds_read_b128 v[134:137], v142 offset:1024
	ds_read_b128 v[138:141], v142 offset:2048
	ds_read_b128 v[142:145], v142 offset:3072
	ds_read_b128 v[146:149], v158
	ds_read_b128 v[150:153], v158 offset:1024
	ds_read_b128 v[154:157], v158 offset:2048
	ds_read_b128 v[158:161], v158 offset:3072
	s_add_u32 s34, s34, 0x40000
	s_addc_u32 s35, s35, 0
	s_mov_b32 m0, s38
	v_lshl_add_u64 v[220:221], s[34:35], 0, v[186:187]
	ds_read_b128 v[162:165], v211 offset:32768
	ds_read_b128 v[166:169], v211 offset:33792
	ds_read_b128 v[170:173], v211 offset:34816
	ds_read_b128 v[174:177], v211 offset:35840
	ds_read_b128 v[180:183], v211 offset:36864
	ds_read_b128 v[198:201], v211 offset:37888
	ds_read_b128 v[202:205], v211 offset:38912
	ds_read_b128 v[206:209], v211 offset:39936
	global_load_lds_dwordx4 v[220:221], off
	v_lshl_add_u64 v[220:221], s[34:35], 0, v[190:191]
	s_mov_b32 m0, s39
	s_nop 0
	global_load_lds_dwordx4 v[220:221], off
	s_waitcnt vmcnt(8)
	s_waitcnt lgkmcnt(0)
	s_barrier
	s_setprio 1
	v_mfma_f32_16x16x32_bf16 v[126:129], v[130:133], v[162:165], v[126:129]
	v_mfma_f32_16x16x32_bf16 v[122:125], v[138:141], v[162:165], v[122:125]
	v_mfma_f32_16x16x32_bf16 v[110:113], v[130:133], v[170:173], v[110:113]
	v_mfma_f32_16x16x32_bf16 v[106:109], v[138:141], v[170:173], v[106:109]
	v_mfma_f32_16x16x32_bf16 v[94:97], v[130:133], v[180:183], v[94:97]
	v_mfma_f32_16x16x32_bf16 v[90:93], v[138:141], v[180:183], v[90:93]
	v_mfma_f32_16x16x32_bf16 v[78:81], v[130:133], v[202:205], v[78:81]
	v_mfma_f32_16x16x32_bf16 v[74:77], v[138:141], v[202:205], v[74:77]
	v_mfma_f32_16x16x32_bf16 v[126:129], v[134:137], v[166:169], v[126:129]
	v_mfma_f32_16x16x32_bf16 v[122:125], v[142:145], v[166:169], v[122:125]
	v_mfma_f32_16x16x32_bf16 v[110:113], v[134:137], v[174:177], v[110:113]
	v_mfma_f32_16x16x32_bf16 v[106:109], v[142:145], v[174:177], v[106:109]
	v_mfma_f32_16x16x32_bf16 v[94:97], v[134:137], v[198:201], v[94:97]
	v_mfma_f32_16x16x32_bf16 v[90:93], v[142:145], v[198:201], v[90:93]
	v_mfma_f32_16x16x32_bf16 v[78:81], v[134:137], v[206:209], v[78:81]
	v_mfma_f32_16x16x32_bf16 v[74:77], v[142:145], v[206:209], v[74:77]
	s_setprio 0
	s_setprio 1
	v_mfma_f32_16x16x32_bf16 v[118:121], v[146:149], v[162:165], v[118:121]
	v_mfma_f32_16x16x32_bf16 v[114:117], v[154:157], v[162:165], v[114:117]
	v_mfma_f32_16x16x32_bf16 v[102:105], v[146:149], v[170:173], v[102:105]
	v_mfma_f32_16x16x32_bf16 v[98:101], v[154:157], v[170:173], v[98:101]
	v_mfma_f32_16x16x32_bf16 v[86:89], v[146:149], v[180:183], v[86:89]
	v_mfma_f32_16x16x32_bf16 v[82:85], v[154:157], v[180:183], v[82:85]
	v_mfma_f32_16x16x32_bf16 v[70:73], v[146:149], v[202:205], v[70:73]
	v_mfma_f32_16x16x32_bf16 v[66:69], v[154:157], v[202:205], v[66:69]
	v_mfma_f32_16x16x32_bf16 v[118:121], v[150:153], v[166:169], v[118:121]
	v_mfma_f32_16x16x32_bf16 v[114:117], v[158:161], v[166:169], v[114:117]
	v_mfma_f32_16x16x32_bf16 v[102:105], v[150:153], v[174:177], v[102:105]
	v_mfma_f32_16x16x32_bf16 v[98:101], v[158:161], v[174:177], v[98:101]
	v_mfma_f32_16x16x32_bf16 v[86:89], v[150:153], v[198:201], v[86:89]
	v_mfma_f32_16x16x32_bf16 v[82:85], v[158:161], v[198:201], v[82:85]
	v_mfma_f32_16x16x32_bf16 v[70:73], v[150:153], v[206:209], v[70:73]
	v_mfma_f32_16x16x32_bf16 v[66:69], v[158:161], v[206:209], v[66:69]
	s_setprio 0
	s_barrier
; #define PG8_STAGE(bufoff, gbase, voff) do { _Pragma("unroll") for (int _i = 0; _i < 2; ++_i) \
;         __builtin_amdgcn_global_load_lds((const unsigned*)((const char*)(gbase) + (voff)[_i]), (PG8_LAS unsigned*)(lds + (bufoff) + ldsw + _i * 8192), 16, 0, 0); } while (0)
; #define PG8_LDA(dst, b, h) do { _Pragma("unroll") for (int m = 0; m < 4; ++m) _Pragma("unroll") for (int k = 0; k < 2; ++k) dst[m][k] = *(const PG8_LAS bf16x8*)(lds + PG8_SA(b, h) + aoff + m * 2048 + k * 1024); } while (0)
; #define PG8_MMA(ai, bj, At, Bt) do { __builtin_amdgcn_s_setprio(1); _Pragma("unroll") for (int m = 0; m < 4; ++m) _Pragma("unroll") for (int n = 0; n < 2; ++n) _Pragma("unroll") for (int k = 0; k < 2; ++k) \
;         acc[ai][bj][m][n] = __builtin_amdgcn_mfma_f32_16x16x32_bf16(Bt[n][k], At[m][k], acc[ai][bj][m][n], 0, 0, 0); __builtin_amdgcn_s_setprio(0); } while (0)
; #define PG8_WAIT_V(n) asm volatile("s_waitcnt vmcnt(" #n ")" ::: "memory")
; #define PG8_WAIT_L(n) asm volatile("s_waitcnt lgkmcnt(" #n ")" ::: "memory")
; #define PG8_BAR __builtin_amdgcn_s_barrier()
; #define PG8_SCHED __builtin_amdgcn_sched_barrier(0)
; template <class Epi, class Sched, bool ALIGN_EPI = false, bool SP2 = false>
; __device__ __forceinline__ void gemm_phase(PG8_LAS unsigned char* lds, const Gemm g, const Sched& S, const Epi& E) {
;     ...
;             PG8_LDA(At, 1, 1); PG8_STAGE(PG8_SB(1, 0), b3, voffB); PG8_STAGE(PG8_SB(1, 1), b3 + hstep, voffB); PG8_STAGE(PG8_SA(1, 0), a3, voffA);
;             PG8_WAIT_V(8); PG8_WAIT_L(0); PG8_BAR; PG8_MMA(1, 0, At, B0); PG8_MMA(1, 1, At, B1); PG8_BAR; PG8_SCHED;
	s_add_i32 s34, s55, s33
	v_lshl_add_u64 v[212:213], v[212:213], 0, s[80:81]
	s_mov_b32 m0, s34
	ds_read_b128 v[162:165], v211 offset:49152
	ds_read_b128 v[166:169], v211 offset:50176
	ds_read_b128 v[170:173], v211 offset:51200
	ds_read_b128 v[174:177], v211 offset:52224
	ds_read_b128 v[180:183], v211 offset:53248
	ds_read_b128 v[198:201], v211 offset:54272
	ds_read_b128 v[202:205], v211 offset:55296
	ds_read_b128 v[206:209], v211 offset:56320
	global_load_lds_dwordx4 v[212:213], off
	s_add_i32 m0, s34, 0x2000
	s_add_u32 s30, s30, 0x40080
	v_lshl_add_u64 v[212:213], v[214:215], 0, s[80:81]
	s_addc_u32 s31, s31, 0
	s_add_i32 s34, s56, s33
	global_load_lds_dwordx4 v[212:213], off
	v_lshl_add_u64 v[212:213], s[30:31], 0, v[188:189]
	s_mov_b32 m0, s34
	s_nop 0
	global_load_lds_dwordx4 v[212:213], off
	v_lshl_add_u64 v[212:213], s[30:31], 0, v[192:193]
	s_add_i32 m0, s34, 0x2000
	s_nop 0
	global_load_lds_dwordx4 v[212:213], off
	v_lshl_add_u64 v[212:213], v[216:217], 0, s[80:81]
	s_mov_b32 m0, s47
	s_nop 0
	global_load_lds_dwordx4 v[212:213], off
	v_lshl_add_u64 v[212:213], v[218:219], 0, s[80:81]
	s_mov_b32 m0, s48
	s_nop 0
	global_load_lds_dwordx4 v[212:213], off
	s_waitcnt vmcnt(8)
	s_waitcnt lgkmcnt(0)
	s_barrier
	s_setprio 1
	v_mfma_f32_16x16x32_bf16 v[62:65], v[130:133], v[162:165], v[62:65]
	v_mfma_f32_16x16x32_bf16 v[58:61], v[138:141], v[162:165], v[58:61]
	v_mfma_f32_16x16x32_bf16 v[46:49], v[130:133], v[170:173], v[46:49]
	v_mfma_f32_16x16x32_bf16 v[42:45], v[138:141], v[170:173], v[42:45]
	v_mfma_f32_16x16x32_bf16 v[30:33], v[130:133], v[180:183], v[30:33]
	v_mfma_f32_16x16x32_bf16 v[26:29], v[138:141], v[180:183], v[26:29]
	v_mfma_f32_16x16x32_bf16 v[14:17], v[130:133], v[202:205], v[14:17]
	v_mfma_f32_16x16x32_bf16 v[10:13], v[138:141], v[202:205], v[10:13]
	v_mfma_f32_16x16x32_bf16 v[62:65], v[134:137], v[166:169], v[62:65]
	v_mfma_f32_16x16x32_bf16 v[58:61], v[142:145], v[166:169], v[58:61]
	v_mfma_f32_16x16x32_bf16 v[46:49], v[134:137], v[174:177], v[46:49]
	v_mfma_f32_16x16x32_bf16 v[42:45], v[142:145], v[174:177], v[42:45]
	v_mfma_f32_16x16x32_bf16 v[30:33], v[134:137], v[198:201], v[30:33]
	v_mfma_f32_16x16x32_bf16 v[26:29], v[142:145], v[198:201], v[26:29]
	v_mfma_f32_16x16x32_bf16 v[14:17], v[134:137], v[206:209], v[14:17]
	v_mfma_f32_16x16x32_bf16 v[10:13], v[142:145], v[206:209], v[10:13]
	s_setprio 0
	s_setprio 1
	v_mfma_f32_16x16x32_bf16 v[54:57], v[146:149], v[162:165], v[54:57]
	v_mfma_f32_16x16x32_bf16 v[50:53], v[154:157], v[162:165], v[50:53]
	v_mfma_f32_16x16x32_bf16 v[38:41], v[146:149], v[170:173], v[38:41]
	v_mfma_f32_16x16x32_bf16 v[34:37], v[154:157], v[170:173], v[34:37]
	v_mfma_f32_16x16x32_bf16 v[22:25], v[146:149], v[180:183], v[22:25]
	v_mfma_f32_16x16x32_bf16 v[18:21], v[154:157], v[180:183], v[18:21]
	v_mfma_f32_16x16x32_bf16 v[6:9], v[146:149], v[202:205], v[6:9]
	v_mfma_f32_16x16x32_bf16 v[2:5], v[154:157], v[202:205], v[2:5]
	v_mfma_f32_16x16x32_bf16 v[54:57], v[150:153], v[166:169], v[54:57]
	v_mfma_f32_16x16x32_bf16 v[50:53], v[158:161], v[166:169], v[50:53]
	v_mfma_f32_16x16x32_bf16 v[38:41], v[150:153], v[174:177], v[38:41]
	v_mfma_f32_16x16x32_bf16 v[34:37], v[158:161], v[174:177], v[34:37]
	v_mfma_f32_16x16x32_bf16 v[22:25], v[150:153], v[198:201], v[22:25]
	v_mfma_f32_16x16x32_bf16 v[18:21], v[158:161], v[198:201], v[18:21]
	v_mfma_f32_16x16x32_bf16 v[6:9], v[150:153], v[206:209], v[6:9]
	v_mfma_f32_16x16x32_bf16 v[2:5], v[158:161], v[206:209], v[2:5]
	s_setprio 0
	s_barrier
	s_add_i32 s54, s54, 2
	s_add_u32 s28, s28, 0x100
	s_addc_u32 s29, s29, 0
	s_add_u32 s52, s52, 0x100
	s_addc_u32 s53, s53, 0
	s_cmp_gt_u32 s54, 13
	s_branch .LBB0_1106

; #define PG8_STAGE(bufoff, gbase, voff) do { _Pragma("unroll") for (int _i = 0; _i < 2; ++_i) \
;         __builtin_amdgcn_global_load_lds((const unsigned*)((const char*)(gbase) + (voff)[_i]), (PG8_LAS unsigned*)(lds + (bufoff) + ldsw + _i * 8192), 16, 0, 0); } while (0)
; #define PG8_LDA(dst, b, h) do { _Pragma("unroll") for (int m = 0; m < 4; ++m) _Pragma("unroll") for (int k = 0; k < 2; ++k) dst[m][k] = *(const PG8_LAS bf16x8*)(lds + PG8_SA(b, h) + aoff + m * 2048 + k * 1024); } while (0)
; #define PG8_LDB(dst, b, h) do { _Pragma("unroll") for (int n = 0; n < 2; ++n) _Pragma("unroll") for (int k = 0; k < 2; ++k) dst[n][k] = *(const PG8_LAS bf16x8*)(lds + PG8_SB(b, h) + boff + n * 2048 + k * 1024); } while (0)
; #define PG8_MMA(ai, bj, At, Bt) do { __builtin_amdgcn_s_setprio(1); _Pragma("unroll") for (int m = 0; m < 4; ++m) _Pragma("unroll") for (int n = 0; n < 2; ++n) _Pragma("unroll") for (int k = 0; k < 2; ++k) \
;         acc[ai][bj][m][n] = __builtin_amdgcn_mfma_f32_16x16x32_bf16(Bt[n][k], At[m][k], acc[ai][bj][m][n], 0, 0, 0); __builtin_amdgcn_s_setprio(0); } while (0)
; #define PG8_WAIT_V(n) asm volatile("s_waitcnt vmcnt(" #n ")" ::: "memory")
; template <class Epi, class Sched, bool ALIGN_EPI = false, bool SP2 = false>
; __device__ __forceinline__ void gemm_phase(PG8_LAS unsigned char* lds, const Gemm g, const Sched& S, const Epi& E) {
;     ...
;         const char* nA = has_next ? (const char*)g.A + (size_t)nxt.pm * tstep : cA; const char* nB = has_next ? (const char*)g.Bt + (size_t)nxt.pn * tstep : cB;
;         for (int t = 0; t < nt; t += 2) {
;             const bool last = (t == nt - 2);
;             const char* a1 = cA + (size_t)(t + 1) * kstep;
;             const char* a2 = last ? nA : cA + (size_t)(t + 2) * kstep; const char* b2 = last ? nB : cB + (size_t)(t + 2) * kstep;
;             const char* a3 = a2 + kstep; const char* b3 = b2 + kstep;
;             if (last && has_next) S.a_ready(nxt);
;             if constexpr (SP2) {
;             PG8_LDB(B0, 0, 0); PG8_LDB(B1, 0, 1); PG8_SCHED; PG8_LDA(At, 0, 0); PG8_STAGE(PG8_SA(1, 1), a1 + hstep, voffA);
;             PG8_WAIT_V(8); PG8_WAIT_L(0); PG8_BAR; PG8_MMA(0, 0, At, B0); PG8_MMA(0, 1, At, B1); PG8_BAR; PG8_SCHED;
;             PG8_LDA(At, 0, 1); PG8_STAGE(PG8_SB(0, 0), b2, voffB); PG8_STAGE(PG8_SB(0, 1), b2 + hstep, voffB); PG8_STAGE(PG8_SA(0, 0), a2, voffA);
.LBB0_1248:
	s_ashr_i32 s17, s16, 31
	s_lshl_b64 s[18:19], s[16:17], 19
	s_add_u32 s18, s0, s18
	s_addc_u32 s19, s1, s19
	s_and_b64 s[20:21], s[4:5], exec
	s_cselect_b32 s17, s19, s25
	s_cselect_b32 s45, s18, s24
	s_ashr_i32 s15, s14, 31
	s_lshl_b64 s[20:21], s[14:15], 19
	s_add_u32 s20, s34, s20
	s_addc_u32 s21, s35, s21
	s_and_b64 s[28:29], s[4:5], exec
	s_cselect_b32 s15, s21, s27
	s_cselect_b32 s46, s20, s26
	s_add_u32 s24, s24, 0x40080
	s_addc_u32 s25, s25, 0
	s_add_u32 s47, s26, 0x100
	s_addc_u32 s48, s27, 0
	s_mov_b32 s49, -2
	s_add_u32 s26, s24, 0xfffc0080
	s_addc_u32 s27, s25, -1
	s_add_i32 s50, 0, 0x10000
	s_cmp_eq_u32 s49, 12
	s_cselect_b32 s29, s17, s27
	s_cselect_b32 s28, s45, s26
	v_add_u32_e32 v156, s50, v158
	s_cselect_b32 s27, s15, s48
	s_cselect_b32 s26, s46, s47
	s_add_i32 s52, 0, 0x14000
	ds_read_b128 v[66:69], v156
	ds_read_b128 v[118:121], v156 offset:1024
	ds_read_b128 v[152:155], v156 offset:2048
	ds_read_b128 v[162:165], v156 offset:3072
	v_add_u32_e32 v156, s52, v158
	ds_read_b128 v[166:169], v156
	ds_read_b128 v[170:173], v156 offset:1024
	ds_read_b128 v[174:177], v156 offset:2048
	ds_read_b128 v[180:183], v156 offset:3072
	v_lshl_add_u64 v[156:157], s[24:25], 0, v[148:149]
	s_add_i32 m0, s33, 0xc000
	ds_read_b128 v[186:189], v160
	ds_read_b128 v[190:193], v160 offset:1024
	ds_read_b128 v[194:197], v160 offset:2048
	ds_read_b128 v[198:201], v160 offset:3072
	ds_read_b128 v[202:205], v160 offset:4096
	ds_read_b128 v[206:209], v160 offset:5120
	ds_read_b128 v[210:213], v160 offset:6144
	ds_read_b128 v[214:217], v160 offset:7168
	global_load_lds_dwordx4 v[156:157], off
	v_lshl_add_u64 v[156:157], s[24:25], 0, v[150:151]
	s_add_i32 m0, s33, 0xe000
	s_nop 0
	global_load_lds_dwordx4 v[156:157], off
	s_waitcnt vmcnt(8)
	s_waitcnt lgkmcnt(0)
	s_barrier
	s_setprio 1
	v_mfma_f32_16x16x32_bf16 v[134:137], v[66:69], v[186:189], 0
	v_mfma_f32_16x16x32_bf16 v[126:129], v[152:155], v[186:189], 0
	v_mfma_f32_16x16x32_bf16 v[114:117], v[66:69], v[194:197], 0
	v_mfma_f32_16x16x32_bf16 v[110:113], v[152:155], v[194:197], 0
	v_mfma_f32_16x16x32_bf16 v[98:101], v[66:69], v[202:205], 0
	v_mfma_f32_16x16x32_bf16 v[94:97], v[152:155], v[202:205], 0
	v_mfma_f32_16x16x32_bf16 v[82:85], v[66:69], v[210:213], 0
	v_mfma_f32_16x16x32_bf16 v[78:81], v[152:155], v[210:213], 0
	v_mfma_f32_16x16x32_bf16 v[134:137], v[118:121], v[190:193], v[134:137]
	v_mfma_f32_16x16x32_bf16 v[126:129], v[162:165], v[190:193], v[126:129]
	v_mfma_f32_16x16x32_bf16 v[114:117], v[118:121], v[198:201], v[114:117]
	v_mfma_f32_16x16x32_bf16 v[110:113], v[162:165], v[198:201], v[110:113]
	v_mfma_f32_16x16x32_bf16 v[98:101], v[118:121], v[206:209], v[98:101]
	v_mfma_f32_16x16x32_bf16 v[94:97], v[162:165], v[206:209], v[94:97]
	v_mfma_f32_16x16x32_bf16 v[82:85], v[118:121], v[214:217], v[82:85]
	v_mfma_f32_16x16x32_bf16 v[78:81], v[162:165], v[214:217], v[78:81]
	s_setprio 0
	s_setprio 1
	v_mfma_f32_16x16x32_bf16 v[130:133], v[166:169], v[186:189], 0
	v_mfma_f32_16x16x32_bf16 v[122:125], v[174:177], v[186:189], 0
	v_mfma_f32_16x16x32_bf16 v[106:109], v[166:169], v[194:197], 0
	v_mfma_f32_16x16x32_bf16 v[102:105], v[174:177], v[194:197], 0
	v_mfma_f32_16x16x32_bf16 v[90:93], v[166:169], v[202:205], 0
	v_mfma_f32_16x16x32_bf16 v[86:89], v[174:177], v[202:205], 0
	v_mfma_f32_16x16x32_bf16 v[74:77], v[166:169], v[210:213], 0
	v_mfma_f32_16x16x32_bf16 v[70:73], v[174:177], v[210:213], 0
	v_mfma_f32_16x16x32_bf16 v[130:133], v[170:173], v[190:193], v[130:133]
	v_mfma_f32_16x16x32_bf16 v[122:125], v[180:183], v[190:193], v[122:125]
	v_mfma_f32_16x16x32_bf16 v[106:109], v[170:173], v[198:201], v[106:109]
	v_mfma_f32_16x16x32_bf16 v[102:105], v[180:183], v[198:201], v[102:105]
	v_mfma_f32_16x16x32_bf16 v[90:93], v[170:173], v[206:209], v[90:93]
	v_mfma_f32_16x16x32_bf16 v[86:89], v[180:183], v[206:209], v[86:89]
	v_mfma_f32_16x16x32_bf16 v[74:77], v[170:173], v[214:217], v[74:77]
	v_mfma_f32_16x16x32_bf16 v[70:73], v[180:183], v[214:217], v[70:73]
	s_setprio 0
	s_barrier
	s_add_i32 s50, s50, s36
	v_lshl_add_u64 v[156:157], s[26:27], 0, v[142:143]
	s_mov_b32 m0, s50
	ds_read_b128 v[186:189], v160 offset:16384
	ds_read_b128 v[190:193], v160 offset:17408
	ds_read_b128 v[194:197], v160 offset:18432
	ds_read_b128 v[198:201], v160 offset:19456
	ds_read_b128 v[202:205], v160 offset:20480
	ds_read_b128 v[206:209], v160 offset:21504
	ds_read_b128 v[210:213], v160 offset:22528
	ds_read_b128 v[214:217], v160 offset:23552
	global_load_lds_dwordx4 v[156:157], off
	s_add_i32 m0, s50, 0x2000
	s_add_u32 s50, s26, 0x40000
	v_lshl_add_u64 v[218:219], s[26:27], 0, v[138:139]
	s_addc_u32 s51, s27, 0
	s_add_i32 s52, s52, s36
	global_load_lds_dwordx4 v[218:219], off
	v_lshl_add_u64 v[220:221], s[50:51], 0, v[142:143]
	s_mov_b32 m0, s52
	v_lshl_add_u64 v[222:223], s[28:29], 0, v[140:141]
	global_load_lds_dwordx4 v[220:221], off
	v_lshl_add_u64 v[220:221], s[50:51], 0, v[138:139]
	s_add_i32 m0, s52, 0x2000
	s_nop 0
	global_load_lds_dwordx4 v[220:221], off
	v_lshl_add_u64 v[220:221], s[28:29], 0, v[144:145]
	s_mov_b32 m0, s33
	s_nop 0
	global_load_lds_dwordx4 v[220:221], off
	s_mov_b32 m0, s38
	s_nop 0
	global_load_lds_dwordx4 v[222:223], off
	s_waitcnt vmcnt(8)
	s_waitcnt lgkmcnt(0)
	s_barrier
; #define PG8_STAGE(bufoff, gbase, voff) do { _Pragma("unroll") for (int _i = 0; _i < 2; ++_i) \
;         __builtin_amdgcn_global_load_lds((const unsigned*)((const char*)(gbase) + (voff)[_i]), (PG8_LAS unsigned*)(lds + (bufoff) + ldsw + _i * 8192), 16, 0, 0); } while (0)
; #define PG8_LDA(dst, b, h) do { _Pragma("unroll") for (int m = 0; m < 4; ++m) _Pragma("unroll") for (int k = 0; k < 2; ++k) dst[m][k] = *(const PG8_LAS bf16x8*)(lds + PG8_SA(b, h) + aoff + m * 2048 + k * 1024); } while (0)
; #define PG8_LDB(dst, b, h) do { _Pragma("unroll") for (int n = 0; n < 2; ++n) _Pragma("unroll") for (int k = 0; k < 2; ++k) dst[n][k] = *(const PG8_LAS bf16x8*)(lds + PG8_SB(b, h) + boff + n * 2048 + k * 1024); } while (0)
; #define PG8_MMA(ai, bj, At, Bt) do { __builtin_amdgcn_s_setprio(1); _Pragma("unroll") for (int m = 0; m < 4; ++m) _Pragma("unroll") for (int n = 0; n < 2; ++n) _Pragma("unroll") for (int k = 0; k < 2; ++k) \
;         acc[ai][bj][m][n] = __builtin_amdgcn_mfma_f32_16x16x32_bf16(Bt[n][k], At[m][k], acc[ai][bj][m][n], 0, 0, 0); __builtin_amdgcn_s_setprio(0); } while (0)
; #define PG8_WAIT_V(n) asm volatile("s_waitcnt vmcnt(" #n ")" ::: "memory")
; #define PG8_WAIT_L(n) asm volatile("s_waitcnt lgkmcnt(" #n ")" ::: "memory")
; #define PG8_BAR __builtin_amdgcn_s_barrier()
; #define PG8_SCHED __builtin_amdgcn_sched_barrier(0)
; template <class Epi, class Sched, bool ALIGN_EPI = false, bool SP2 = false>
; __device__ __forceinline__ void gemm_phase(PG8_LAS unsigned char* lds, const Gemm g, const Sched& S, const Epi& E) {
;     ...
;             PG8_WAIT_V(8); PG8_WAIT_L(0); PG8_BAR; PG8_MMA(1, 0, At, B0); PG8_MMA(1, 1, At, B1); PG8_BAR; PG8_SCHED;
;             PG8_LDB(B0, 1, 0); PG8_LDB(B1, 1, 1); PG8_SCHED; PG8_LDA(At, 1, 0); PG8_STAGE(PG8_SA(0, 1), a2 + hstep, voffA);
;             PG8_WAIT_V(8); PG8_WAIT_L(0); PG8_BAR; PG8_MMA(0, 0, At, B0); PG8_MMA(0, 1, At, B1); PG8_BAR; PG8_SCHED;
	s_setprio 1
	v_mfma_f32_16x16x32_bf16 v[62:65], v[66:69], v[186:189], 0
	v_mfma_f32_16x16x32_bf16 v[58:61], v[152:155], v[186:189], 0
	v_mfma_f32_16x16x32_bf16 v[46:49], v[66:69], v[194:197], 0
	v_mfma_f32_16x16x32_bf16 v[42:45], v[152:155], v[194:197], 0
	v_mfma_f32_16x16x32_bf16 v[30:33], v[66:69], v[202:205], 0
	v_mfma_f32_16x16x32_bf16 v[26:29], v[152:155], v[202:205], 0
	v_mfma_f32_16x16x32_bf16 v[14:17], v[66:69], v[210:213], 0
	v_mfma_f32_16x16x32_bf16 v[10:13], v[152:155], v[210:213], 0
	v_mfma_f32_16x16x32_bf16 v[62:65], v[118:121], v[190:193], v[62:65]
	v_mfma_f32_16x16x32_bf16 v[58:61], v[162:165], v[190:193], v[58:61]
	v_mfma_f32_16x16x32_bf16 v[46:49], v[118:121], v[198:201], v[46:49]
	v_mfma_f32_16x16x32_bf16 v[42:45], v[162:165], v[198:201], v[42:45]
	v_mfma_f32_16x16x32_bf16 v[30:33], v[118:121], v[206:209], v[30:33]
	v_mfma_f32_16x16x32_bf16 v[26:29], v[162:165], v[206:209], v[26:29]
	v_mfma_f32_16x16x32_bf16 v[14:17], v[118:121], v[214:217], v[14:17]
	v_mfma_f32_16x16x32_bf16 v[10:13], v[162:165], v[214:217], v[10:13]
	s_setprio 0
	s_setprio 1
	v_mfma_f32_16x16x32_bf16 v[54:57], v[166:169], v[186:189], 0
	v_mfma_f32_16x16x32_bf16 v[50:53], v[174:177], v[186:189], 0
	v_mfma_f32_16x16x32_bf16 v[38:41], v[166:169], v[194:197], 0
	v_mfma_f32_16x16x32_bf16 v[34:37], v[174:177], v[194:197], 0
	v_mfma_f32_16x16x32_bf16 v[22:25], v[166:169], v[202:205], 0
	v_mfma_f32_16x16x32_bf16 v[18:21], v[174:177], v[202:205], 0
	v_mfma_f32_16x16x32_bf16 v[6:9], v[166:169], v[210:213], 0
	v_mfma_f32_16x16x32_bf16 v[2:5], v[174:177], v[210:213], 0
	v_mfma_f32_16x16x32_bf16 v[54:57], v[170:173], v[190:193], v[54:57]
	v_mfma_f32_16x16x32_bf16 v[50:53], v[180:183], v[190:193], v[50:53]
	v_mfma_f32_16x16x32_bf16 v[38:41], v[170:173], v[198:201], v[38:41]
	v_mfma_f32_16x16x32_bf16 v[34:37], v[180:183], v[198:201], v[34:37]
	v_mfma_f32_16x16x32_bf16 v[22:25], v[170:173], v[206:209], v[22:25]
	v_mfma_f32_16x16x32_bf16 v[18:21], v[180:183], v[206:209], v[18:21]
	v_mfma_f32_16x16x32_bf16 v[6:9], v[170:173], v[214:217], v[6:9]
	v_mfma_f32_16x16x32_bf16 v[2:5], v[180:183], v[214:217], v[2:5]
	s_setprio 0
	s_barrier
	s_add_i32 s50, 0, 0x18000
	v_add_u32_e32 v161, s50, v158
	s_add_i32 s51, 0, 0x1c000
	ds_read_b128 v[66:69], v161
	ds_read_b128 v[118:121], v161 offset:1024
	ds_read_b128 v[152:155], v161 offset:2048
	ds_read_b128 v[162:165], v161 offset:3072
	v_add_u32_e32 v161, s51, v158
	ds_read_b128 v[166:169], v161
	ds_read_b128 v[170:173], v161 offset:1024
	ds_read_b128 v[174:177], v161 offset:2048
	ds_read_b128 v[180:183], v161 offset:3072
	s_add_u32 s28, s28, 0x40000
	s_addc_u32 s29, s29, 0
	s_mov_b32 m0, s39
	v_lshl_add_u64 v[240:241], s[28:29], 0, v[144:145]
	ds_read_b128 v[186:189], v160 offset:32768
	ds_read_b128 v[190:193], v160 offset:33792
	ds_read_b128 v[194:197], v160 offset:34816
	ds_read_b128 v[198:201], v160 offset:35840
	ds_read_b128 v[202:205], v160 offset:36864
	ds_read_b128 v[206:209], v160 offset:37888
	ds_read_b128 v[210:213], v160 offset:38912
	ds_read_b128 v[214:217], v160 offset:39936
	global_load_lds_dwordx4 v[240:241], off
	v_lshl_add_u64 v[240:241], s[28:29], 0, v[140:141]
	s_mov_b32 m0, s40
	s_nop 0
	global_load_lds_dwordx4 v[240:241], off
	s_waitcnt vmcnt(8)
	s_waitcnt lgkmcnt(0)
	s_barrier
	s_setprio 1
	v_mfma_f32_16x16x32_bf16 v[134:137], v[66:69], v[186:189], v[134:137]
	v_mfma_f32_16x16x32_bf16 v[126:129], v[152:155], v[186:189], v[126:129]
	v_mfma_f32_16x16x32_bf16 v[114:117], v[66:69], v[194:197], v[114:117]
	v_mfma_f32_16x16x32_bf16 v[110:113], v[152:155], v[194:197], v[110:113]
	v_mfma_f32_16x16x32_bf16 v[98:101], v[66:69], v[202:205], v[98:101]
	v_mfma_f32_16x16x32_bf16 v[94:97], v[152:155], v[202:205], v[94:97]
	v_mfma_f32_16x16x32_bf16 v[82:85], v[66:69], v[210:213], v[82:85]
	v_mfma_f32_16x16x32_bf16 v[78:81], v[152:155], v[210:213], v[78:81]
	v_mfma_f32_16x16x32_bf16 v[134:137], v[118:121], v[190:193], v[134:137]
	v_mfma_f32_16x16x32_bf16 v[126:129], v[162:165], v[190:193], v[126:129]
	v_mfma_f32_16x16x32_bf16 v[114:117], v[118:121], v[198:201], v[114:117]
	v_mfma_f32_16x16x32_bf16 v[110:113], v[162:165], v[198:201], v[110:113]
	v_mfma_f32_16x16x32_bf16 v[98:101], v[118:121], v[206:209], v[98:101]
	v_mfma_f32_16x16x32_bf16 v[94:97], v[162:165], v[206:209], v[94:97]
	v_mfma_f32_16x16x32_bf16 v[82:85], v[118:121], v[214:217], v[82:85]
	v_mfma_f32_16x16x32_bf16 v[78:81], v[162:165], v[214:217], v[78:81]
	s_setprio 0
	s_setprio 1
	v_mfma_f32_16x16x32_bf16 v[130:133], v[166:169], v[186:189], v[130:133]
	v_mfma_f32_16x16x32_bf16 v[122:125], v[174:177], v[186:189], v[122:125]
	v_mfma_f32_16x16x32_bf16 v[106:109], v[166:169], v[194:197], v[106:109]
	v_mfma_f32_16x16x32_bf16 v[102:105], v[174:177], v[194:197], v[102:105]
	v_mfma_f32_16x16x32_bf16 v[90:93], v[166:169], v[202:205], v[90:93]
	v_mfma_f32_16x16x32_bf16 v[86:89], v[174:177], v[202:205], v[86:89]
	v_mfma_f32_16x16x32_bf16 v[74:77], v[166:169], v[210:213], v[74:77]
	v_mfma_f32_16x16x32_bf16 v[70:73], v[174:177], v[210:213], v[70:73]
	v_mfma_f32_16x16x32_bf16 v[130:133], v[170:173], v[190:193], v[130:133]
	v_mfma_f32_16x16x32_bf16 v[122:125], v[180:183], v[190:193], v[122:125]
	v_mfma_f32_16x16x32_bf16 v[106:109], v[170:173], v[198:201], v[106:109]
	v_mfma_f32_16x16x32_bf16 v[102:105], v[180:183], v[198:201], v[102:105]
	v_mfma_f32_16x16x32_bf16 v[90:93], v[170:173], v[206:209], v[90:93]
	v_mfma_f32_16x16x32_bf16 v[86:89], v[180:183], v[206:209], v[86:89]
	v_mfma_f32_16x16x32_bf16 v[74:77], v[170:173], v[214:217], v[74:77]
	v_mfma_f32_16x16x32_bf16 v[70:73], v[180:183], v[214:217], v[70:73]
	s_setprio 0
	s_barrier
; #define PG8_STAGE(bufoff, gbase, voff) do { _Pragma("unroll") for (int _i = 0; _i < 2; ++_i) \
;         __builtin_amdgcn_global_load_lds((const unsigned*)((const char*)(gbase) + (voff)[_i]), (PG8_LAS unsigned*)(lds + (bufoff) + ldsw + _i * 8192), 16, 0, 0); } while (0)
; #define PG8_LDA(dst, b, h) do { _Pragma("unroll") for (int m = 0; m < 4; ++m) _Pragma("unroll") for (int k = 0; k < 2; ++k) dst[m][k] = *(const PG8_LAS bf16x8*)(lds + PG8_SA(b, h) + aoff + m * 2048 + k * 1024); } while (0)
; #define PG8_MMA(ai, bj, At, Bt) do { __builtin_amdgcn_s_setprio(1); _Pragma("unroll") for (int m = 0; m < 4; ++m) _Pragma("unroll") for (int n = 0; n < 2; ++n) _Pragma("unroll") for (int k = 0; k < 2; ++k) \
;         acc[ai][bj][m][n] = __builtin_amdgcn_mfma_f32_16x16x32_bf16(Bt[n][k], At[m][k], acc[ai][bj][m][n], 0, 0, 0); __builtin_amdgcn_s_setprio(0); } while (0)
; #define PG8_WAIT_V(n) asm volatile("s_waitcnt vmcnt(" #n ")" ::: "memory")
; #define PG8_WAIT_L(n) asm volatile("s_waitcnt lgkmcnt(" #n ")" ::: "memory")
; #define PG8_BAR __builtin_amdgcn_s_barrier()
; #define PG8_SCHED __builtin_amdgcn_sched_barrier(0)
; template <class Epi, class Sched, bool ALIGN_EPI = false, bool SP2 = false>
; __device__ __forceinline__ void gemm_phase(PG8_LAS unsigned char* lds, const Gemm g, const Sched& S, const Epi& E) {
;     ...
;             PG8_LDA(At, 1, 1); PG8_STAGE(PG8_SB(1, 0), b3, voffB); PG8_STAGE(PG8_SB(1, 1), b3 + hstep, voffB); PG8_STAGE(PG8_SA(1, 0), a3, voffA);
;             PG8_WAIT_V(8); PG8_WAIT_L(0); PG8_BAR; PG8_MMA(1, 0, At, B0); PG8_MMA(1, 1, At, B1); PG8_BAR; PG8_SCHED;
	s_add_i32 s28, s50, s36
	v_lshl_add_u64 v[156:157], v[156:157], 0, s[80:81]
	s_mov_b32 m0, s28
	ds_read_b128 v[186:189], v160 offset:49152
	ds_read_b128 v[190:193], v160 offset:50176
	ds_read_b128 v[194:197], v160 offset:51200
	ds_read_b128 v[198:201], v160 offset:52224
	ds_read_b128 v[202:205], v160 offset:53248
	ds_read_b128 v[206:209], v160 offset:54272
	ds_read_b128 v[210:213], v160 offset:55296
	ds_read_b128 v[214:217], v160 offset:56320
	global_load_lds_dwordx4 v[156:157], off
	s_add_i32 m0, s28, 0x2000
	s_add_u32 s26, s26, 0x40080
	v_lshl_add_u64 v[156:157], v[218:219], 0, s[80:81]
	s_addc_u32 s27, s27, 0
	s_add_i32 s28, s51, s36
	global_load_lds_dwordx4 v[156:157], off
	v_lshl_add_u64 v[156:157], s[26:27], 0, v[142:143]
	s_mov_b32 m0, s28
	s_nop 0
	global_load_lds_dwordx4 v[156:157], off
	v_lshl_add_u64 v[156:157], s[26:27], 0, v[138:139]
	s_add_i32 m0, s28, 0x2000
	s_nop 0
	global_load_lds_dwordx4 v[156:157], off
	v_lshl_add_u64 v[156:157], v[220:221], 0, s[80:81]
	s_mov_b32 m0, s41
	s_nop 0
	global_load_lds_dwordx4 v[156:157], off
	v_lshl_add_u64 v[156:157], v[222:223], 0, s[80:81]
	s_mov_b32 m0, s42
	s_nop 0
	global_load_lds_dwordx4 v[156:157], off
	s_waitcnt vmcnt(8)
	s_waitcnt lgkmcnt(0)
	s_barrier
	s_setprio 1
	v_mfma_f32_16x16x32_bf16 v[62:65], v[66:69], v[186:189], v[62:65]
	v_mfma_f32_16x16x32_bf16 v[58:61], v[152:155], v[186:189], v[58:61]
	v_mfma_f32_16x16x32_bf16 v[46:49], v[66:69], v[194:197], v[46:49]
	v_mfma_f32_16x16x32_bf16 v[42:45], v[152:155], v[194:197], v[42:45]
	v_mfma_f32_16x16x32_bf16 v[30:33], v[66:69], v[202:205], v[30:33]
	v_mfma_f32_16x16x32_bf16 v[26:29], v[152:155], v[202:205], v[26:29]
	v_mfma_f32_16x16x32_bf16 v[14:17], v[66:69], v[210:213], v[14:17]
	v_mfma_f32_16x16x32_bf16 v[10:13], v[152:155], v[210:213], v[10:13]
	v_mfma_f32_16x16x32_bf16 v[62:65], v[118:121], v[190:193], v[62:65]
	v_mfma_f32_16x16x32_bf16 v[58:61], v[162:165], v[190:193], v[58:61]
	v_mfma_f32_16x16x32_bf16 v[46:49], v[118:121], v[198:201], v[46:49]
	v_mfma_f32_16x16x32_bf16 v[42:45], v[162:165], v[198:201], v[42:45]
	v_mfma_f32_16x16x32_bf16 v[30:33], v[118:121], v[206:209], v[30:33]
	v_mfma_f32_16x16x32_bf16 v[26:29], v[162:165], v[206:209], v[26:29]
	v_mfma_f32_16x16x32_bf16 v[14:17], v[118:121], v[214:217], v[14:17]
	v_mfma_f32_16x16x32_bf16 v[10:13], v[162:165], v[214:217], v[10:13]
	s_setprio 0
	s_setprio 1
	v_mfma_f32_16x16x32_bf16 v[54:57], v[166:169], v[186:189], v[54:57]
	v_mfma_f32_16x16x32_bf16 v[50:53], v[174:177], v[186:189], v[50:53]
	v_mfma_f32_16x16x32_bf16 v[38:41], v[166:169], v[194:197], v[38:41]
	v_mfma_f32_16x16x32_bf16 v[34:37], v[174:177], v[194:197], v[34:37]
	v_mfma_f32_16x16x32_bf16 v[22:25], v[166:169], v[202:205], v[22:25]
	v_mfma_f32_16x16x32_bf16 v[18:21], v[174:177], v[202:205], v[18:21]
	v_mfma_f32_16x16x32_bf16 v[6:9], v[166:169], v[210:213], v[6:9]
	v_mfma_f32_16x16x32_bf16 v[2:5], v[174:177], v[210:213], v[2:5]
	v_mfma_f32_16x16x32_bf16 v[54:57], v[170:173], v[190:193], v[54:57]
	v_mfma_f32_16x16x32_bf16 v[50:53], v[180:183], v[190:193], v[50:53]
	v_mfma_f32_16x16x32_bf16 v[38:41], v[170:173], v[198:201], v[38:41]
	v_mfma_f32_16x16x32_bf16 v[34:37], v[180:183], v[198:201], v[34:37]
	v_mfma_f32_16x16x32_bf16 v[22:25], v[170:173], v[206:209], v[22:25]
	v_mfma_f32_16x16x32_bf16 v[18:21], v[180:183], v[206:209], v[18:21]
	v_mfma_f32_16x16x32_bf16 v[6:9], v[170:173], v[214:217], v[6:9]
	v_mfma_f32_16x16x32_bf16 v[2:5], v[180:183], v[214:217], v[2:5]
	s_setprio 0
	s_barrier
	s_add_i32 s49, s49, 2
	s_add_u32 s24, s24, 0x100
	s_addc_u32 s25, s25, 0
	s_add_u32 s47, s47, 0x100
	s_addc_u32 s48, s48, 0
	s_cmp_gt_u32 s49, 13
	s_branch .LBB0_1249

; #define PG8_STAGE(bufoff, gbase, voff) do { _Pragma("unroll") for (int _i = 0; _i < 2; ++_i) \
;         __builtin_amdgcn_global_load_lds((const unsigned*)((const char*)(gbase) + (voff)[_i]), (PG8_LAS unsigned*)(lds + (bufoff) + ldsw + _i * 8192), 16, 0, 0); } while (0)
; #define PG8_LDA(dst, b, h) do { _Pragma("unroll") for (int m = 0; m < 4; ++m) _Pragma("unroll") for (int k = 0; k < 2; ++k) dst[m][k] = *(const PG8_LAS bf16x8*)(lds + PG8_SA(b, h) + aoff + m * 2048 + k * 1024); } while (0)
; #define PG8_LDB(dst, b, h) do { _Pragma("unroll") for (int n = 0; n < 2; ++n) _Pragma("unroll") for (int k = 0; k < 2; ++k) dst[n][k] = *(const PG8_LAS bf16x8*)(lds + PG8_SB(b, h) + boff + n * 2048 + k * 1024); } while (0)
; #define PG8_MMA(ai, bj, At, Bt) do { __builtin_amdgcn_s_setprio(1); _Pragma("unroll") for (int m = 0; m < 4; ++m) _Pragma("unroll") for (int n = 0; n < 2; ++n) _Pragma("unroll") for (int k = 0; k < 2; ++k) \
;         acc[ai][bj][m][n] = __builtin_amdgcn_mfma_f32_16x16x32_bf16(Bt[n][k], At[m][k], acc[ai][bj][m][n], 0, 0, 0); __builtin_amdgcn_s_setprio(0); } while (0)
; #define PG8_WAIT_V(n) asm volatile("s_waitcnt vmcnt(" #n ")" ::: "memory")
; template <class Epi, class Sched, bool ALIGN_EPI = false, bool SP2 = false>
; __device__ __forceinline__ void gemm_phase(PG8_LAS unsigned char* lds, const Gemm g, const Sched& S, const Epi& E) {
;     ...
;         const char* nA = has_next ? (const char*)g.A + (size_t)nxt.pm * tstep : cA; const char* nB = has_next ? (const char*)g.Bt + (size_t)nxt.pn * tstep : cB;
;         for (int t = 0; t < nt; t += 2) {
;             const bool last = (t == nt - 2);
;             const char* a1 = cA + (size_t)(t + 1) * kstep;
;             const char* a2 = last ? nA : cA + (size_t)(t + 2) * kstep; const char* b2 = last ? nB : cB + (size_t)(t + 2) * kstep;
;             const char* a3 = a2 + kstep; const char* b3 = b2 + kstep;
;             if (last && has_next) S.a_ready(nxt);
;             if constexpr (SP2) {
;             PG8_LDB(B0, 0, 0); PG8_LDB(B1, 0, 1); PG8_SCHED; PG8_LDA(At, 0, 0); PG8_STAGE(PG8_SA(1, 1), a1 + hstep, voffA);
;             PG8_WAIT_V(8); PG8_WAIT_L(0); PG8_BAR; PG8_MMA(0, 0, At, B0); PG8_MMA(0, 1, At, B1); PG8_BAR; PG8_SCHED;
;             PG8_LDA(At, 0, 1); PG8_STAGE(PG8_SB(0, 0), b2, voffB); PG8_STAGE(PG8_SB(0, 1), b2 + hstep, voffB); PG8_STAGE(PG8_SA(0, 0), a2, voffA);
.LBB0_1329:
	s_add_u32 s49, s22, 0x100
	s_addc_u32 s50, s23, 0
	s_mov_b32 s51, -2
	s_add_u32 s22, s20, 0x100
	s_addc_u32 s23, s21, 0
	s_add_i32 s52, 0, 0x10000
	s_cmp_eq_u32 s51, 40
	s_cselect_b32 s27, s7, s23
	s_cselect_b32 s26, s6, s22
	v_add_u32_e32 v157, s52, v154
	s_cselect_b32 s25, s19, s50
	s_cselect_b32 s24, s18, s49
	s_add_i32 s53, 0, 0x14000
	ds_read_b128 v[142:145], v157
	ds_read_b128 v[146:149], v157 offset:1024
	ds_read_b128 v[150:153], v157 offset:2048
	ds_read_b128 v[158:161], v157 offset:3072
	v_add_u32_e32 v157, s53, v154
	ds_read_b128 v[162:165], v157
	ds_read_b128 v[166:169], v157 offset:1024
	ds_read_b128 v[170:173], v157 offset:2048
	ds_read_b128 v[174:177], v157 offset:3072
	v_lshl_add_u64 v[214:215], s[20:21], 0, v[138:139]
	s_add_i32 m0, s37, 0xc000
	ds_read_b128 v[180:183], v156
	ds_read_b128 v[186:189], v156 offset:1024
	ds_read_b128 v[190:193], v156 offset:2048
	ds_read_b128 v[194:197], v156 offset:3072
	ds_read_b128 v[198:201], v156 offset:4096
	ds_read_b128 v[202:205], v156 offset:5120
	ds_read_b128 v[206:209], v156 offset:6144
	ds_read_b128 v[210:213], v156 offset:7168
	global_load_lds_dwordx4 v[214:215], off
	v_lshl_add_u64 v[214:215], s[20:21], 0, v[140:141]
	s_add_i32 m0, s37, 0xe000
	s_nop 0
	global_load_lds_dwordx4 v[214:215], off
	s_waitcnt vmcnt(8)
	s_waitcnt lgkmcnt(0)
	s_barrier
	s_setprio 1
	v_mfma_f32_16x16x32_bf16 v[126:129], v[142:145], v[180:183], 0
	v_mfma_f32_16x16x32_bf16 v[122:125], v[150:153], v[180:183], 0
	v_mfma_f32_16x16x32_bf16 v[114:117], v[142:145], v[190:193], 0
	v_mfma_f32_16x16x32_bf16 v[106:109], v[150:153], v[190:193], 0
	v_mfma_f32_16x16x32_bf16 v[98:101], v[142:145], v[198:201], 0
	v_mfma_f32_16x16x32_bf16 v[90:93], v[150:153], v[198:201], 0
	v_mfma_f32_16x16x32_bf16 v[82:85], v[142:145], v[206:209], 0
	v_mfma_f32_16x16x32_bf16 v[74:77], v[150:153], v[206:209], 0
	v_mfma_f32_16x16x32_bf16 v[126:129], v[146:149], v[186:189], v[126:129]
	v_mfma_f32_16x16x32_bf16 v[122:125], v[158:161], v[186:189], v[122:125]
	v_mfma_f32_16x16x32_bf16 v[114:117], v[146:149], v[194:197], v[114:117]
	v_mfma_f32_16x16x32_bf16 v[106:109], v[158:161], v[194:197], v[106:109]
	v_mfma_f32_16x16x32_bf16 v[98:101], v[146:149], v[202:205], v[98:101]
	v_mfma_f32_16x16x32_bf16 v[90:93], v[158:161], v[202:205], v[90:93]
	v_mfma_f32_16x16x32_bf16 v[82:85], v[146:149], v[210:213], v[82:85]
	v_mfma_f32_16x16x32_bf16 v[74:77], v[158:161], v[210:213], v[74:77]
	s_setprio 0
	s_setprio 1
	v_mfma_f32_16x16x32_bf16 v[118:121], v[162:165], v[180:183], 0
	v_mfma_f32_16x16x32_bf16 v[110:113], v[170:173], v[180:183], 0
	v_mfma_f32_16x16x32_bf16 v[102:105], v[162:165], v[190:193], 0
	v_mfma_f32_16x16x32_bf16 v[94:97], v[170:173], v[190:193], 0
	v_mfma_f32_16x16x32_bf16 v[86:89], v[162:165], v[198:201], 0
	v_mfma_f32_16x16x32_bf16 v[78:81], v[170:173], v[198:201], 0
	v_mfma_f32_16x16x32_bf16 v[70:73], v[162:165], v[206:209], 0
	v_mfma_f32_16x16x32_bf16 v[66:69], v[170:173], v[206:209], 0
	v_mfma_f32_16x16x32_bf16 v[118:121], v[166:169], v[186:189], v[118:121]
	v_mfma_f32_16x16x32_bf16 v[110:113], v[174:177], v[186:189], v[110:113]
	v_mfma_f32_16x16x32_bf16 v[102:105], v[166:169], v[194:197], v[102:105]
	v_mfma_f32_16x16x32_bf16 v[94:97], v[174:177], v[194:197], v[94:97]
	v_mfma_f32_16x16x32_bf16 v[86:89], v[166:169], v[202:205], v[86:89]
	v_mfma_f32_16x16x32_bf16 v[78:81], v[174:177], v[202:205], v[78:81]
	v_mfma_f32_16x16x32_bf16 v[70:73], v[166:169], v[210:213], v[70:73]
	v_mfma_f32_16x16x32_bf16 v[66:69], v[174:177], v[210:213], v[66:69]
	s_setprio 0
	s_barrier
	s_add_i32 s20, s52, s36
	v_lshl_add_u64 v[214:215], s[24:25], 0, v[132:133]
	s_mov_b32 m0, s20
	ds_read_b128 v[180:183], v156 offset:16384
	ds_read_b128 v[186:189], v156 offset:17408
	ds_read_b128 v[190:193], v156 offset:18432
	ds_read_b128 v[194:197], v156 offset:19456
	ds_read_b128 v[198:201], v156 offset:20480
	ds_read_b128 v[202:205], v156 offset:21504
	ds_read_b128 v[206:209], v156 offset:22528
	ds_read_b128 v[210:213], v156 offset:23552
	global_load_lds_dwordx4 v[214:215], off
	s_add_i32 m0, s20, 0x2000
	s_add_u32 s20, s24, 0xb0000
	v_lshl_add_u64 v[216:217], s[24:25], 0, v[136:137]
	s_addc_u32 s21, s25, 0
	s_add_i32 s52, s53, s36
	global_load_lds_dwordx4 v[216:217], off
	v_lshl_add_u64 v[218:219], s[20:21], 0, v[132:133]
	s_mov_b32 m0, s52
	v_lshl_add_u64 v[220:221], s[26:27], 0, v[134:135]
	global_load_lds_dwordx4 v[218:219], off
	v_lshl_add_u64 v[218:219], s[20:21], 0, v[136:137]
	s_add_i32 m0, s52, 0x2000
	s_nop 0
	global_load_lds_dwordx4 v[218:219], off
	v_lshl_add_u64 v[218:219], s[26:27], 0, v[130:131]
	s_mov_b32 m0, s37
	s_nop 0
	global_load_lds_dwordx4 v[218:219], off
	s_mov_b32 m0, s38
	s_nop 0
	global_load_lds_dwordx4 v[220:221], off
	s_waitcnt vmcnt(8)
	s_waitcnt lgkmcnt(0)
	s_barrier
; #define PG8_STAGE(bufoff, gbase, voff) do { _Pragma("unroll") for (int _i = 0; _i < 2; ++_i) \
;         __builtin_amdgcn_global_load_lds((const unsigned*)((const char*)(gbase) + (voff)[_i]), (PG8_LAS unsigned*)(lds + (bufoff) + ldsw + _i * 8192), 16, 0, 0); } while (0)
; #define PG8_LDA(dst, b, h) do { _Pragma("unroll") for (int m = 0; m < 4; ++m) _Pragma("unroll") for (int k = 0; k < 2; ++k) dst[m][k] = *(const PG8_LAS bf16x8*)(lds + PG8_SA(b, h) + aoff + m * 2048 + k * 1024); } while (0)
; #define PG8_LDB(dst, b, h) do { _Pragma("unroll") for (int n = 0; n < 2; ++n) _Pragma("unroll") for (int k = 0; k < 2; ++k) dst[n][k] = *(const PG8_LAS bf16x8*)(lds + PG8_SB(b, h) + boff + n * 2048 + k * 1024); } while (0)
; #define PG8_MMA(ai, bj, At, Bt) do { __builtin_amdgcn_s_setprio(1); _Pragma("unroll") for (int m = 0; m < 4; ++m) _Pragma("unroll") for (int n = 0; n < 2; ++n) _Pragma("unroll") for (int k = 0; k < 2; ++k) \
;         acc[ai][bj][m][n] = __builtin_amdgcn_mfma_f32_16x16x32_bf16(Bt[n][k], At[m][k], acc[ai][bj][m][n], 0, 0, 0); __builtin_amdgcn_s_setprio(0); } while (0)
; #define PG8_WAIT_V(n) asm volatile("s_waitcnt vmcnt(" #n ")" ::: "memory")
; #define PG8_WAIT_L(n) asm volatile("s_waitcnt lgkmcnt(" #n ")" ::: "memory")
; #define PG8_BAR __builtin_amdgcn_s_barrier()
; #define PG8_SCHED __builtin_amdgcn_sched_barrier(0)
; template <class Epi, class Sched, bool ALIGN_EPI = false, bool SP2 = false>
; __device__ __forceinline__ void gemm_phase(PG8_LAS unsigned char* lds, const Gemm g, const Sched& S, const Epi& E) {
;     ...
;             PG8_WAIT_V(8); PG8_WAIT_L(0); PG8_BAR; PG8_MMA(1, 0, At, B0); PG8_MMA(1, 1, At, B1); PG8_BAR; PG8_SCHED;
;             PG8_LDB(B0, 1, 0); PG8_LDB(B1, 1, 1); PG8_SCHED; PG8_LDA(At, 1, 0); PG8_STAGE(PG8_SA(0, 1), a2 + hstep, voffA);
;             PG8_WAIT_V(8); PG8_WAIT_L(0); PG8_BAR; PG8_MMA(0, 0, At, B0); PG8_MMA(0, 1, At, B1); PG8_BAR; PG8_SCHED;
	s_setprio 1
	v_mfma_f32_16x16x32_bf16 v[62:65], v[142:145], v[180:183], 0
	v_mfma_f32_16x16x32_bf16 v[58:61], v[150:153], v[180:183], 0
	v_mfma_f32_16x16x32_bf16 v[50:53], v[142:145], v[190:193], 0
	v_mfma_f32_16x16x32_bf16 v[42:45], v[150:153], v[190:193], 0
	v_mfma_f32_16x16x32_bf16 v[34:37], v[142:145], v[198:201], 0
	v_mfma_f32_16x16x32_bf16 v[26:29], v[150:153], v[198:201], 0
	v_mfma_f32_16x16x32_bf16 v[18:21], v[142:145], v[206:209], 0
	v_mfma_f32_16x16x32_bf16 v[10:13], v[150:153], v[206:209], 0
	v_mfma_f32_16x16x32_bf16 v[62:65], v[146:149], v[186:189], v[62:65]
	v_mfma_f32_16x16x32_bf16 v[58:61], v[158:161], v[186:189], v[58:61]
	v_mfma_f32_16x16x32_bf16 v[50:53], v[146:149], v[194:197], v[50:53]
	v_mfma_f32_16x16x32_bf16 v[42:45], v[158:161], v[194:197], v[42:45]
	v_mfma_f32_16x16x32_bf16 v[34:37], v[146:149], v[202:205], v[34:37]
	v_mfma_f32_16x16x32_bf16 v[26:29], v[158:161], v[202:205], v[26:29]
	v_mfma_f32_16x16x32_bf16 v[18:21], v[146:149], v[210:213], v[18:21]
	v_mfma_f32_16x16x32_bf16 v[10:13], v[158:161], v[210:213], v[10:13]
	s_setprio 0
	s_setprio 1
	v_mfma_f32_16x16x32_bf16 v[54:57], v[162:165], v[180:183], 0
	v_mfma_f32_16x16x32_bf16 v[46:49], v[170:173], v[180:183], 0
	v_mfma_f32_16x16x32_bf16 v[38:41], v[162:165], v[190:193], 0
	v_mfma_f32_16x16x32_bf16 v[30:33], v[170:173], v[190:193], 0
	v_mfma_f32_16x16x32_bf16 v[22:25], v[162:165], v[198:201], 0
	v_mfma_f32_16x16x32_bf16 v[14:17], v[170:173], v[198:201], 0
	v_mfma_f32_16x16x32_bf16 v[6:9], v[162:165], v[206:209], 0
	v_mfma_f32_16x16x32_bf16 v[2:5], v[170:173], v[206:209], 0
	v_mfma_f32_16x16x32_bf16 v[54:57], v[166:169], v[186:189], v[54:57]
	v_mfma_f32_16x16x32_bf16 v[46:49], v[174:177], v[186:189], v[46:49]
	v_mfma_f32_16x16x32_bf16 v[38:41], v[166:169], v[194:197], v[38:41]
	v_mfma_f32_16x16x32_bf16 v[30:33], v[174:177], v[194:197], v[30:33]
	v_mfma_f32_16x16x32_bf16 v[22:25], v[166:169], v[202:205], v[22:25]
	v_mfma_f32_16x16x32_bf16 v[14:17], v[174:177], v[202:205], v[14:17]
	v_mfma_f32_16x16x32_bf16 v[6:9], v[166:169], v[210:213], v[6:9]
	v_mfma_f32_16x16x32_bf16 v[2:5], v[174:177], v[210:213], v[2:5]
	s_setprio 0
	s_barrier
	s_add_i32 s52, 0, 0x18000
	v_add_u32_e32 v157, s52, v154
	s_add_i32 s53, 0, 0x1c000
	ds_read_b128 v[142:145], v157
	ds_read_b128 v[146:149], v157 offset:1024
	ds_read_b128 v[150:153], v157 offset:2048
	ds_read_b128 v[158:161], v157 offset:3072
	v_add_u32_e32 v157, s53, v154
	ds_read_b128 v[162:165], v157
	ds_read_b128 v[166:169], v157 offset:1024
	ds_read_b128 v[170:173], v157 offset:2048
	ds_read_b128 v[174:177], v157 offset:3072
	s_add_u32 s20, s26, 0xb0000
	s_addc_u32 s21, s27, 0
	s_mov_b32 m0, s39
	v_lshl_add_u64 v[222:223], s[20:21], 0, v[130:131]
	ds_read_b128 v[180:183], v156 offset:32768
	ds_read_b128 v[186:189], v156 offset:33792
	ds_read_b128 v[190:193], v156 offset:34816
	ds_read_b128 v[194:197], v156 offset:35840
	ds_read_b128 v[198:201], v156 offset:36864
	ds_read_b128 v[202:205], v156 offset:37888
	ds_read_b128 v[206:209], v156 offset:38912
	ds_read_b128 v[210:213], v156 offset:39936
	global_load_lds_dwordx4 v[222:223], off
	v_lshl_add_u64 v[222:223], s[20:21], 0, v[134:135]
	s_mov_b32 m0, s40
	s_nop 0
	global_load_lds_dwordx4 v[222:223], off
	s_waitcnt vmcnt(8)
	s_waitcnt lgkmcnt(0)
	s_barrier
	s_setprio 1
	v_mfma_f32_16x16x32_bf16 v[126:129], v[142:145], v[180:183], v[126:129]
	v_mfma_f32_16x16x32_bf16 v[122:125], v[150:153], v[180:183], v[122:125]
	v_mfma_f32_16x16x32_bf16 v[114:117], v[142:145], v[190:193], v[114:117]
	v_mfma_f32_16x16x32_bf16 v[106:109], v[150:153], v[190:193], v[106:109]
	v_mfma_f32_16x16x32_bf16 v[98:101], v[142:145], v[198:201], v[98:101]
	v_mfma_f32_16x16x32_bf16 v[90:93], v[150:153], v[198:201], v[90:93]
	v_mfma_f32_16x16x32_bf16 v[82:85], v[142:145], v[206:209], v[82:85]
	v_mfma_f32_16x16x32_bf16 v[74:77], v[150:153], v[206:209], v[74:77]
	v_mfma_f32_16x16x32_bf16 v[126:129], v[146:149], v[186:189], v[126:129]
	v_mfma_f32_16x16x32_bf16 v[122:125], v[158:161], v[186:189], v[122:125]
	v_mfma_f32_16x16x32_bf16 v[114:117], v[146:149], v[194:197], v[114:117]
	v_mfma_f32_16x16x32_bf16 v[106:109], v[158:161], v[194:197], v[106:109]
	v_mfma_f32_16x16x32_bf16 v[98:101], v[146:149], v[202:205], v[98:101]
	v_mfma_f32_16x16x32_bf16 v[90:93], v[158:161], v[202:205], v[90:93]
	v_mfma_f32_16x16x32_bf16 v[82:85], v[146:149], v[210:213], v[82:85]
	v_mfma_f32_16x16x32_bf16 v[74:77], v[158:161], v[210:213], v[74:77]
	s_setprio 0
	s_setprio 1
	v_mfma_f32_16x16x32_bf16 v[118:121], v[162:165], v[180:183], v[118:121]
	v_mfma_f32_16x16x32_bf16 v[110:113], v[170:173], v[180:183], v[110:113]
	v_mfma_f32_16x16x32_bf16 v[102:105], v[162:165], v[190:193], v[102:105]
	v_mfma_f32_16x16x32_bf16 v[94:97], v[170:173], v[190:193], v[94:97]
	v_mfma_f32_16x16x32_bf16 v[86:89], v[162:165], v[198:201], v[86:89]
	v_mfma_f32_16x16x32_bf16 v[78:81], v[170:173], v[198:201], v[78:81]
	v_mfma_f32_16x16x32_bf16 v[70:73], v[162:165], v[206:209], v[70:73]
	v_mfma_f32_16x16x32_bf16 v[66:69], v[170:173], v[206:209], v[66:69]
	v_mfma_f32_16x16x32_bf16 v[118:121], v[166:169], v[186:189], v[118:121]
	v_mfma_f32_16x16x32_bf16 v[110:113], v[174:177], v[186:189], v[110:113]
	v_mfma_f32_16x16x32_bf16 v[102:105], v[166:169], v[194:197], v[102:105]
	v_mfma_f32_16x16x32_bf16 v[94:97], v[174:177], v[194:197], v[94:97]
	v_mfma_f32_16x16x32_bf16 v[86:89], v[166:169], v[202:205], v[86:89]
	v_mfma_f32_16x16x32_bf16 v[78:81], v[174:177], v[202:205], v[78:81]
	v_mfma_f32_16x16x32_bf16 v[70:73], v[166:169], v[210:213], v[70:73]
	v_mfma_f32_16x16x32_bf16 v[66:69], v[174:177], v[210:213], v[66:69]
	s_setprio 0
	s_barrier
; #define PG8_STAGE(bufoff, gbase, voff) do { _Pragma("unroll") for (int _i = 0; _i < 2; ++_i) \
;         __builtin_amdgcn_global_load_lds((const unsigned*)((const char*)(gbase) + (voff)[_i]), (PG8_LAS unsigned*)(lds + (bufoff) + ldsw + _i * 8192), 16, 0, 0); } while (0)
; #define PG8_LDA(dst, b, h) do { _Pragma("unroll") for (int m = 0; m < 4; ++m) _Pragma("unroll") for (int k = 0; k < 2; ++k) dst[m][k] = *(const PG8_LAS bf16x8*)(lds + PG8_SA(b, h) + aoff + m * 2048 + k * 1024); } while (0)
; #define PG8_MMA(ai, bj, At, Bt) do { __builtin_amdgcn_s_setprio(1); _Pragma("unroll") for (int m = 0; m < 4; ++m) _Pragma("unroll") for (int n = 0; n < 2; ++n) _Pragma("unroll") for (int k = 0; k < 2; ++k) \
;         acc[ai][bj][m][n] = __builtin_amdgcn_mfma_f32_16x16x32_bf16(Bt[n][k], At[m][k], acc[ai][bj][m][n], 0, 0, 0); __builtin_amdgcn_s_setprio(0); } while (0)
; #define PG8_WAIT_V(n) asm volatile("s_waitcnt vmcnt(" #n ")" ::: "memory")
; #define PG8_WAIT_L(n) asm volatile("s_waitcnt lgkmcnt(" #n ")" ::: "memory")
; #define PG8_BAR __builtin_amdgcn_s_barrier()
; #define PG8_SCHED __builtin_amdgcn_sched_barrier(0)
; template <class Epi, class Sched, bool ALIGN_EPI = false, bool SP2 = false>
; __device__ __forceinline__ void gemm_phase(PG8_LAS unsigned char* lds, const Gemm g, const Sched& S, const Epi& E) {
;     ...
;             PG8_LDA(At, 1, 1); PG8_STAGE(PG8_SB(1, 0), b3, voffB); PG8_STAGE(PG8_SB(1, 1), b3 + hstep, voffB); PG8_STAGE(PG8_SA(1, 0), a3, voffA);
;             PG8_WAIT_V(8); PG8_WAIT_L(0); PG8_BAR; PG8_MMA(1, 0, At, B0); PG8_MMA(1, 1, At, B1); PG8_BAR; PG8_SCHED;
	s_add_i32 s20, s52, s36
	v_lshl_add_u64 v[214:215], v[214:215], 0, s[80:81]
	s_mov_b32 m0, s20
	ds_read_b128 v[180:183], v156 offset:49152
	ds_read_b128 v[186:189], v156 offset:50176
	ds_read_b128 v[190:193], v156 offset:51200
	ds_read_b128 v[194:197], v156 offset:52224
	ds_read_b128 v[198:201], v156 offset:53248
	ds_read_b128 v[202:205], v156 offset:54272
	ds_read_b128 v[206:209], v156 offset:55296
	ds_read_b128 v[210:213], v156 offset:56320
	global_load_lds_dwordx4 v[214:215], off
	s_add_i32 m0, s20, 0x2000
	s_add_u32 s20, s24, 0xb0080
	v_lshl_add_u64 v[214:215], v[216:217], 0, s[80:81]
	s_addc_u32 s21, s25, 0
	s_add_i32 s24, s53, s36
	global_load_lds_dwordx4 v[214:215], off
	v_lshl_add_u64 v[214:215], s[20:21], 0, v[132:133]
	s_mov_b32 m0, s24
	s_nop 0
	global_load_lds_dwordx4 v[214:215], off
	v_lshl_add_u64 v[214:215], s[20:21], 0, v[136:137]
	s_add_i32 m0, s24, 0x2000
	s_nop 0
	global_load_lds_dwordx4 v[214:215], off
	v_lshl_add_u64 v[214:215], v[218:219], 0, s[80:81]
	s_mov_b32 m0, s41
	s_nop 0
	global_load_lds_dwordx4 v[214:215], off
	v_lshl_add_u64 v[214:215], v[220:221], 0, s[80:81]
	s_mov_b32 m0, s42
	s_nop 0
	global_load_lds_dwordx4 v[214:215], off
	s_waitcnt vmcnt(8)
	s_waitcnt lgkmcnt(0)
	s_barrier
	s_setprio 1
	v_mfma_f32_16x16x32_bf16 v[62:65], v[142:145], v[180:183], v[62:65]
	v_mfma_f32_16x16x32_bf16 v[58:61], v[150:153], v[180:183], v[58:61]
	v_mfma_f32_16x16x32_bf16 v[50:53], v[142:145], v[190:193], v[50:53]
	v_mfma_f32_16x16x32_bf16 v[42:45], v[150:153], v[190:193], v[42:45]
	v_mfma_f32_16x16x32_bf16 v[34:37], v[142:145], v[198:201], v[34:37]
	v_mfma_f32_16x16x32_bf16 v[26:29], v[150:153], v[198:201], v[26:29]
	v_mfma_f32_16x16x32_bf16 v[18:21], v[142:145], v[206:209], v[18:21]
	v_mfma_f32_16x16x32_bf16 v[10:13], v[150:153], v[206:209], v[10:13]
	v_mfma_f32_16x16x32_bf16 v[62:65], v[146:149], v[186:189], v[62:65]
	v_mfma_f32_16x16x32_bf16 v[58:61], v[158:161], v[186:189], v[58:61]
	v_mfma_f32_16x16x32_bf16 v[50:53], v[146:149], v[194:197], v[50:53]
	v_mfma_f32_16x16x32_bf16 v[42:45], v[158:161], v[194:197], v[42:45]
	v_mfma_f32_16x16x32_bf16 v[34:37], v[146:149], v[202:205], v[34:37]
	v_mfma_f32_16x16x32_bf16 v[26:29], v[158:161], v[202:205], v[26:29]
	v_mfma_f32_16x16x32_bf16 v[18:21], v[146:149], v[210:213], v[18:21]
	v_mfma_f32_16x16x32_bf16 v[10:13], v[158:161], v[210:213], v[10:13]
	s_setprio 0
	s_setprio 1
	v_mfma_f32_16x16x32_bf16 v[54:57], v[162:165], v[180:183], v[54:57]
	v_mfma_f32_16x16x32_bf16 v[46:49], v[170:173], v[180:183], v[46:49]
	v_mfma_f32_16x16x32_bf16 v[38:41], v[162:165], v[190:193], v[38:41]
	v_mfma_f32_16x16x32_bf16 v[30:33], v[170:173], v[190:193], v[30:33]
	v_mfma_f32_16x16x32_bf16 v[22:25], v[162:165], v[198:201], v[22:25]
	v_mfma_f32_16x16x32_bf16 v[14:17], v[170:173], v[198:201], v[14:17]
	v_mfma_f32_16x16x32_bf16 v[6:9], v[162:165], v[206:209], v[6:9]
	v_mfma_f32_16x16x32_bf16 v[2:5], v[170:173], v[206:209], v[2:5]
	v_mfma_f32_16x16x32_bf16 v[54:57], v[166:169], v[186:189], v[54:57]
	v_mfma_f32_16x16x32_bf16 v[46:49], v[174:177], v[186:189], v[46:49]
	v_mfma_f32_16x16x32_bf16 v[38:41], v[166:169], v[194:197], v[38:41]
	v_mfma_f32_16x16x32_bf16 v[30:33], v[174:177], v[194:197], v[30:33]
	v_mfma_f32_16x16x32_bf16 v[22:25], v[166:169], v[202:205], v[22:25]
	v_mfma_f32_16x16x32_bf16 v[14:17], v[174:177], v[202:205], v[14:17]
	v_mfma_f32_16x16x32_bf16 v[6:9], v[166:169], v[210:213], v[6:9]
	v_mfma_f32_16x16x32_bf16 v[2:5], v[174:177], v[210:213], v[2:5]
	s_setprio 0
	s_barrier
	s_add_i32 s51, s51, 2
	s_add_u32 s49, s49, 0x100
	s_addc_u32 s50, s50, 0
	s_cmp_gt_u32 s51, 41
	s_mov_b64 s[20:21], s[22:23]
	s_branch .LBB0_1330

; #define PG8_STAGE(bufoff, gbase, voff) do { _Pragma("unroll") for (int _i = 0; _i < 2; ++_i) \
;         __builtin_amdgcn_global_load_lds((const unsigned*)((const char*)(gbase) + (voff)[_i]), (PG8_LAS unsigned*)(lds + (bufoff) + ldsw + _i * 8192), 16, 0, 0); } while (0)
; #define PG8_LDA(dst, b, h) do { _Pragma("unroll") for (int m = 0; m < 4; ++m) _Pragma("unroll") for (int k = 0; k < 2; ++k) dst[m][k] = *(const PG8_LAS bf16x8*)(lds + PG8_SA(b, h) + aoff + m * 2048 + k * 1024); } while (0)
; #define PG8_LDB(dst, b, h) do { _Pragma("unroll") for (int n = 0; n < 2; ++n) _Pragma("unroll") for (int k = 0; k < 2; ++k) dst[n][k] = *(const PG8_LAS bf16x8*)(lds + PG8_SB(b, h) + boff + n * 2048 + k * 1024); } while (0)
; #define PG8_MMA(ai, bj, At, Bt) do { __builtin_amdgcn_s_setprio(1); _Pragma("unroll") for (int m = 0; m < 4; ++m) _Pragma("unroll") for (int n = 0; n < 2; ++n) _Pragma("unroll") for (int k = 0; k < 2; ++k) \
;         acc[ai][bj][m][n] = __builtin_amdgcn_mfma_f32_16x16x32_bf16(Bt[n][k], At[m][k], acc[ai][bj][m][n], 0, 0, 0); __builtin_amdgcn_s_setprio(0); } while (0)
; #define PG8_WAIT_V(n) asm volatile("s_waitcnt vmcnt(" #n ")" ::: "memory")
; template <class Epi, class Sched, bool ALIGN_EPI = false, bool SP2 = false>
; __device__ __forceinline__ void gemm_phase(PG8_LAS unsigned char* lds, const Gemm g, const Sched& S, const Epi& E) {
;     ...
;         const char* nA = has_next ? (const char*)g.A + (size_t)nxt.pm * tstep : cA; const char* nB = has_next ? (const char*)g.Bt + (size_t)nxt.pn * tstep : cB;
;         for (int t = 0; t < nt; t += 2) {
;             const bool last = (t == nt - 2);
;             const char* a1 = cA + (size_t)(t + 1) * kstep;
;             const char* a2 = last ? nA : cA + (size_t)(t + 2) * kstep; const char* b2 = last ? nB : cB + (size_t)(t + 2) * kstep;
;             const char* a3 = a2 + kstep; const char* b3 = b2 + kstep;
;             if (last && has_next) S.a_ready(nxt);
;             if constexpr (SP2) {
;             PG8_LDB(B0, 0, 0); PG8_LDB(B1, 0, 1); PG8_SCHED; PG8_LDA(At, 0, 0); PG8_STAGE(PG8_SA(1, 1), a1 + hstep, voffA);
;             PG8_WAIT_V(8); PG8_WAIT_L(0); PG8_BAR; PG8_MMA(0, 0, At, B0); PG8_MMA(0, 1, At, B1); PG8_BAR; PG8_SCHED;
;             PG8_LDA(At, 0, 1); PG8_STAGE(PG8_SB(0, 0), b2, voffB); PG8_STAGE(PG8_SB(0, 1), b2 + hstep, voffB); PG8_STAGE(PG8_SA(0, 0), a2, voffA);
.LBB0_1359:
	s_add_u32 s47, s20, 0x100
	s_addc_u32 s48, s21, 0
	s_mov_b32 s49, -2
	s_add_u32 s20, s18, 0x100
	s_addc_u32 s21, s19, 0
	s_add_i32 s50, 0, 0x10000
	s_cmp_eq_u32 s49, 40
	s_cselect_b32 s25, s7, s21
	s_cselect_b32 s24, s6, s20
	v_add_u32_e32 v146, s50, v148
	s_cselect_b32 s23, s17, s48
	s_cselect_b32 s22, s16, s47
	s_add_i32 s51, 0, 0x14000
	ds_read_b128 v[142:145], v146
	ds_read_b128 v[152:155], v146 offset:1024
	ds_read_b128 v[156:159], v146 offset:2048
	ds_read_b128 v[160:163], v146 offset:3072
	v_add_u32_e32 v146, s51, v148
	ds_read_b128 v[164:167], v146
	ds_read_b128 v[168:171], v146 offset:1024
	ds_read_b128 v[172:175], v146 offset:2048
	ds_read_b128 v[180:183], v146 offset:3072
	v_lshl_add_u64 v[146:147], s[18:19], 0, v[138:139]
	s_add_i32 m0, s33, 0xc000
	ds_read_b128 v[186:189], v150
	ds_read_b128 v[190:193], v150 offset:1024
	ds_read_b128 v[194:197], v150 offset:2048
	ds_read_b128 v[198:201], v150 offset:3072
	ds_read_b128 v[202:205], v150 offset:4096
	ds_read_b128 v[206:209], v150 offset:5120
	ds_read_b128 v[210:213], v150 offset:6144
	ds_read_b128 v[214:217], v150 offset:7168
	global_load_lds_dwordx4 v[146:147], off
	v_lshl_add_u64 v[146:147], s[18:19], 0, v[140:141]
	s_add_i32 m0, s33, 0xe000
	s_nop 0
	global_load_lds_dwordx4 v[146:147], off
	s_waitcnt vmcnt(8)
	s_waitcnt lgkmcnt(0)
	s_barrier
	s_setprio 1
	v_mfma_f32_16x16x32_bf16 v[126:129], v[142:145], v[186:189], 0
	v_mfma_f32_16x16x32_bf16 v[122:125], v[156:159], v[186:189], 0
	v_mfma_f32_16x16x32_bf16 v[114:117], v[142:145], v[194:197], 0
	v_mfma_f32_16x16x32_bf16 v[106:109], v[156:159], v[194:197], 0
	v_mfma_f32_16x16x32_bf16 v[98:101], v[142:145], v[202:205], 0
	v_mfma_f32_16x16x32_bf16 v[90:93], v[156:159], v[202:205], 0
	v_mfma_f32_16x16x32_bf16 v[82:85], v[142:145], v[210:213], 0
	v_mfma_f32_16x16x32_bf16 v[74:77], v[156:159], v[210:213], 0
	v_mfma_f32_16x16x32_bf16 v[126:129], v[152:155], v[190:193], v[126:129]
	v_mfma_f32_16x16x32_bf16 v[122:125], v[160:163], v[190:193], v[122:125]
	v_mfma_f32_16x16x32_bf16 v[114:117], v[152:155], v[198:201], v[114:117]
	v_mfma_f32_16x16x32_bf16 v[106:109], v[160:163], v[198:201], v[106:109]
	v_mfma_f32_16x16x32_bf16 v[98:101], v[152:155], v[206:209], v[98:101]
	v_mfma_f32_16x16x32_bf16 v[90:93], v[160:163], v[206:209], v[90:93]
	v_mfma_f32_16x16x32_bf16 v[82:85], v[152:155], v[214:217], v[82:85]
	v_mfma_f32_16x16x32_bf16 v[74:77], v[160:163], v[214:217], v[74:77]
	s_setprio 0
	s_setprio 1
	v_mfma_f32_16x16x32_bf16 v[118:121], v[164:167], v[186:189], 0
	v_mfma_f32_16x16x32_bf16 v[110:113], v[172:175], v[186:189], 0
	v_mfma_f32_16x16x32_bf16 v[102:105], v[164:167], v[194:197], 0
	v_mfma_f32_16x16x32_bf16 v[94:97], v[172:175], v[194:197], 0
	v_mfma_f32_16x16x32_bf16 v[86:89], v[164:167], v[202:205], 0
	v_mfma_f32_16x16x32_bf16 v[78:81], v[172:175], v[202:205], 0
	v_mfma_f32_16x16x32_bf16 v[70:73], v[164:167], v[210:213], 0
	v_mfma_f32_16x16x32_bf16 v[66:69], v[172:175], v[210:213], 0
	v_mfma_f32_16x16x32_bf16 v[118:121], v[168:171], v[190:193], v[118:121]
	v_mfma_f32_16x16x32_bf16 v[110:113], v[180:183], v[190:193], v[110:113]
	v_mfma_f32_16x16x32_bf16 v[102:105], v[168:171], v[198:201], v[102:105]
	v_mfma_f32_16x16x32_bf16 v[94:97], v[180:183], v[198:201], v[94:97]
	v_mfma_f32_16x16x32_bf16 v[86:89], v[168:171], v[206:209], v[86:89]
	v_mfma_f32_16x16x32_bf16 v[78:81], v[180:183], v[206:209], v[78:81]
	v_mfma_f32_16x16x32_bf16 v[70:73], v[168:171], v[214:217], v[70:73]
	v_mfma_f32_16x16x32_bf16 v[66:69], v[180:183], v[214:217], v[66:69]
	s_setprio 0
	s_barrier
	s_add_i32 s18, s50, s27
	v_lshl_add_u64 v[146:147], s[22:23], 0, v[132:133]
	s_mov_b32 m0, s18
	ds_read_b128 v[186:189], v150 offset:16384
	ds_read_b128 v[190:193], v150 offset:17408
	ds_read_b128 v[194:197], v150 offset:18432
	ds_read_b128 v[198:201], v150 offset:19456
	ds_read_b128 v[202:205], v150 offset:20480
	ds_read_b128 v[206:209], v150 offset:21504
	ds_read_b128 v[210:213], v150 offset:22528
	ds_read_b128 v[214:217], v150 offset:23552
	global_load_lds_dwordx4 v[146:147], off
	s_add_i32 m0, s18, 0x2000
	s_add_u32 s18, s22, 0xb0000
	v_lshl_add_u64 v[176:177], s[22:23], 0, v[136:137]
	s_addc_u32 s19, s23, 0
	s_add_i32 s50, s51, s27
	global_load_lds_dwordx4 v[176:177], off
	v_lshl_add_u64 v[218:219], s[18:19], 0, v[132:133]
	s_mov_b32 m0, s50
	v_lshl_add_u64 v[220:221], s[24:25], 0, v[134:135]
	global_load_lds_dwordx4 v[218:219], off
	v_lshl_add_u64 v[218:219], s[18:19], 0, v[136:137]
	s_add_i32 m0, s50, 0x2000
	s_nop 0
	global_load_lds_dwordx4 v[218:219], off
	v_lshl_add_u64 v[218:219], s[24:25], 0, v[130:131]
	s_mov_b32 m0, s33
	s_nop 0
	global_load_lds_dwordx4 v[218:219], off
	s_mov_b32 m0, s36
	s_nop 0
	global_load_lds_dwordx4 v[220:221], off
	s_waitcnt vmcnt(8)
	s_waitcnt lgkmcnt(0)
	s_barrier
; #define PG8_STAGE(bufoff, gbase, voff) do { _Pragma("unroll") for (int _i = 0; _i < 2; ++_i) \
;         __builtin_amdgcn_global_load_lds((const unsigned*)((const char*)(gbase) + (voff)[_i]), (PG8_LAS unsigned*)(lds + (bufoff) + ldsw + _i * 8192), 16, 0, 0); } while (0)
; #define PG8_LDA(dst, b, h) do { _Pragma("unroll") for (int m = 0; m < 4; ++m) _Pragma("unroll") for (int k = 0; k < 2; ++k) dst[m][k] = *(const PG8_LAS bf16x8*)(lds + PG8_SA(b, h) + aoff + m * 2048 + k * 1024); } while (0)
; #define PG8_LDB(dst, b, h) do { _Pragma("unroll") for (int n = 0; n < 2; ++n) _Pragma("unroll") for (int k = 0; k < 2; ++k) dst[n][k] = *(const PG8_LAS bf16x8*)(lds + PG8_SB(b, h) + boff + n * 2048 + k * 1024); } while (0)
; #define PG8_MMA(ai, bj, At, Bt) do { __builtin_amdgcn_s_setprio(1); _Pragma("unroll") for (int m = 0; m < 4; ++m) _Pragma("unroll") for (int n = 0; n < 2; ++n) _Pragma("unroll") for (int k = 0; k < 2; ++k) \
;         acc[ai][bj][m][n] = __builtin_amdgcn_mfma_f32_16x16x32_bf16(Bt[n][k], At[m][k], acc[ai][bj][m][n], 0, 0, 0); __builtin_amdgcn_s_setprio(0); } while (0)
; #define PG8_WAIT_V(n) asm volatile("s_waitcnt vmcnt(" #n ")" ::: "memory")
; #define PG8_WAIT_L(n) asm volatile("s_waitcnt lgkmcnt(" #n ")" ::: "memory")
; #define PG8_BAR __builtin_amdgcn_s_barrier()
; #define PG8_SCHED __builtin_amdgcn_sched_barrier(0)
; template <class Epi, class Sched, bool ALIGN_EPI = false, bool SP2 = false>
; __device__ __forceinline__ void gemm_phase(PG8_LAS unsigned char* lds, const Gemm g, const Sched& S, const Epi& E) {
;     ...
;             PG8_WAIT_V(8); PG8_WAIT_L(0); PG8_BAR; PG8_MMA(1, 0, At, B0); PG8_MMA(1, 1, At, B1); PG8_BAR; PG8_SCHED;
;             PG8_LDB(B0, 1, 0); PG8_LDB(B1, 1, 1); PG8_SCHED; PG8_LDA(At, 1, 0); PG8_STAGE(PG8_SA(0, 1), a2 + hstep, voffA);
;             PG8_WAIT_V(8); PG8_WAIT_L(0); PG8_BAR; PG8_MMA(0, 0, At, B0); PG8_MMA(0, 1, At, B1); PG8_BAR; PG8_SCHED;
	s_setprio 1
	v_mfma_f32_16x16x32_bf16 v[62:65], v[142:145], v[186:189], 0
	v_mfma_f32_16x16x32_bf16 v[58:61], v[156:159], v[186:189], 0
	v_mfma_f32_16x16x32_bf16 v[50:53], v[142:145], v[194:197], 0
	v_mfma_f32_16x16x32_bf16 v[42:45], v[156:159], v[194:197], 0
	v_mfma_f32_16x16x32_bf16 v[34:37], v[142:145], v[202:205], 0
	v_mfma_f32_16x16x32_bf16 v[26:29], v[156:159], v[202:205], 0
	v_mfma_f32_16x16x32_bf16 v[18:21], v[142:145], v[210:213], 0
	v_mfma_f32_16x16x32_bf16 v[10:13], v[156:159], v[210:213], 0
	v_mfma_f32_16x16x32_bf16 v[62:65], v[152:155], v[190:193], v[62:65]
	v_mfma_f32_16x16x32_bf16 v[58:61], v[160:163], v[190:193], v[58:61]
	v_mfma_f32_16x16x32_bf16 v[50:53], v[152:155], v[198:201], v[50:53]
	v_mfma_f32_16x16x32_bf16 v[42:45], v[160:163], v[198:201], v[42:45]
	v_mfma_f32_16x16x32_bf16 v[34:37], v[152:155], v[206:209], v[34:37]
	v_mfma_f32_16x16x32_bf16 v[26:29], v[160:163], v[206:209], v[26:29]
	v_mfma_f32_16x16x32_bf16 v[18:21], v[152:155], v[214:217], v[18:21]
	v_mfma_f32_16x16x32_bf16 v[10:13], v[160:163], v[214:217], v[10:13]
	s_setprio 0
	s_setprio 1
	v_mfma_f32_16x16x32_bf16 v[54:57], v[164:167], v[186:189], 0
	v_mfma_f32_16x16x32_bf16 v[46:49], v[172:175], v[186:189], 0
	v_mfma_f32_16x16x32_bf16 v[38:41], v[164:167], v[194:197], 0
	v_mfma_f32_16x16x32_bf16 v[30:33], v[172:175], v[194:197], 0
	v_mfma_f32_16x16x32_bf16 v[22:25], v[164:167], v[202:205], 0
	v_mfma_f32_16x16x32_bf16 v[14:17], v[172:175], v[202:205], 0
	v_mfma_f32_16x16x32_bf16 v[6:9], v[164:167], v[210:213], 0
	v_mfma_f32_16x16x32_bf16 v[2:5], v[172:175], v[210:213], 0
	v_mfma_f32_16x16x32_bf16 v[54:57], v[168:171], v[190:193], v[54:57]
	v_mfma_f32_16x16x32_bf16 v[46:49], v[180:183], v[190:193], v[46:49]
	v_mfma_f32_16x16x32_bf16 v[38:41], v[168:171], v[198:201], v[38:41]
	v_mfma_f32_16x16x32_bf16 v[30:33], v[180:183], v[198:201], v[30:33]
	v_mfma_f32_16x16x32_bf16 v[22:25], v[168:171], v[206:209], v[22:25]
	v_mfma_f32_16x16x32_bf16 v[14:17], v[180:183], v[206:209], v[14:17]
	v_mfma_f32_16x16x32_bf16 v[6:9], v[168:171], v[214:217], v[6:9]
	v_mfma_f32_16x16x32_bf16 v[2:5], v[180:183], v[214:217], v[2:5]
	s_setprio 0
	s_barrier
	s_add_i32 s50, 0, 0x18000
	v_add_u32_e32 v151, s50, v148
	s_add_i32 s51, 0, 0x1c000
	ds_read_b128 v[142:145], v151
	ds_read_b128 v[152:155], v151 offset:1024
	ds_read_b128 v[156:159], v151 offset:2048
	ds_read_b128 v[160:163], v151 offset:3072
	v_add_u32_e32 v151, s51, v148
	ds_read_b128 v[164:167], v151
	ds_read_b128 v[168:171], v151 offset:1024
	ds_read_b128 v[172:175], v151 offset:2048
	ds_read_b128 v[180:183], v151 offset:3072
	s_add_u32 s18, s24, 0xb0000
	s_addc_u32 s19, s25, 0
	s_mov_b32 m0, s37
	v_lshl_add_u64 v[222:223], s[18:19], 0, v[130:131]
	ds_read_b128 v[186:189], v150 offset:32768
	ds_read_b128 v[190:193], v150 offset:33792
	ds_read_b128 v[194:197], v150 offset:34816
	ds_read_b128 v[198:201], v150 offset:35840
	ds_read_b128 v[202:205], v150 offset:36864
	ds_read_b128 v[206:209], v150 offset:37888
	ds_read_b128 v[210:213], v150 offset:38912
	ds_read_b128 v[214:217], v150 offset:39936
	global_load_lds_dwordx4 v[222:223], off
	v_lshl_add_u64 v[222:223], s[18:19], 0, v[134:135]
	s_mov_b32 m0, s38
	s_nop 0
	global_load_lds_dwordx4 v[222:223], off
	s_waitcnt vmcnt(8)
	s_waitcnt lgkmcnt(0)
	s_barrier
	s_setprio 1
	v_mfma_f32_16x16x32_bf16 v[126:129], v[142:145], v[186:189], v[126:129]
	v_mfma_f32_16x16x32_bf16 v[122:125], v[156:159], v[186:189], v[122:125]
	v_mfma_f32_16x16x32_bf16 v[114:117], v[142:145], v[194:197], v[114:117]
	v_mfma_f32_16x16x32_bf16 v[106:109], v[156:159], v[194:197], v[106:109]
	v_mfma_f32_16x16x32_bf16 v[98:101], v[142:145], v[202:205], v[98:101]
	v_mfma_f32_16x16x32_bf16 v[90:93], v[156:159], v[202:205], v[90:93]
	v_mfma_f32_16x16x32_bf16 v[82:85], v[142:145], v[210:213], v[82:85]
	v_mfma_f32_16x16x32_bf16 v[74:77], v[156:159], v[210:213], v[74:77]
	v_mfma_f32_16x16x32_bf16 v[126:129], v[152:155], v[190:193], v[126:129]
	v_mfma_f32_16x16x32_bf16 v[122:125], v[160:163], v[190:193], v[122:125]
	v_mfma_f32_16x16x32_bf16 v[114:117], v[152:155], v[198:201], v[114:117]
	v_mfma_f32_16x16x32_bf16 v[106:109], v[160:163], v[198:201], v[106:109]
	v_mfma_f32_16x16x32_bf16 v[98:101], v[152:155], v[206:209], v[98:101]
	v_mfma_f32_16x16x32_bf16 v[90:93], v[160:163], v[206:209], v[90:93]
	v_mfma_f32_16x16x32_bf16 v[82:85], v[152:155], v[214:217], v[82:85]
	v_mfma_f32_16x16x32_bf16 v[74:77], v[160:163], v[214:217], v[74:77]
	s_setprio 0
	s_setprio 1
	v_mfma_f32_16x16x32_bf16 v[118:121], v[164:167], v[186:189], v[118:121]
	v_mfma_f32_16x16x32_bf16 v[110:113], v[172:175], v[186:189], v[110:113]
	v_mfma_f32_16x16x32_bf16 v[102:105], v[164:167], v[194:197], v[102:105]
	v_mfma_f32_16x16x32_bf16 v[94:97], v[172:175], v[194:197], v[94:97]
	v_mfma_f32_16x16x32_bf16 v[86:89], v[164:167], v[202:205], v[86:89]
	v_mfma_f32_16x16x32_bf16 v[78:81], v[172:175], v[202:205], v[78:81]
	v_mfma_f32_16x16x32_bf16 v[70:73], v[164:167], v[210:213], v[70:73]
	v_mfma_f32_16x16x32_bf16 v[66:69], v[172:175], v[210:213], v[66:69]
	v_mfma_f32_16x16x32_bf16 v[118:121], v[168:171], v[190:193], v[118:121]
	v_mfma_f32_16x16x32_bf16 v[110:113], v[180:183], v[190:193], v[110:113]
	v_mfma_f32_16x16x32_bf16 v[102:105], v[168:171], v[198:201], v[102:105]
	v_mfma_f32_16x16x32_bf16 v[94:97], v[180:183], v[198:201], v[94:97]
	v_mfma_f32_16x16x32_bf16 v[86:89], v[168:171], v[206:209], v[86:89]
	v_mfma_f32_16x16x32_bf16 v[78:81], v[180:183], v[206:209], v[78:81]
	v_mfma_f32_16x16x32_bf16 v[70:73], v[168:171], v[214:217], v[70:73]
	v_mfma_f32_16x16x32_bf16 v[66:69], v[180:183], v[214:217], v[66:69]
	s_setprio 0
	s_barrier
; #define PG8_STAGE(bufoff, gbase, voff) do { _Pragma("unroll") for (int _i = 0; _i < 2; ++_i) \
;         __builtin_amdgcn_global_load_lds((const unsigned*)((const char*)(gbase) + (voff)[_i]), (PG8_LAS unsigned*)(lds + (bufoff) + ldsw + _i * 8192), 16, 0, 0); } while (0)
; #define PG8_LDA(dst, b, h) do { _Pragma("unroll") for (int m = 0; m < 4; ++m) _Pragma("unroll") for (int k = 0; k < 2; ++k) dst[m][k] = *(const PG8_LAS bf16x8*)(lds + PG8_SA(b, h) + aoff + m * 2048 + k * 1024); } while (0)
; #define PG8_MMA(ai, bj, At, Bt) do { __builtin_amdgcn_s_setprio(1); _Pragma("unroll") for (int m = 0; m < 4; ++m) _Pragma("unroll") for (int n = 0; n < 2; ++n) _Pragma("unroll") for (int k = 0; k < 2; ++k) \
;         acc[ai][bj][m][n] = __builtin_amdgcn_mfma_f32_16x16x32_bf16(Bt[n][k], At[m][k], acc[ai][bj][m][n], 0, 0, 0); __builtin_amdgcn_s_setprio(0); } while (0)
; #define PG8_WAIT_V(n) asm volatile("s_waitcnt vmcnt(" #n ")" ::: "memory")
; #define PG8_WAIT_L(n) asm volatile("s_waitcnt lgkmcnt(" #n ")" ::: "memory")
; #define PG8_BAR __builtin_amdgcn_s_barrier()
; #define PG8_SCHED __builtin_amdgcn_sched_barrier(0)
; template <class Epi, class Sched, bool ALIGN_EPI = false, bool SP2 = false>
; __device__ __forceinline__ void gemm_phase(PG8_LAS unsigned char* lds, const Gemm g, const Sched& S, const Epi& E) {
;     ...
;             PG8_LDA(At, 1, 1); PG8_STAGE(PG8_SB(1, 0), b3, voffB); PG8_STAGE(PG8_SB(1, 1), b3 + hstep, voffB); PG8_STAGE(PG8_SA(1, 0), a3, voffA);
;             PG8_WAIT_V(8); PG8_WAIT_L(0); PG8_BAR; PG8_MMA(1, 0, At, B0); PG8_MMA(1, 1, At, B1); PG8_BAR; PG8_SCHED;
	s_add_i32 s18, s50, s27
	v_lshl_add_u64 v[146:147], v[146:147], 0, s[80:81]
	s_mov_b32 m0, s18
	ds_read_b128 v[186:189], v150 offset:49152
	ds_read_b128 v[190:193], v150 offset:50176
	ds_read_b128 v[194:197], v150 offset:51200
	ds_read_b128 v[198:201], v150 offset:52224
	ds_read_b128 v[202:205], v150 offset:53248
	ds_read_b128 v[206:209], v150 offset:54272
	ds_read_b128 v[210:213], v150 offset:55296
	ds_read_b128 v[214:217], v150 offset:56320
	global_load_lds_dwordx4 v[146:147], off
	s_add_i32 m0, s18, 0x2000
	s_add_u32 s18, s22, 0xb0080
	v_lshl_add_u64 v[146:147], v[176:177], 0, s[80:81]
	s_addc_u32 s19, s23, 0
	s_add_i32 s22, s51, s27
	global_load_lds_dwordx4 v[146:147], off
	v_lshl_add_u64 v[146:147], s[18:19], 0, v[132:133]
	s_mov_b32 m0, s22
	s_nop 0
	global_load_lds_dwordx4 v[146:147], off
	v_lshl_add_u64 v[146:147], s[18:19], 0, v[136:137]
	s_add_i32 m0, s22, 0x2000
	s_nop 0
	global_load_lds_dwordx4 v[146:147], off
	v_lshl_add_u64 v[146:147], v[218:219], 0, s[80:81]
	s_mov_b32 m0, s39
	s_nop 0
	global_load_lds_dwordx4 v[146:147], off
	v_lshl_add_u64 v[146:147], v[220:221], 0, s[80:81]
	s_mov_b32 m0, s40
	s_nop 0
	global_load_lds_dwordx4 v[146:147], off
	s_waitcnt vmcnt(8)
	s_waitcnt lgkmcnt(0)
	s_barrier
	s_setprio 1
	v_mfma_f32_16x16x32_bf16 v[62:65], v[142:145], v[186:189], v[62:65]
	v_mfma_f32_16x16x32_bf16 v[58:61], v[156:159], v[186:189], v[58:61]
	v_mfma_f32_16x16x32_bf16 v[50:53], v[142:145], v[194:197], v[50:53]
	v_mfma_f32_16x16x32_bf16 v[42:45], v[156:159], v[194:197], v[42:45]
	v_mfma_f32_16x16x32_bf16 v[34:37], v[142:145], v[202:205], v[34:37]
	v_mfma_f32_16x16x32_bf16 v[26:29], v[156:159], v[202:205], v[26:29]
	v_mfma_f32_16x16x32_bf16 v[18:21], v[142:145], v[210:213], v[18:21]
	v_mfma_f32_16x16x32_bf16 v[10:13], v[156:159], v[210:213], v[10:13]
	v_mfma_f32_16x16x32_bf16 v[62:65], v[152:155], v[190:193], v[62:65]
	v_mfma_f32_16x16x32_bf16 v[58:61], v[160:163], v[190:193], v[58:61]
	v_mfma_f32_16x16x32_bf16 v[50:53], v[152:155], v[198:201], v[50:53]
	v_mfma_f32_16x16x32_bf16 v[42:45], v[160:163], v[198:201], v[42:45]
	v_mfma_f32_16x16x32_bf16 v[34:37], v[152:155], v[206:209], v[34:37]
	v_mfma_f32_16x16x32_bf16 v[26:29], v[160:163], v[206:209], v[26:29]
	v_mfma_f32_16x16x32_bf16 v[18:21], v[152:155], v[214:217], v[18:21]
	v_mfma_f32_16x16x32_bf16 v[10:13], v[160:163], v[214:217], v[10:13]
	s_setprio 0
	s_setprio 1
	v_mfma_f32_16x16x32_bf16 v[54:57], v[164:167], v[186:189], v[54:57]
	v_mfma_f32_16x16x32_bf16 v[46:49], v[172:175], v[186:189], v[46:49]
	v_mfma_f32_16x16x32_bf16 v[38:41], v[164:167], v[194:197], v[38:41]
	v_mfma_f32_16x16x32_bf16 v[30:33], v[172:175], v[194:197], v[30:33]
	v_mfma_f32_16x16x32_bf16 v[22:25], v[164:167], v[202:205], v[22:25]
	v_mfma_f32_16x16x32_bf16 v[14:17], v[172:175], v[202:205], v[14:17]
	v_mfma_f32_16x16x32_bf16 v[6:9], v[164:167], v[210:213], v[6:9]
	v_mfma_f32_16x16x32_bf16 v[2:5], v[172:175], v[210:213], v[2:5]
	v_mfma_f32_16x16x32_bf16 v[54:57], v[168:171], v[190:193], v[54:57]
	v_mfma_f32_16x16x32_bf16 v[46:49], v[180:183], v[190:193], v[46:49]
	v_mfma_f32_16x16x32_bf16 v[38:41], v[168:171], v[198:201], v[38:41]
	v_mfma_f32_16x16x32_bf16 v[30:33], v[180:183], v[198:201], v[30:33]
	v_mfma_f32_16x16x32_bf16 v[22:25], v[168:171], v[206:209], v[22:25]
	v_mfma_f32_16x16x32_bf16 v[14:17], v[180:183], v[206:209], v[14:17]
	v_mfma_f32_16x16x32_bf16 v[6:9], v[168:171], v[214:217], v[6:9]
	v_mfma_f32_16x16x32_bf16 v[2:5], v[180:183], v[214:217], v[2:5]
	s_setprio 0
	s_barrier
	s_add_i32 s49, s49, 2
	s_add_u32 s47, s47, 0x100
	s_addc_u32 s48, s48, 0
	s_cmp_gt_u32 s49, 41
	s_mov_b64 s[18:19], s[20:21]
	s_branch .LBB0_1360
